# code placement: every 32-MFMA block of the GEMM mainloops starts 8-byte aligned (s_nop 0 added in the preceding load segment where needed)
# speedup vs baseline: 1.0021x; 1.0021x over previous
; #define PG8_STAGE(bufoff, gbase, voff) do { _Pragma("unroll") for (int _i = 0; _i < 2; ++_i) \
;         __builtin_amdgcn_global_load_lds((const unsigned*)((const char*)(gbase) + (voff)[_i]), (PG8_LAS unsigned*)(lds + (bufoff) + ldsw + _i * 8192), 16, 0, 0); } while (0)
; #define PG8_LDA(dst, b, h) do { _Pragma("unroll") for (int m = 0; m < 4; ++m) _Pragma("unroll") for (int k = 0; k < 2; ++k) dst[m][k] = *(const PG8_LAS bf16x8*)(lds + PG8_SA(b, h) + aoff + m * 2048 + k * 1024); } while (0)
; #define PG8_LDB(dst, b, h) do { _Pragma("unroll") for (int n = 0; n < 2; ++n) _Pragma("unroll") for (int k = 0; k < 2; ++k) dst[n][k] = *(const PG8_LAS bf16x8*)(lds + PG8_SB(b, h) + boff + n * 2048 + k * 1024); } while (0)
; #define PG8_MMA(ai, bj, At, Bt) do { __builtin_amdgcn_s_setprio(1); _Pragma("unroll") for (int m = 0; m < 4; ++m) _Pragma("unroll") for (int n = 0; n < 2; ++n) _Pragma("unroll") for (int k = 0; k < 2; ++k) \
;         acc[ai][bj][m][n] = __builtin_amdgcn_mfma_f32_16x16x32_bf16(Bt[n][k], At[m][k], acc[ai][bj][m][n], 0, 0, 0); __builtin_amdgcn_s_setprio(0); } while (0)
; #define PG8_WAIT_V(n) asm volatile("s_waitcnt vmcnt(" #n ")" ::: "memory")
; #define PG8_WAIT_L(n) asm volatile("s_waitcnt lgkmcnt(" #n ")" ::: "memory")
; #define PG8_BAR __builtin_amdgcn_s_barrier()
; #define PG8_SCHED __builtin_amdgcn_sched_barrier(0)
; template <class Epi, class Sched, bool ALIGN_EPI = false, bool SP2 = false>
; __device__ __forceinline__ void gemm_phase(PG8_LAS unsigned char* lds, const Gemm g, const Sched& S, const Epi& E) {
;     ...
;             PG8_LDB(B0, 0, 0); PG8_LDB(B1, 0, 1); PG8_SCHED; PG8_LDA(At, 0, 0); PG8_STAGE(PG8_SA(1, 1), a1 + hstepA, voffA);
;             PG8_WAIT_V(8); PG8_WAIT_L(0); PG8_BAR; PG8_MMA(0, 0, At, B0); PG8_MMA(0, 1, At, B1); PG8_BAR; PG8_SCHED;
;             PG8_LDA(At, 0, 1); PG8_STAGE(PG8_SB(0, 0), b2, voffB); PG8_STAGE(PG8_SB(0, 1), b2 + hstepB, voffB); PG8_STAGE(PG8_SA(0, 0), a2, voffA);
;             PG8_WAIT_V(8); PG8_WAIT_L(0); PG8_BAR; PG8_MMA(1, 0, At, B0); PG8_MMA(1, 1, At, B1); PG8_BAR; PG8_SCHED;
.LBB0_300:
	ds_read_b128 v[156:159], v152
	ds_read_b128 v[160:163], v152 offset:1024
	ds_read_b128 v[164:167], v152 offset:2048
	ds_read_b128 v[168:171], v152 offset:3072
	ds_read_b128 v[172:175], v153
	ds_read_b128 v[176:179], v153 offset:1024
	ds_read_b128 v[180:183], v153 offset:2048
	ds_read_b128 v[186:189], v153 offset:3072
	s_add_u32 s56, s50, 0xfff80080
	s_addc_u32 s57, s51, -1
	s_cmp_eq_u32 s61, 28
	s_cselect_b32 s59, s4, s57
	s_cselect_b32 s58, s5, s56
	s_cselect_b32 s57, s12, s43
	s_cselect_b32 s56, s13, s41
	v_lshl_add_u64 v[222:223], s[50:51], 0, v[142:143]
	s_add_i32 m0, s6, 0xc000
	ds_read_b128 v[190:193], v154
	ds_read_b128 v[194:197], v154 offset:1024
	ds_read_b128 v[198:201], v154 offset:2048
	ds_read_b128 v[202:205], v154 offset:3072
	ds_read_b128 v[206:209], v154 offset:4096
	ds_read_b128 v[210:213], v154 offset:5120
	ds_read_b128 v[214:217], v154 offset:6144
	ds_read_b128 v[218:221], v154 offset:7168
	global_load_lds_dwordx4 v[222:223], off
	v_lshl_add_u64 v[222:223], s[50:51], 0, v[144:145]
	s_add_i32 m0, s6, 0xe000
	s_nop 0
	global_load_lds_dwordx4 v[222:223], off
	s_waitcnt vmcnt(8)
	s_waitcnt lgkmcnt(0)
	s_setprio 1
	s_barrier
	v_mfma_f32_16x16x32_bf16 v[124:127], v[156:159], v[190:193], v[124:127]
	v_mfma_f32_16x16x32_bf16 v[120:123], v[164:167], v[190:193], v[120:123]
	v_mfma_f32_16x16x32_bf16 v[108:111], v[156:159], v[198:201], v[108:111]
	v_mfma_f32_16x16x32_bf16 v[104:107], v[164:167], v[198:201], v[104:107]
	v_mfma_f32_16x16x32_bf16 v[92:95], v[156:159], v[206:209], v[92:95]
	v_mfma_f32_16x16x32_bf16 v[88:91], v[164:167], v[206:209], v[88:91]
	v_mfma_f32_16x16x32_bf16 v[76:79], v[156:159], v[214:217], v[76:79]
	v_mfma_f32_16x16x32_bf16 v[72:75], v[164:167], v[214:217], v[72:75]
	v_mfma_f32_16x16x32_bf16 v[124:127], v[160:163], v[194:197], v[124:127]
	v_mfma_f32_16x16x32_bf16 v[120:123], v[168:171], v[194:197], v[120:123]
	v_mfma_f32_16x16x32_bf16 v[108:111], v[160:163], v[202:205], v[108:111]
	v_mfma_f32_16x16x32_bf16 v[104:107], v[168:171], v[202:205], v[104:107]
	v_mfma_f32_16x16x32_bf16 v[92:95], v[160:163], v[210:213], v[92:95]
	v_mfma_f32_16x16x32_bf16 v[88:91], v[168:171], v[210:213], v[88:91]
	v_mfma_f32_16x16x32_bf16 v[76:79], v[160:163], v[218:221], v[76:79]
	v_mfma_f32_16x16x32_bf16 v[72:75], v[168:171], v[218:221], v[72:75]
	s_setprio 0
	s_setprio 1
	v_mfma_f32_16x16x32_bf16 v[116:119], v[172:175], v[190:193], v[116:119]
	v_mfma_f32_16x16x32_bf16 v[112:115], v[180:183], v[190:193], v[112:115]
	v_mfma_f32_16x16x32_bf16 v[100:103], v[172:175], v[198:201], v[100:103]
	v_mfma_f32_16x16x32_bf16 v[96:99], v[180:183], v[198:201], v[96:99]
	v_mfma_f32_16x16x32_bf16 v[84:87], v[172:175], v[206:209], v[84:87]
	v_mfma_f32_16x16x32_bf16 v[80:83], v[180:183], v[206:209], v[80:83]
	v_mfma_f32_16x16x32_bf16 v[68:71], v[172:175], v[214:217], v[68:71]
	v_mfma_f32_16x16x32_bf16 v[64:67], v[180:183], v[214:217], v[64:67]
	v_mfma_f32_16x16x32_bf16 v[116:119], v[176:179], v[194:197], v[116:119]
	v_mfma_f32_16x16x32_bf16 v[112:115], v[186:189], v[194:197], v[112:115]
	v_mfma_f32_16x16x32_bf16 v[100:103], v[176:179], v[202:205], v[100:103]
	v_mfma_f32_16x16x32_bf16 v[96:99], v[186:189], v[202:205], v[96:99]
	v_mfma_f32_16x16x32_bf16 v[84:87], v[176:179], v[210:213], v[84:87]
	v_mfma_f32_16x16x32_bf16 v[80:83], v[186:189], v[210:213], v[80:83]
	v_mfma_f32_16x16x32_bf16 v[68:71], v[176:179], v[218:221], v[68:71]
	v_mfma_f32_16x16x32_bf16 v[64:67], v[186:189], v[218:221], v[64:67]
	s_barrier
	s_setprio 0
	s_add_i32 s62, s53, s3
	v_lshl_add_u64 v[222:223], s[56:57], 0, v[130:131]
	s_mov_b32 m0, s62
	ds_read_b128 v[190:193], v154 offset:16384
	ds_read_b128 v[194:197], v154 offset:17408
	ds_read_b128 v[198:201], v154 offset:18432
	ds_read_b128 v[202:205], v154 offset:19456
	ds_read_b128 v[206:209], v154 offset:20480
	ds_read_b128 v[210:213], v154 offset:21504
	ds_read_b128 v[214:217], v154 offset:22528
	ds_read_b128 v[218:221], v154 offset:23552
	global_load_lds_dwordx4 v[222:223], off
	s_add_i32 m0, s62, 0x2000
	s_add_u32 s62, s56, 0x80000
	v_lshl_add_u64 v[224:225], s[56:57], 0, v[134:135]
	s_addc_u32 s63, s57, 0
	s_add_i32 s64, s55, s3
	global_load_lds_dwordx4 v[224:225], off
	v_lshl_add_u64 v[226:227], s[62:63], 0, v[130:131]
	s_mov_b32 m0, s64
	v_lshl_add_u64 v[228:229], s[58:59], 0, v[132:133]
	global_load_lds_dwordx4 v[226:227], off
	v_lshl_add_u64 v[226:227], s[62:63], 0, v[134:135]
	s_add_i32 m0, s64, 0x2000
	s_nop 0
	global_load_lds_dwordx4 v[226:227], off
	v_lshl_add_u64 v[226:227], s[58:59], 0, v[128:129]
	s_mov_b32 m0, s6
	s_nop 0
	global_load_lds_dwordx4 v[226:227], off
	s_mov_b32 m0, s7
	s_nop 0
	global_load_lds_dwordx4 v[228:229], off
	s_waitcnt vmcnt(8)
	s_waitcnt lgkmcnt(0)
	s_setprio 1
	s_barrier
; #define PG8_STAGE(bufoff, gbase, voff) do { _Pragma("unroll") for (int _i = 0; _i < 2; ++_i) \
;         __builtin_amdgcn_global_load_lds((const unsigned*)((const char*)(gbase) + (voff)[_i]), (PG8_LAS unsigned*)(lds + (bufoff) + ldsw + _i * 8192), 16, 0, 0); } while (0)
; #define PG8_LDA(dst, b, h) do { _Pragma("unroll") for (int m = 0; m < 4; ++m) _Pragma("unroll") for (int k = 0; k < 2; ++k) dst[m][k] = *(const PG8_LAS bf16x8*)(lds + PG8_SA(b, h) + aoff + m * 2048 + k * 1024); } while (0)
; #define PG8_LDB(dst, b, h) do { _Pragma("unroll") for (int n = 0; n < 2; ++n) _Pragma("unroll") for (int k = 0; k < 2; ++k) dst[n][k] = *(const PG8_LAS bf16x8*)(lds + PG8_SB(b, h) + boff + n * 2048 + k * 1024); } while (0)
; #define PG8_MMA(ai, bj, At, Bt) do { __builtin_amdgcn_s_setprio(1); _Pragma("unroll") for (int m = 0; m < 4; ++m) _Pragma("unroll") for (int n = 0; n < 2; ++n) _Pragma("unroll") for (int k = 0; k < 2; ++k) \
;         acc[ai][bj][m][n] = __builtin_amdgcn_mfma_f32_16x16x32_bf16(Bt[n][k], At[m][k], acc[ai][bj][m][n], 0, 0, 0); __builtin_amdgcn_s_setprio(0); } while (0)
; #define PG8_WAIT_V(n) asm volatile("s_waitcnt vmcnt(" #n ")" ::: "memory")
; #define PG8_WAIT_L(n) asm volatile("s_waitcnt lgkmcnt(" #n ")" ::: "memory")
; #define PG8_BAR __builtin_amdgcn_s_barrier()
; #define PG8_SCHED __builtin_amdgcn_sched_barrier(0)
; template <class Epi, class Sched, bool ALIGN_EPI = false, bool SP2 = false>
; __device__ __forceinline__ void gemm_phase(PG8_LAS unsigned char* lds, const Gemm g, const Sched& S, const Epi& E) {
;     ...
;             PG8_WAIT_V(8); PG8_WAIT_L(0); PG8_BAR; PG8_MMA(1, 0, At, B0); PG8_MMA(1, 1, At, B1); PG8_BAR; PG8_SCHED;
;             PG8_LDB(B0, 1, 0); PG8_LDB(B1, 1, 1); PG8_SCHED; PG8_LDA(At, 1, 0); PG8_STAGE(PG8_SA(0, 1), a2 + hstepA, voffA);
;             PG8_WAIT_V(8); PG8_WAIT_L(0); PG8_BAR; PG8_MMA(0, 0, At, B0); PG8_MMA(0, 1, At, B1); PG8_BAR; PG8_SCHED;
	v_mfma_f32_16x16x32_bf16 v[60:63], v[156:159], v[190:193], v[60:63]
	v_mfma_f32_16x16x32_bf16 v[56:59], v[164:167], v[190:193], v[56:59]
	v_mfma_f32_16x16x32_bf16 v[44:47], v[156:159], v[198:201], v[44:47]
	v_mfma_f32_16x16x32_bf16 v[40:43], v[164:167], v[198:201], v[40:43]
	v_mfma_f32_16x16x32_bf16 v[28:31], v[156:159], v[206:209], v[28:31]
	v_mfma_f32_16x16x32_bf16 v[24:27], v[164:167], v[206:209], v[24:27]
	v_mfma_f32_16x16x32_bf16 v[12:15], v[156:159], v[214:217], v[12:15]
	v_mfma_f32_16x16x32_bf16 v[8:11], v[164:167], v[214:217], v[8:11]
	v_mfma_f32_16x16x32_bf16 v[60:63], v[160:163], v[194:197], v[60:63]
	v_mfma_f32_16x16x32_bf16 v[56:59], v[168:171], v[194:197], v[56:59]
	v_mfma_f32_16x16x32_bf16 v[44:47], v[160:163], v[202:205], v[44:47]
	v_mfma_f32_16x16x32_bf16 v[40:43], v[168:171], v[202:205], v[40:43]
	v_mfma_f32_16x16x32_bf16 v[28:31], v[160:163], v[210:213], v[28:31]
	v_mfma_f32_16x16x32_bf16 v[24:27], v[168:171], v[210:213], v[24:27]
	v_mfma_f32_16x16x32_bf16 v[12:15], v[160:163], v[218:221], v[12:15]
	v_mfma_f32_16x16x32_bf16 v[8:11], v[168:171], v[218:221], v[8:11]
	s_setprio 0
	s_setprio 1
	v_mfma_f32_16x16x32_bf16 v[52:55], v[172:175], v[190:193], v[52:55]
	v_mfma_f32_16x16x32_bf16 v[48:51], v[180:183], v[190:193], v[48:51]
	v_mfma_f32_16x16x32_bf16 v[36:39], v[172:175], v[198:201], v[36:39]
	v_mfma_f32_16x16x32_bf16 v[32:35], v[180:183], v[198:201], v[32:35]
	v_mfma_f32_16x16x32_bf16 v[20:23], v[172:175], v[206:209], v[20:23]
	v_mfma_f32_16x16x32_bf16 v[16:19], v[180:183], v[206:209], v[16:19]
	v_mfma_f32_16x16x32_bf16 v[4:7], v[172:175], v[214:217], v[4:7]
	v_mfma_f32_16x16x32_bf16 v[0:3], v[180:183], v[214:217], v[0:3]
	v_mfma_f32_16x16x32_bf16 v[52:55], v[176:179], v[194:197], v[52:55]
	v_mfma_f32_16x16x32_bf16 v[48:51], v[186:189], v[194:197], v[48:51]
	v_mfma_f32_16x16x32_bf16 v[36:39], v[176:179], v[202:205], v[36:39]
	v_mfma_f32_16x16x32_bf16 v[32:35], v[186:189], v[202:205], v[32:35]
	v_mfma_f32_16x16x32_bf16 v[20:23], v[176:179], v[210:213], v[20:23]
	v_mfma_f32_16x16x32_bf16 v[16:19], v[186:189], v[210:213], v[16:19]
	v_mfma_f32_16x16x32_bf16 v[4:7], v[176:179], v[218:221], v[4:7]
	v_mfma_f32_16x16x32_bf16 v[0:3], v[186:189], v[218:221], v[0:3]
	s_barrier
	s_setprio 0
	s_add_i32 s62, 0, 0x18000
	v_add_u32_e32 v155, s62, v150
	s_add_i32 s63, 0, 0x1c000
	ds_read_b128 v[156:159], v155
	ds_read_b128 v[160:163], v155 offset:1024
	ds_read_b128 v[164:167], v155 offset:2048
	ds_read_b128 v[168:171], v155 offset:3072
	v_add_u32_e32 v155, s63, v150
	ds_read_b128 v[172:175], v155
	ds_read_b128 v[176:179], v155 offset:1024
	ds_read_b128 v[180:183], v155 offset:2048
	ds_read_b128 v[186:189], v155 offset:3072
	s_add_u32 s58, s58, 0x80000
	s_addc_u32 s59, s59, 0
	s_mov_b32 m0, s8
	v_lshl_add_u64 v[230:231], s[58:59], 0, v[128:129]
	ds_read_b128 v[190:193], v154 offset:32768
	ds_read_b128 v[194:197], v154 offset:33792
	ds_read_b128 v[198:201], v154 offset:34816
	ds_read_b128 v[202:205], v154 offset:35840
	ds_read_b128 v[206:209], v154 offset:36864
	ds_read_b128 v[210:213], v154 offset:37888
	ds_read_b128 v[214:217], v154 offset:38912
	ds_read_b128 v[218:221], v154 offset:39936
	global_load_lds_dwordx4 v[230:231], off
	v_lshl_add_u64 v[230:231], s[58:59], 0, v[132:133]
	s_mov_b32 m0, s9
	s_nop 0
	global_load_lds_dwordx4 v[230:231], off
	s_waitcnt vmcnt(8)
	s_waitcnt lgkmcnt(0)
	s_setprio 1
	s_barrier
	v_mfma_f32_16x16x32_bf16 v[124:127], v[156:159], v[190:193], v[124:127]
	v_mfma_f32_16x16x32_bf16 v[120:123], v[164:167], v[190:193], v[120:123]
	v_mfma_f32_16x16x32_bf16 v[108:111], v[156:159], v[198:201], v[108:111]
	v_mfma_f32_16x16x32_bf16 v[104:107], v[164:167], v[198:201], v[104:107]
	v_mfma_f32_16x16x32_bf16 v[92:95], v[156:159], v[206:209], v[92:95]
	v_mfma_f32_16x16x32_bf16 v[88:91], v[164:167], v[206:209], v[88:91]
	v_mfma_f32_16x16x32_bf16 v[76:79], v[156:159], v[214:217], v[76:79]
	v_mfma_f32_16x16x32_bf16 v[72:75], v[164:167], v[214:217], v[72:75]
	v_mfma_f32_16x16x32_bf16 v[124:127], v[160:163], v[194:197], v[124:127]
	v_mfma_f32_16x16x32_bf16 v[120:123], v[168:171], v[194:197], v[120:123]
	v_mfma_f32_16x16x32_bf16 v[108:111], v[160:163], v[202:205], v[108:111]
	v_mfma_f32_16x16x32_bf16 v[104:107], v[168:171], v[202:205], v[104:107]
	v_mfma_f32_16x16x32_bf16 v[92:95], v[160:163], v[210:213], v[92:95]
	v_mfma_f32_16x16x32_bf16 v[88:91], v[168:171], v[210:213], v[88:91]
	v_mfma_f32_16x16x32_bf16 v[76:79], v[160:163], v[218:221], v[76:79]
	v_mfma_f32_16x16x32_bf16 v[72:75], v[168:171], v[218:221], v[72:75]
	s_setprio 0
	s_setprio 1
	v_mfma_f32_16x16x32_bf16 v[116:119], v[172:175], v[190:193], v[116:119]
	v_mfma_f32_16x16x32_bf16 v[112:115], v[180:183], v[190:193], v[112:115]
	v_mfma_f32_16x16x32_bf16 v[100:103], v[172:175], v[198:201], v[100:103]
	v_mfma_f32_16x16x32_bf16 v[96:99], v[180:183], v[198:201], v[96:99]
	v_mfma_f32_16x16x32_bf16 v[84:87], v[172:175], v[206:209], v[84:87]
	v_mfma_f32_16x16x32_bf16 v[80:83], v[180:183], v[206:209], v[80:83]
	v_mfma_f32_16x16x32_bf16 v[68:71], v[172:175], v[214:217], v[68:71]
	v_mfma_f32_16x16x32_bf16 v[64:67], v[180:183], v[214:217], v[64:67]
	v_mfma_f32_16x16x32_bf16 v[116:119], v[176:179], v[194:197], v[116:119]
	v_mfma_f32_16x16x32_bf16 v[112:115], v[186:189], v[194:197], v[112:115]
	v_mfma_f32_16x16x32_bf16 v[100:103], v[176:179], v[202:205], v[100:103]
	v_mfma_f32_16x16x32_bf16 v[96:99], v[186:189], v[202:205], v[96:99]
	v_mfma_f32_16x16x32_bf16 v[84:87], v[176:179], v[210:213], v[84:87]
	v_mfma_f32_16x16x32_bf16 v[80:83], v[186:189], v[210:213], v[80:83]
	v_mfma_f32_16x16x32_bf16 v[68:71], v[176:179], v[218:221], v[68:71]
	v_mfma_f32_16x16x32_bf16 v[64:67], v[186:189], v[218:221], v[64:67]
	s_barrier
; #define PG8_STAGE(bufoff, gbase, voff) do { _Pragma("unroll") for (int _i = 0; _i < 2; ++_i) \
;         __builtin_amdgcn_global_load_lds((const unsigned*)((const char*)(gbase) + (voff)[_i]), (PG8_LAS unsigned*)(lds + (bufoff) + ldsw + _i * 8192), 16, 0, 0); } while (0)
; #define PG8_LDA(dst, b, h) do { _Pragma("unroll") for (int m = 0; m < 4; ++m) _Pragma("unroll") for (int k = 0; k < 2; ++k) dst[m][k] = *(const PG8_LAS bf16x8*)(lds + PG8_SA(b, h) + aoff + m * 2048 + k * 1024); } while (0)
; #define PG8_MMA(ai, bj, At, Bt) do { __builtin_amdgcn_s_setprio(1); _Pragma("unroll") for (int m = 0; m < 4; ++m) _Pragma("unroll") for (int n = 0; n < 2; ++n) _Pragma("unroll") for (int k = 0; k < 2; ++k) \
;         acc[ai][bj][m][n] = __builtin_amdgcn_mfma_f32_16x16x32_bf16(Bt[n][k], At[m][k], acc[ai][bj][m][n], 0, 0, 0); __builtin_amdgcn_s_setprio(0); } while (0)
; #define PG8_WAIT_V(n) asm volatile("s_waitcnt vmcnt(" #n ")" ::: "memory")
; #define PG8_WAIT_L(n) asm volatile("s_waitcnt lgkmcnt(" #n ")" ::: "memory")
; #define PG8_BAR __builtin_amdgcn_s_barrier()
; #define PG8_SCHED __builtin_amdgcn_sched_barrier(0)
; template <class Epi, class Sched, bool ALIGN_EPI = false, bool SP2 = false>
; __device__ __forceinline__ void gemm_phase(PG8_LAS unsigned char* lds, const Gemm g, const Sched& S, const Epi& E) {
;     ...
;             PG8_LDA(At, 1, 1); PG8_STAGE(PG8_SB(1, 0), b3, voffB); PG8_STAGE(PG8_SB(1, 1), b3 + hstepB, voffB); PG8_STAGE(PG8_SA(1, 0), a3, voffA);
;             PG8_WAIT_V(8); PG8_WAIT_L(0); PG8_BAR; PG8_MMA(1, 0, At, B0); PG8_MMA(1, 1, At, B1); PG8_BAR; PG8_SCHED;
;     ...
;         }
;         if constexpr (ALIGN_EPI) { if (wr == 0) PG8_BAR; }
	s_setprio 0
	s_add_i32 s58, s62, s3
	v_lshl_add_u64 v[222:223], v[222:223], 0, s[36:37]
	s_mov_b32 m0, s58
	ds_read_b128 v[190:193], v154 offset:49152
	ds_read_b128 v[194:197], v154 offset:50176
	ds_read_b128 v[198:201], v154 offset:51200
	ds_read_b128 v[202:205], v154 offset:52224
	ds_read_b128 v[206:209], v154 offset:53248
	ds_read_b128 v[210:213], v154 offset:54272
	ds_read_b128 v[214:217], v154 offset:55296
	ds_read_b128 v[218:221], v154 offset:56320
	global_load_lds_dwordx4 v[222:223], off
	s_add_i32 m0, s58, 0x2000
	s_add_u32 s56, s56, 0x80080
	v_lshl_add_u64 v[222:223], v[224:225], 0, s[36:37]
	s_addc_u32 s57, s57, 0
	s_add_i32 s58, s63, s3
	global_load_lds_dwordx4 v[222:223], off
	v_lshl_add_u64 v[222:223], s[56:57], 0, v[130:131]
	s_mov_b32 m0, s58
	s_nop 0
	global_load_lds_dwordx4 v[222:223], off
	v_lshl_add_u64 v[222:223], s[56:57], 0, v[134:135]
	s_add_i32 m0, s58, 0x2000
	s_nop 0
	global_load_lds_dwordx4 v[222:223], off
	v_lshl_add_u64 v[222:223], v[226:227], 0, s[36:37]
	s_mov_b32 m0, s44
	s_nop 0
	global_load_lds_dwordx4 v[222:223], off
	v_lshl_add_u64 v[222:223], v[228:229], 0, s[36:37]
	s_mov_b32 m0, s45
	s_nop 0
	global_load_lds_dwordx4 v[222:223], off
	s_nop 0
	s_waitcnt vmcnt(8)
	s_waitcnt lgkmcnt(0)
	s_setprio 1
	s_barrier
	v_mfma_f32_16x16x32_bf16 v[60:63], v[156:159], v[190:193], v[60:63]
	v_mfma_f32_16x16x32_bf16 v[56:59], v[164:167], v[190:193], v[56:59]
	v_mfma_f32_16x16x32_bf16 v[44:47], v[156:159], v[198:201], v[44:47]
	v_mfma_f32_16x16x32_bf16 v[40:43], v[164:167], v[198:201], v[40:43]
	v_mfma_f32_16x16x32_bf16 v[28:31], v[156:159], v[206:209], v[28:31]
	v_mfma_f32_16x16x32_bf16 v[24:27], v[164:167], v[206:209], v[24:27]
	v_mfma_f32_16x16x32_bf16 v[12:15], v[156:159], v[214:217], v[12:15]
	v_mfma_f32_16x16x32_bf16 v[8:11], v[164:167], v[214:217], v[8:11]
	v_mfma_f32_16x16x32_bf16 v[60:63], v[160:163], v[194:197], v[60:63]
	v_mfma_f32_16x16x32_bf16 v[56:59], v[168:171], v[194:197], v[56:59]
	v_mfma_f32_16x16x32_bf16 v[44:47], v[160:163], v[202:205], v[44:47]
	v_mfma_f32_16x16x32_bf16 v[40:43], v[168:171], v[202:205], v[40:43]
	v_mfma_f32_16x16x32_bf16 v[28:31], v[160:163], v[210:213], v[28:31]
	v_mfma_f32_16x16x32_bf16 v[24:27], v[168:171], v[210:213], v[24:27]
	v_mfma_f32_16x16x32_bf16 v[12:15], v[160:163], v[218:221], v[12:15]
	v_mfma_f32_16x16x32_bf16 v[8:11], v[168:171], v[218:221], v[8:11]
	s_setprio 0
	s_setprio 1
	v_mfma_f32_16x16x32_bf16 v[52:55], v[172:175], v[190:193], v[52:55]
	v_mfma_f32_16x16x32_bf16 v[48:51], v[180:183], v[190:193], v[48:51]
	v_mfma_f32_16x16x32_bf16 v[36:39], v[172:175], v[198:201], v[36:39]
	v_mfma_f32_16x16x32_bf16 v[32:35], v[180:183], v[198:201], v[32:35]
	v_mfma_f32_16x16x32_bf16 v[20:23], v[172:175], v[206:209], v[20:23]
	v_mfma_f32_16x16x32_bf16 v[16:19], v[180:183], v[206:209], v[16:19]
	v_mfma_f32_16x16x32_bf16 v[4:7], v[172:175], v[214:217], v[4:7]
	v_mfma_f32_16x16x32_bf16 v[0:3], v[180:183], v[214:217], v[0:3]
	v_mfma_f32_16x16x32_bf16 v[52:55], v[176:179], v[194:197], v[52:55]
	v_mfma_f32_16x16x32_bf16 v[48:51], v[186:189], v[194:197], v[48:51]
	v_mfma_f32_16x16x32_bf16 v[36:39], v[176:179], v[202:205], v[36:39]
	v_mfma_f32_16x16x32_bf16 v[32:35], v[186:189], v[202:205], v[32:35]
	v_mfma_f32_16x16x32_bf16 v[20:23], v[176:179], v[210:213], v[20:23]
	v_mfma_f32_16x16x32_bf16 v[16:19], v[186:189], v[210:213], v[16:19]
	v_mfma_f32_16x16x32_bf16 v[4:7], v[176:179], v[218:221], v[4:7]
	v_mfma_f32_16x16x32_bf16 v[0:3], v[186:189], v[218:221], v[0:3]
	s_barrier
	s_setprio 0
	s_add_i32 s61, s61, 2
	s_add_u32 s50, s50, 0x100
	s_addc_u32 s51, s51, 0
	s_add_u32 s41, s41, 0x100
	s_addc_u32 s43, s43, 0
	s_cmp_gt_u32 s61, 29
	s_cbranch_scc0 .LBB0_300
	s_and_b64 vcc, exec, s[38:39]
	s_cbranch_vccz .LBB0_303
	s_barrier

; #define PG8_STAGE(bufoff, gbase, voff) do { _Pragma("unroll") for (int _i = 0; _i < 2; ++_i) \
;         __builtin_amdgcn_global_load_lds((const unsigned*)((const char*)(gbase) + (voff)[_i]), (PG8_LAS unsigned*)(lds + (bufoff) + ldsw + _i * 8192), 16, 0, 0); } while (0)
; #define PG8_LDA(dst, b, h) do { _Pragma("unroll") for (int m = 0; m < 4; ++m) _Pragma("unroll") for (int k = 0; k < 2; ++k) dst[m][k] = *(const PG8_LAS bf16x8*)(lds + PG8_SA(b, h) + aoff + m * 2048 + k * 1024); } while (0)
; #define PG8_LDB(dst, b, h) do { _Pragma("unroll") for (int n = 0; n < 2; ++n) _Pragma("unroll") for (int k = 0; k < 2; ++k) dst[n][k] = *(const PG8_LAS bf16x8*)(lds + PG8_SB(b, h) + boff + n * 2048 + k * 1024); } while (0)
; #define PG8_MMA(ai, bj, At, Bt) do { __builtin_amdgcn_s_setprio(1); _Pragma("unroll") for (int m = 0; m < 4; ++m) _Pragma("unroll") for (int n = 0; n < 2; ++n) _Pragma("unroll") for (int k = 0; k < 2; ++k) \
;         acc[ai][bj][m][n] = __builtin_amdgcn_mfma_f32_16x16x32_bf16(Bt[n][k], At[m][k], acc[ai][bj][m][n], 0, 0, 0); __builtin_amdgcn_s_setprio(0); } while (0)
; #define PG8_WAIT_V(n) asm volatile("s_waitcnt vmcnt(" #n ")" ::: "memory")
; #define PG8_BAR __builtin_amdgcn_s_barrier()
; template <class Epi, class Sched, bool ALIGN_EPI = false, bool SP2 = false>
; __device__ __forceinline__ void gemm_phase(PG8_LAS unsigned char* lds, const Gemm g, const Sched& S, const Epi& E) {
;     ...
;         for (int t = 0; t < nt; t += 2) {
;             const bool last = (t == nt - 2);
;             const char* a1 = cA + (size_t)(t + 1) * kstA;
;             const char* a2 = last ? nA : cA + (size_t)(t + 2) * kstA; const char* b2 = last ? nB : cB + (size_t)(t + 2) * kstep;
;             const char* a3 = a2 + kstA; const char* b3 = b2 + kstep;
;             if (last && has_next) S.a_ready(nxt);
;             if constexpr (SP2) {
;             PG8_LDB(B0, 0, 0); PG8_LDB(B1, 0, 1); PG8_SCHED; PG8_LDA(At, 0, 0); PG8_STAGE(PG8_SA(1, 1), a1 + hstepA, voffA);
;             PG8_WAIT_V(8); PG8_WAIT_L(0); PG8_BAR; PG8_MMA(0, 0, At, B0); PG8_MMA(0, 1, At, B1); PG8_BAR; PG8_SCHED;
;             PG8_LDA(At, 0, 1); PG8_STAGE(PG8_SB(0, 0), b2, voffB); PG8_STAGE(PG8_SB(0, 1), b2 + hstepB, voffB); PG8_STAGE(PG8_SA(0, 0), a2, voffA);
;             PG8_WAIT_V(8); PG8_WAIT_L(0); PG8_BAR; PG8_MMA(1, 0, At, B0); PG8_MMA(1, 1, At, B1); PG8_BAR; PG8_SCHED;
.LBB0_397:
	s_or_b32 s42, s74, 1
	s_add_i32 s74, s74, 2
	s_mov_b32 s75, s43
	s_lshl_b64 s[4:5], s[42:43], 15
	s_lshl_b64 s[12:13], s[74:75], 15
	s_add_u32 s42, s38, s12
	v_add_u32_e32 v170, s10, v177
	v_add_u32_e32 v174, s11, v177
	s_addc_u32 s46, s39, s13
	ds_read_b128 v[158:161], v170
	ds_read_b128 v[162:165], v170 offset:1024
	ds_read_b128 v[166:169], v170 offset:2048
	ds_read_b128 v[170:173], v170 offset:3072
	ds_read_b128 v[180:183], v174
	ds_read_b128 v[186:189], v174 offset:1024
	ds_read_b128 v[190:193], v174 offset:2048
	ds_read_b128 v[194:197], v174 offset:3072
	s_and_b64 s[12:13], s[50:51], exec
	s_cselect_b32 s59, s46, s61
	s_cselect_b32 s58, s42, s60
	s_lshl_b64 s[12:13], s[74:75], 7
	s_add_u32 s42, s40, s12
	s_addc_u32 s46, s41, s13
	s_and_b64 s[12:13], s[50:51], exec
	s_cselect_b32 s53, s46, s63
	s_cselect_b32 s52, s42, s62
	s_add_u32 s50, s58, 0x8000
	s_addc_u32 s51, s59, 0
	s_add_u32 s4, s35, s4
	s_addc_u32 s5, s65, s5
	v_lshl_add_u64 v[174:175], s[4:5], 0, v[128:129]
	s_add_i32 m0, s66, 0xc000
	ds_read_b128 v[198:201], v179
	ds_read_b128 v[202:205], v179 offset:1024
	ds_read_b128 v[206:209], v179 offset:2048
	ds_read_b128 v[210:213], v179 offset:3072
	ds_read_b128 v[214:217], v179 offset:4096
	ds_read_b128 v[218:221], v179 offset:5120
	ds_read_b128 v[222:225], v179 offset:6144
	ds_read_b128 v[226:229], v179 offset:7168
	global_load_lds_dwordx4 v[174:175], off
	v_lshl_add_u64 v[174:175], s[4:5], 0, v[132:133]
	s_add_i32 m0, s66, 0xe000
	s_nop 0
	global_load_lds_dwordx4 v[174:175], off
	s_nop 0
	s_waitcnt vmcnt(8)
	s_waitcnt lgkmcnt(0)
	s_setprio 1
	s_barrier
	v_mfma_f32_16x16x32_bf16 v[124:127], v[158:161], v[198:201], v[124:127]
	v_mfma_f32_16x16x32_bf16 v[120:123], v[166:169], v[198:201], v[120:123]
	v_mfma_f32_16x16x32_bf16 v[116:119], v[158:161], v[206:209], v[116:119]
	v_mfma_f32_16x16x32_bf16 v[112:115], v[166:169], v[206:209], v[112:115]
	v_mfma_f32_16x16x32_bf16 v[108:111], v[158:161], v[214:217], v[108:111]
	v_mfma_f32_16x16x32_bf16 v[104:107], v[166:169], v[214:217], v[104:107]
	v_mfma_f32_16x16x32_bf16 v[100:103], v[158:161], v[222:225], v[100:103]
	v_mfma_f32_16x16x32_bf16 v[96:99], v[166:169], v[222:225], v[96:99]
	v_mfma_f32_16x16x32_bf16 v[124:127], v[162:165], v[202:205], v[124:127]
	v_mfma_f32_16x16x32_bf16 v[120:123], v[170:173], v[202:205], v[120:123]
	v_mfma_f32_16x16x32_bf16 v[116:119], v[162:165], v[210:213], v[116:119]
	v_mfma_f32_16x16x32_bf16 v[112:115], v[170:173], v[210:213], v[112:115]
	v_mfma_f32_16x16x32_bf16 v[108:111], v[162:165], v[218:221], v[108:111]
	v_mfma_f32_16x16x32_bf16 v[104:107], v[170:173], v[218:221], v[104:107]
	v_mfma_f32_16x16x32_bf16 v[100:103], v[162:165], v[226:229], v[100:103]
	v_mfma_f32_16x16x32_bf16 v[96:99], v[170:173], v[226:229], v[96:99]
	s_setprio 0
	s_setprio 1
	v_mfma_f32_16x16x32_bf16 v[92:95], v[180:183], v[198:201], v[92:95]
	v_mfma_f32_16x16x32_bf16 v[88:91], v[190:193], v[198:201], v[88:91]
	v_mfma_f32_16x16x32_bf16 v[84:87], v[180:183], v[206:209], v[84:87]
	v_mfma_f32_16x16x32_bf16 v[80:83], v[190:193], v[206:209], v[80:83]
	v_mfma_f32_16x16x32_bf16 v[76:79], v[180:183], v[214:217], v[76:79]
	v_mfma_f32_16x16x32_bf16 v[72:75], v[190:193], v[214:217], v[72:75]
	v_mfma_f32_16x16x32_bf16 v[68:71], v[180:183], v[222:225], v[68:71]
	v_mfma_f32_16x16x32_bf16 v[64:67], v[190:193], v[222:225], v[64:67]
	v_mfma_f32_16x16x32_bf16 v[92:95], v[186:189], v[202:205], v[92:95]
	v_mfma_f32_16x16x32_bf16 v[88:91], v[194:197], v[202:205], v[88:91]
	v_mfma_f32_16x16x32_bf16 v[84:87], v[186:189], v[210:213], v[84:87]
	v_mfma_f32_16x16x32_bf16 v[80:83], v[194:197], v[210:213], v[80:83]
	v_mfma_f32_16x16x32_bf16 v[76:79], v[186:189], v[218:221], v[76:79]
	v_mfma_f32_16x16x32_bf16 v[72:75], v[194:197], v[218:221], v[72:75]
	v_mfma_f32_16x16x32_bf16 v[68:71], v[186:189], v[226:229], v[68:71]
	v_mfma_f32_16x16x32_bf16 v[64:67], v[194:197], v[226:229], v[64:67]
	s_barrier
	s_setprio 0
	s_add_i32 s4, s10, s9
	v_lshl_add_u64 v[174:175], s[52:53], 0, v[130:131]
	s_mov_b32 m0, s4
	ds_read_b128 v[198:201], v179 offset:16384
	ds_read_b128 v[202:205], v179 offset:17408
	ds_read_b128 v[206:209], v179 offset:18432
	ds_read_b128 v[210:213], v179 offset:19456
	ds_read_b128 v[214:217], v179 offset:20480
	ds_read_b128 v[218:221], v179 offset:21504
	ds_read_b128 v[222:225], v179 offset:22528
	ds_read_b128 v[226:229], v179 offset:23552
	global_load_lds_dwordx4 v[174:175], off
	s_add_i32 m0, s4, 0x2000
	s_add_u32 s4, s52, 0x160000
	v_lshl_add_u64 v[230:231], s[52:53], 0, v[134:135]
	s_addc_u32 s5, s53, 0
	s_add_i32 s12, s11, s9
	global_load_lds_dwordx4 v[230:231], off
	v_lshl_add_u64 v[232:233], s[4:5], 0, v[130:131]
	s_mov_b32 m0, s12
	s_nop 0
	global_load_lds_dwordx4 v[232:233], off
	v_lshl_add_u64 v[232:233], s[4:5], 0, v[134:135]
	s_add_i32 m0, s12, 0x2000
	s_nop 0
	global_load_lds_dwordx4 v[232:233], off
	v_lshl_add_u64 v[232:233], s[58:59], 0, v[128:129]
	s_mov_b32 m0, s66
	s_nop 0
	global_load_lds_dwordx4 v[232:233], off
	v_lshl_add_u64 v[232:233], s[58:59], 0, v[132:133]
	s_mov_b32 m0, s67
	s_nop 0
	global_load_lds_dwordx4 v[232:233], off
	s_nop 0
	s_waitcnt vmcnt(8)
	s_waitcnt lgkmcnt(0)
	s_setprio 1
	s_barrier
; #define PG8_STAGE(bufoff, gbase, voff) do { _Pragma("unroll") for (int _i = 0; _i < 2; ++_i) \
;         __builtin_amdgcn_global_load_lds((const unsigned*)((const char*)(gbase) + (voff)[_i]), (PG8_LAS unsigned*)(lds + (bufoff) + ldsw + _i * 8192), 16, 0, 0); } while (0)
; #define PG8_LDA(dst, b, h) do { _Pragma("unroll") for (int m = 0; m < 4; ++m) _Pragma("unroll") for (int k = 0; k < 2; ++k) dst[m][k] = *(const PG8_LAS bf16x8*)(lds + PG8_SA(b, h) + aoff + m * 2048 + k * 1024); } while (0)
; #define PG8_LDB(dst, b, h) do { _Pragma("unroll") for (int n = 0; n < 2; ++n) _Pragma("unroll") for (int k = 0; k < 2; ++k) dst[n][k] = *(const PG8_LAS bf16x8*)(lds + PG8_SB(b, h) + boff + n * 2048 + k * 1024); } while (0)
; #define PG8_MMA(ai, bj, At, Bt) do { __builtin_amdgcn_s_setprio(1); _Pragma("unroll") for (int m = 0; m < 4; ++m) _Pragma("unroll") for (int n = 0; n < 2; ++n) _Pragma("unroll") for (int k = 0; k < 2; ++k) \
;         acc[ai][bj][m][n] = __builtin_amdgcn_mfma_f32_16x16x32_bf16(Bt[n][k], At[m][k], acc[ai][bj][m][n], 0, 0, 0); __builtin_amdgcn_s_setprio(0); } while (0)
; #define PG8_WAIT_V(n) asm volatile("s_waitcnt vmcnt(" #n ")" ::: "memory")
; #define PG8_WAIT_L(n) asm volatile("s_waitcnt lgkmcnt(" #n ")" ::: "memory")
; #define PG8_BAR __builtin_amdgcn_s_barrier()
; #define PG8_SCHED __builtin_amdgcn_sched_barrier(0)
; template <class Epi, class Sched, bool ALIGN_EPI = false, bool SP2 = false>
; __device__ __forceinline__ void gemm_phase(PG8_LAS unsigned char* lds, const Gemm g, const Sched& S, const Epi& E) {
;     ...
;             PG8_WAIT_V(8); PG8_WAIT_L(0); PG8_BAR; PG8_MMA(1, 0, At, B0); PG8_MMA(1, 1, At, B1); PG8_BAR; PG8_SCHED;
;             PG8_LDB(B0, 1, 0); PG8_LDB(B1, 1, 1); PG8_SCHED; PG8_LDA(At, 1, 0); PG8_STAGE(PG8_SA(0, 1), a2 + hstepA, voffA);
;             PG8_WAIT_V(8); PG8_WAIT_L(0); PG8_BAR; PG8_MMA(0, 0, At, B0); PG8_MMA(0, 1, At, B1); PG8_BAR; PG8_SCHED;
	v_mfma_f32_16x16x32_bf16 v[60:63], v[158:161], v[198:201], v[60:63]
	v_mfma_f32_16x16x32_bf16 v[56:59], v[166:169], v[198:201], v[56:59]
	v_mfma_f32_16x16x32_bf16 v[52:55], v[158:161], v[206:209], v[52:55]
	v_mfma_f32_16x16x32_bf16 v[48:51], v[166:169], v[206:209], v[48:51]
	v_mfma_f32_16x16x32_bf16 v[44:47], v[158:161], v[214:217], v[44:47]
	v_mfma_f32_16x16x32_bf16 v[40:43], v[166:169], v[214:217], v[40:43]
	v_mfma_f32_16x16x32_bf16 v[36:39], v[158:161], v[222:225], v[36:39]
	v_mfma_f32_16x16x32_bf16 v[32:35], v[166:169], v[222:225], v[32:35]
	v_mfma_f32_16x16x32_bf16 v[60:63], v[162:165], v[202:205], v[60:63]
	v_mfma_f32_16x16x32_bf16 v[56:59], v[170:173], v[202:205], v[56:59]
	v_mfma_f32_16x16x32_bf16 v[52:55], v[162:165], v[210:213], v[52:55]
	v_mfma_f32_16x16x32_bf16 v[48:51], v[170:173], v[210:213], v[48:51]
	v_mfma_f32_16x16x32_bf16 v[44:47], v[162:165], v[218:221], v[44:47]
	v_mfma_f32_16x16x32_bf16 v[40:43], v[170:173], v[218:221], v[40:43]
	v_mfma_f32_16x16x32_bf16 v[36:39], v[162:165], v[226:229], v[36:39]
	v_mfma_f32_16x16x32_bf16 v[32:35], v[170:173], v[226:229], v[32:35]
	s_setprio 0
	s_setprio 1
	v_mfma_f32_16x16x32_bf16 v[28:31], v[180:183], v[198:201], v[28:31]
	v_mfma_f32_16x16x32_bf16 v[24:27], v[190:193], v[198:201], v[24:27]
	v_mfma_f32_16x16x32_bf16 v[20:23], v[180:183], v[206:209], v[20:23]
	v_mfma_f32_16x16x32_bf16 v[16:19], v[190:193], v[206:209], v[16:19]
	v_mfma_f32_16x16x32_bf16 v[12:15], v[180:183], v[214:217], v[12:15]
	v_mfma_f32_16x16x32_bf16 v[8:11], v[190:193], v[214:217], v[8:11]
	v_mfma_f32_16x16x32_bf16 v[4:7], v[180:183], v[222:225], v[4:7]
	v_mfma_f32_16x16x32_bf16 v[0:3], v[190:193], v[222:225], v[0:3]
	v_mfma_f32_16x16x32_bf16 v[28:31], v[186:189], v[202:205], v[28:31]
	v_mfma_f32_16x16x32_bf16 v[24:27], v[194:197], v[202:205], v[24:27]
	v_mfma_f32_16x16x32_bf16 v[20:23], v[186:189], v[210:213], v[20:23]
	v_mfma_f32_16x16x32_bf16 v[16:19], v[194:197], v[210:213], v[16:19]
	v_mfma_f32_16x16x32_bf16 v[12:15], v[186:189], v[218:221], v[12:15]
	v_mfma_f32_16x16x32_bf16 v[8:11], v[194:197], v[218:221], v[8:11]
	v_mfma_f32_16x16x32_bf16 v[4:7], v[186:189], v[226:229], v[4:7]
	v_mfma_f32_16x16x32_bf16 v[0:3], v[194:197], v[226:229], v[0:3]
	s_barrier
	s_setprio 0
	s_add_i32 s12, 0, 0x18000
	s_add_i32 s13, 0, 0x1c000
	v_add_u32_e32 v170, s12, v177
	v_add_u32_e32 v185, s13, v177
	ds_read_b128 v[158:161], v170
	ds_read_b128 v[162:165], v170 offset:1024
	ds_read_b128 v[166:169], v170 offset:2048
	ds_read_b128 v[170:173], v170 offset:3072
	ds_read_b128 v[180:183], v185
	ds_read_b128 v[186:189], v185 offset:1024
	ds_read_b128 v[190:193], v185 offset:2048
	ds_read_b128 v[194:197], v185 offset:3072
	s_add_u32 s4, s58, 0x4000
	s_addc_u32 s5, s59, 0
	s_mov_b32 m0, s76
	v_lshl_add_u64 v[232:233], s[4:5], 0, v[128:129]
	ds_read_b128 v[198:201], v179 offset:32768
	ds_read_b128 v[202:205], v179 offset:33792
	ds_read_b128 v[206:209], v179 offset:34816
	ds_read_b128 v[210:213], v179 offset:35840
	ds_read_b128 v[214:217], v179 offset:36864
	ds_read_b128 v[218:221], v179 offset:37888
	ds_read_b128 v[222:225], v179 offset:38912
	ds_read_b128 v[226:229], v179 offset:39936
	global_load_lds_dwordx4 v[232:233], off
	v_lshl_add_u64 v[232:233], s[4:5], 0, v[132:133]
	s_mov_b32 m0, s77
	s_nop 0
	global_load_lds_dwordx4 v[232:233], off
	s_waitcnt vmcnt(8)
	s_waitcnt lgkmcnt(0)
	s_setprio 1
	s_barrier
	v_mfma_f32_16x16x32_bf16 v[124:127], v[158:161], v[198:201], v[124:127]
	v_mfma_f32_16x16x32_bf16 v[120:123], v[166:169], v[198:201], v[120:123]
	v_mfma_f32_16x16x32_bf16 v[116:119], v[158:161], v[206:209], v[116:119]
	v_mfma_f32_16x16x32_bf16 v[112:115], v[166:169], v[206:209], v[112:115]
	v_mfma_f32_16x16x32_bf16 v[108:111], v[158:161], v[214:217], v[108:111]
	v_mfma_f32_16x16x32_bf16 v[104:107], v[166:169], v[214:217], v[104:107]
	v_mfma_f32_16x16x32_bf16 v[100:103], v[158:161], v[222:225], v[100:103]
	v_mfma_f32_16x16x32_bf16 v[96:99], v[166:169], v[222:225], v[96:99]
	v_mfma_f32_16x16x32_bf16 v[124:127], v[162:165], v[202:205], v[124:127]
	v_mfma_f32_16x16x32_bf16 v[120:123], v[170:173], v[202:205], v[120:123]
	v_mfma_f32_16x16x32_bf16 v[116:119], v[162:165], v[210:213], v[116:119]
	v_mfma_f32_16x16x32_bf16 v[112:115], v[170:173], v[210:213], v[112:115]
	v_mfma_f32_16x16x32_bf16 v[108:111], v[162:165], v[218:221], v[108:111]
	v_mfma_f32_16x16x32_bf16 v[104:107], v[170:173], v[218:221], v[104:107]
	v_mfma_f32_16x16x32_bf16 v[100:103], v[162:165], v[226:229], v[100:103]
	v_mfma_f32_16x16x32_bf16 v[96:99], v[170:173], v[226:229], v[96:99]
	s_setprio 0
	s_setprio 1
	v_mfma_f32_16x16x32_bf16 v[92:95], v[180:183], v[198:201], v[92:95]
	v_mfma_f32_16x16x32_bf16 v[88:91], v[190:193], v[198:201], v[88:91]
	v_mfma_f32_16x16x32_bf16 v[84:87], v[180:183], v[206:209], v[84:87]
	v_mfma_f32_16x16x32_bf16 v[80:83], v[190:193], v[206:209], v[80:83]
	v_mfma_f32_16x16x32_bf16 v[76:79], v[180:183], v[214:217], v[76:79]
	v_mfma_f32_16x16x32_bf16 v[72:75], v[190:193], v[214:217], v[72:75]
	v_mfma_f32_16x16x32_bf16 v[68:71], v[180:183], v[222:225], v[68:71]
	v_mfma_f32_16x16x32_bf16 v[64:67], v[190:193], v[222:225], v[64:67]
	v_mfma_f32_16x16x32_bf16 v[92:95], v[186:189], v[202:205], v[92:95]
	v_mfma_f32_16x16x32_bf16 v[88:91], v[194:197], v[202:205], v[88:91]
	v_mfma_f32_16x16x32_bf16 v[84:87], v[186:189], v[210:213], v[84:87]
	v_mfma_f32_16x16x32_bf16 v[80:83], v[194:197], v[210:213], v[80:83]
	v_mfma_f32_16x16x32_bf16 v[76:79], v[186:189], v[218:221], v[76:79]
	v_mfma_f32_16x16x32_bf16 v[72:75], v[194:197], v[218:221], v[72:75]
	v_mfma_f32_16x16x32_bf16 v[68:71], v[186:189], v[226:229], v[68:71]
	v_mfma_f32_16x16x32_bf16 v[64:67], v[194:197], v[226:229], v[64:67]
	s_barrier
; #define PG8_STAGE(bufoff, gbase, voff) do { _Pragma("unroll") for (int _i = 0; _i < 2; ++_i) \
;         __builtin_amdgcn_global_load_lds((const unsigned*)((const char*)(gbase) + (voff)[_i]), (PG8_LAS unsigned*)(lds + (bufoff) + ldsw + _i * 8192), 16, 0, 0); } while (0)
; #define PG8_LDA(dst, b, h) do { _Pragma("unroll") for (int m = 0; m < 4; ++m) _Pragma("unroll") for (int k = 0; k < 2; ++k) dst[m][k] = *(const PG8_LAS bf16x8*)(lds + PG8_SA(b, h) + aoff + m * 2048 + k * 1024); } while (0)
; #define PG8_MMA(ai, bj, At, Bt) do { __builtin_amdgcn_s_setprio(1); _Pragma("unroll") for (int m = 0; m < 4; ++m) _Pragma("unroll") for (int n = 0; n < 2; ++n) _Pragma("unroll") for (int k = 0; k < 2; ++k) \
;         acc[ai][bj][m][n] = __builtin_amdgcn_mfma_f32_16x16x32_bf16(Bt[n][k], At[m][k], acc[ai][bj][m][n], 0, 0, 0); __builtin_amdgcn_s_setprio(0); } while (0)
; #define PG8_WAIT_V(n) asm volatile("s_waitcnt vmcnt(" #n ")" ::: "memory")
; #define PG8_WAIT_L(n) asm volatile("s_waitcnt lgkmcnt(" #n ")" ::: "memory")
; #define PG8_BAR __builtin_amdgcn_s_barrier()
; #define PG8_SCHED __builtin_amdgcn_sched_barrier(0)
; template <class Epi, class Sched, bool ALIGN_EPI = false, bool SP2 = false>
; __device__ __forceinline__ void gemm_phase(PG8_LAS unsigned char* lds, const Gemm g, const Sched& S, const Epi& E) {
;     ...
;         for (int t = 0; t < nt; t += 2) {
;             const bool last = (t == nt - 2);
;     ...
;             PG8_LDA(At, 1, 1); PG8_STAGE(PG8_SB(1, 0), b3, voffB); PG8_STAGE(PG8_SB(1, 1), b3 + hstepB, voffB); PG8_STAGE(PG8_SA(1, 0), a3, voffA);
;             PG8_WAIT_V(8); PG8_WAIT_L(0); PG8_BAR; PG8_MMA(1, 0, At, B0); PG8_MMA(1, 1, At, B1); PG8_BAR; PG8_SCHED;
	s_setprio 0
	s_add_i32 s4, s12, s9
	v_lshl_add_u64 v[174:175], v[174:175], 0, s[54:55]
	s_mov_b32 m0, s4
	ds_read_b128 v[198:201], v179 offset:49152
	ds_read_b128 v[202:205], v179 offset:50176
	ds_read_b128 v[206:209], v179 offset:51200
	ds_read_b128 v[210:213], v179 offset:52224
	ds_read_b128 v[214:217], v179 offset:53248
	ds_read_b128 v[218:221], v179 offset:54272
	ds_read_b128 v[222:225], v179 offset:55296
	ds_read_b128 v[226:229], v179 offset:56320
	global_load_lds_dwordx4 v[174:175], off
	s_add_i32 m0, s4, 0x2000
	s_add_u32 s4, s52, 0x160080
	v_lshl_add_u64 v[174:175], v[230:231], 0, s[54:55]
	s_addc_u32 s5, s53, 0
	s_add_i32 s12, s13, s9
	global_load_lds_dwordx4 v[174:175], off
	v_lshl_add_u64 v[174:175], s[4:5], 0, v[130:131]
	s_mov_b32 m0, s12
	s_nop 0
	global_load_lds_dwordx4 v[174:175], off
	v_lshl_add_u64 v[174:175], s[4:5], 0, v[134:135]
	s_add_i32 m0, s12, 0x2000
	s_nop 0
	global_load_lds_dwordx4 v[174:175], off
	v_lshl_add_u64 v[174:175], s[50:51], 0, v[128:129]
	s_mov_b32 m0, s45
	s_nop 0
	global_load_lds_dwordx4 v[174:175], off
	v_lshl_add_u64 v[174:175], s[50:51], 0, v[132:133]
	s_mov_b32 m0, s56
	s_nop 0
	global_load_lds_dwordx4 v[174:175], off
	s_nop 0
	s_waitcnt vmcnt(8)
	s_waitcnt lgkmcnt(0)
	s_setprio 1
	s_barrier
	v_mfma_f32_16x16x32_bf16 v[60:63], v[158:161], v[198:201], v[60:63]
	v_mfma_f32_16x16x32_bf16 v[56:59], v[166:169], v[198:201], v[56:59]
	v_mfma_f32_16x16x32_bf16 v[52:55], v[158:161], v[206:209], v[52:55]
	v_mfma_f32_16x16x32_bf16 v[48:51], v[166:169], v[206:209], v[48:51]
	v_mfma_f32_16x16x32_bf16 v[44:47], v[158:161], v[214:217], v[44:47]
	v_mfma_f32_16x16x32_bf16 v[40:43], v[166:169], v[214:217], v[40:43]
	v_mfma_f32_16x16x32_bf16 v[36:39], v[158:161], v[222:225], v[36:39]
	v_mfma_f32_16x16x32_bf16 v[32:35], v[166:169], v[222:225], v[32:35]
	v_mfma_f32_16x16x32_bf16 v[60:63], v[162:165], v[202:205], v[60:63]
	v_mfma_f32_16x16x32_bf16 v[56:59], v[170:173], v[202:205], v[56:59]
	v_mfma_f32_16x16x32_bf16 v[52:55], v[162:165], v[210:213], v[52:55]
	v_mfma_f32_16x16x32_bf16 v[48:51], v[170:173], v[210:213], v[48:51]
	v_mfma_f32_16x16x32_bf16 v[44:47], v[162:165], v[218:221], v[44:47]
	v_mfma_f32_16x16x32_bf16 v[40:43], v[170:173], v[218:221], v[40:43]
	v_mfma_f32_16x16x32_bf16 v[36:39], v[162:165], v[226:229], v[36:39]
	v_mfma_f32_16x16x32_bf16 v[32:35], v[170:173], v[226:229], v[32:35]
	s_setprio 0
	s_setprio 1
	v_mfma_f32_16x16x32_bf16 v[28:31], v[180:183], v[198:201], v[28:31]
	v_mfma_f32_16x16x32_bf16 v[24:27], v[190:193], v[198:201], v[24:27]
	v_mfma_f32_16x16x32_bf16 v[20:23], v[180:183], v[206:209], v[20:23]
	v_mfma_f32_16x16x32_bf16 v[16:19], v[190:193], v[206:209], v[16:19]
	v_mfma_f32_16x16x32_bf16 v[12:15], v[180:183], v[214:217], v[12:15]
	v_mfma_f32_16x16x32_bf16 v[8:11], v[190:193], v[214:217], v[8:11]
	v_mfma_f32_16x16x32_bf16 v[4:7], v[180:183], v[222:225], v[4:7]
	v_mfma_f32_16x16x32_bf16 v[0:3], v[190:193], v[222:225], v[0:3]
	v_mfma_f32_16x16x32_bf16 v[28:31], v[186:189], v[202:205], v[28:31]
	v_mfma_f32_16x16x32_bf16 v[24:27], v[194:197], v[202:205], v[24:27]
	v_mfma_f32_16x16x32_bf16 v[20:23], v[186:189], v[210:213], v[20:23]
	v_mfma_f32_16x16x32_bf16 v[16:19], v[194:197], v[210:213], v[16:19]
	v_mfma_f32_16x16x32_bf16 v[12:15], v[186:189], v[218:221], v[12:15]
	v_mfma_f32_16x16x32_bf16 v[8:11], v[194:197], v[218:221], v[8:11]
	v_mfma_f32_16x16x32_bf16 v[4:7], v[186:189], v[226:229], v[4:7]
	v_mfma_f32_16x16x32_bf16 v[0:3], v[194:197], v[226:229], v[0:3]
	s_barrier
	s_setprio 0
	s_cmp_ge_i32 s74, s57
	s_cbranch_scc1 .LBB0_409

; #define PG8_STAGE(bufoff, gbase, voff) do { _Pragma("unroll") for (int _i = 0; _i < 2; ++_i) \
;         __builtin_amdgcn_global_load_lds((const unsigned*)((const char*)(gbase) + (voff)[_i]), (PG8_LAS unsigned*)(lds + (bufoff) + ldsw + _i * 8192), 16, 0, 0); } while (0)
; #define PG8_LDA(dst, b, h) do { _Pragma("unroll") for (int m = 0; m < 4; ++m) _Pragma("unroll") for (int k = 0; k < 2; ++k) dst[m][k] = *(const PG8_LAS bf16x8*)(lds + PG8_SA(b, h) + aoff + m * 2048 + k * 1024); } while (0)
; #define PG8_LDB(dst, b, h) do { _Pragma("unroll") for (int n = 0; n < 2; ++n) _Pragma("unroll") for (int k = 0; k < 2; ++k) dst[n][k] = *(const PG8_LAS bf16x8*)(lds + PG8_SB(b, h) + boff + n * 2048 + k * 1024); } while (0)
; #define PG8_MMA(ai, bj, At, Bt) do { __builtin_amdgcn_s_setprio(1); _Pragma("unroll") for (int m = 0; m < 4; ++m) _Pragma("unroll") for (int n = 0; n < 2; ++n) _Pragma("unroll") for (int k = 0; k < 2; ++k) \
;         acc[ai][bj][m][n] = __builtin_amdgcn_mfma_f32_16x16x32_bf16(Bt[n][k], At[m][k], acc[ai][bj][m][n], 0, 0, 0); __builtin_amdgcn_s_setprio(0); } while (0)
; #define PG8_WAIT_V(n) asm volatile("s_waitcnt vmcnt(" #n ")" ::: "memory")
; #define PG8_WAIT_L(n) asm volatile("s_waitcnt lgkmcnt(" #n ")" ::: "memory")
; #define PG8_BAR __builtin_amdgcn_s_barrier()
; #define PG8_SCHED __builtin_amdgcn_sched_barrier(0)
; template <class Epi, class Sched, bool ALIGN_EPI = false, bool SP2 = false>
; __device__ __forceinline__ void gemm_phase(PG8_LAS unsigned char* lds, const Gemm g, const Sched& S, const Epi& E) {
;     ...
;             PG8_LDB(B0, 0, 0); PG8_LDB(B1, 0, 1); PG8_SCHED; PG8_LDA(At, 0, 0); PG8_STAGE(PG8_SA(1, 1), a1 + hstepA, voffA);
;             PG8_WAIT_V(8); PG8_WAIT_L(0); PG8_BAR; PG8_MMA(0, 0, At, B0); PG8_MMA(0, 1, At, B1); PG8_BAR; PG8_SCHED;
;             PG8_LDA(At, 0, 1); PG8_STAGE(PG8_SB(0, 0), b2, voffB); PG8_STAGE(PG8_SB(0, 1), b2 + hstepB, voffB); PG8_STAGE(PG8_SA(0, 0), a2, voffA);
;             PG8_WAIT_V(8); PG8_WAIT_L(0); PG8_BAR; PG8_MMA(1, 0, At, B0); PG8_MMA(1, 1, At, B1); PG8_BAR; PG8_SCHED;
.LBB0_656:
	ds_read_b128 v[166:169], v163
	ds_read_b128 v[170:173], v163 offset:1024
	ds_read_b128 v[174:177], v163 offset:2048
	ds_read_b128 v[178:181], v163 offset:3072
	ds_read_b128 v[186:189], v164
	ds_read_b128 v[190:193], v164 offset:1024
	ds_read_b128 v[194:197], v164 offset:2048
	ds_read_b128 v[198:201], v164 offset:3072
	s_add_u32 s47, s50, 0xfff80080
	s_addc_u32 s52, s51, -1
	s_cmp_eq_u32 s46, 28
	s_cselect_b32 s59, s63, s52
	s_cselect_b32 s58, s62, s47
	s_cselect_b32 s53, s65, s5
	s_cselect_b32 s52, s64, s4
	v_lshl_add_u64 v[158:159], s[50:51], 0, v[152:153]
	s_add_i32 m0, s9, 0xc000
	ds_read_b128 v[202:205], v165
	ds_read_b128 v[206:209], v165 offset:1024
	ds_read_b128 v[210:213], v165 offset:2048
	ds_read_b128 v[214:217], v165 offset:3072
	ds_read_b128 v[218:221], v165 offset:4096
	ds_read_b128 v[222:225], v165 offset:5120
	ds_read_b128 v[226:229], v165 offset:6144
	ds_read_b128 v[230:233], v165 offset:7168
	global_load_lds_dwordx4 v[158:159], off
	v_lshl_add_u64 v[158:159], s[50:51], 0, v[154:155]
	s_add_i32 m0, s9, 0xe000
	s_nop 0
	global_load_lds_dwordx4 v[158:159], off
	s_nop 0
	s_waitcnt vmcnt(8)
	s_waitcnt lgkmcnt(0)
	s_setprio 1
	s_barrier
	v_mfma_f32_16x16x32_bf16 v[124:127], v[166:169], v[202:205], v[124:127]
	v_mfma_f32_16x16x32_bf16 v[120:123], v[174:177], v[202:205], v[120:123]
	v_mfma_f32_16x16x32_bf16 v[112:115], v[166:169], v[210:213], v[112:115]
	v_mfma_f32_16x16x32_bf16 v[104:107], v[174:177], v[210:213], v[104:107]
	v_mfma_f32_16x16x32_bf16 v[96:99], v[166:169], v[218:221], v[96:99]
	v_mfma_f32_16x16x32_bf16 v[88:91], v[174:177], v[218:221], v[88:91]
	v_mfma_f32_16x16x32_bf16 v[80:83], v[166:169], v[226:229], v[80:83]
	v_mfma_f32_16x16x32_bf16 v[72:75], v[174:177], v[226:229], v[72:75]
	v_mfma_f32_16x16x32_bf16 v[124:127], v[170:173], v[206:209], v[124:127]
	v_mfma_f32_16x16x32_bf16 v[120:123], v[178:181], v[206:209], v[120:123]
	v_mfma_f32_16x16x32_bf16 v[112:115], v[170:173], v[214:217], v[112:115]
	v_mfma_f32_16x16x32_bf16 v[104:107], v[178:181], v[214:217], v[104:107]
	v_mfma_f32_16x16x32_bf16 v[96:99], v[170:173], v[222:225], v[96:99]
	v_mfma_f32_16x16x32_bf16 v[88:91], v[178:181], v[222:225], v[88:91]
	v_mfma_f32_16x16x32_bf16 v[80:83], v[170:173], v[230:233], v[80:83]
	v_mfma_f32_16x16x32_bf16 v[72:75], v[178:181], v[230:233], v[72:75]
	s_setprio 0
	s_setprio 1
	v_mfma_f32_16x16x32_bf16 v[116:119], v[186:189], v[202:205], v[116:119]
	v_mfma_f32_16x16x32_bf16 v[108:111], v[194:197], v[202:205], v[108:111]
	v_mfma_f32_16x16x32_bf16 v[100:103], v[186:189], v[210:213], v[100:103]
	v_mfma_f32_16x16x32_bf16 v[92:95], v[194:197], v[210:213], v[92:95]
	v_mfma_f32_16x16x32_bf16 v[84:87], v[186:189], v[218:221], v[84:87]
	v_mfma_f32_16x16x32_bf16 v[76:79], v[194:197], v[218:221], v[76:79]
	v_mfma_f32_16x16x32_bf16 v[68:71], v[186:189], v[226:229], v[68:71]
	v_mfma_f32_16x16x32_bf16 v[64:67], v[194:197], v[226:229], v[64:67]
	v_mfma_f32_16x16x32_bf16 v[116:119], v[190:193], v[206:209], v[116:119]
	v_mfma_f32_16x16x32_bf16 v[108:111], v[198:201], v[206:209], v[108:111]
	v_mfma_f32_16x16x32_bf16 v[100:103], v[190:193], v[214:217], v[100:103]
	v_mfma_f32_16x16x32_bf16 v[92:95], v[198:201], v[214:217], v[92:95]
	v_mfma_f32_16x16x32_bf16 v[84:87], v[190:193], v[222:225], v[84:87]
	v_mfma_f32_16x16x32_bf16 v[76:79], v[198:201], v[222:225], v[76:79]
	v_mfma_f32_16x16x32_bf16 v[68:71], v[190:193], v[230:233], v[68:71]
	v_mfma_f32_16x16x32_bf16 v[64:67], v[198:201], v[230:233], v[64:67]
	s_barrier
	s_setprio 0
	s_add_i32 s47, s44, s8
	v_lshl_add_u64 v[158:159], s[52:53], 0, v[130:131]
	s_mov_b32 m0, s47
	ds_read_b128 v[202:205], v165 offset:16384
	ds_read_b128 v[206:209], v165 offset:17408
	ds_read_b128 v[210:213], v165 offset:18432
	ds_read_b128 v[214:217], v165 offset:19456
	ds_read_b128 v[218:221], v165 offset:20480
	ds_read_b128 v[222:225], v165 offset:21504
	ds_read_b128 v[226:229], v165 offset:22528
	ds_read_b128 v[230:233], v165 offset:23552
	global_load_lds_dwordx4 v[158:159], off
	s_add_i32 m0, s47, 0x2000
	s_add_u32 s66, s52, 0x80000
	v_lshl_add_u64 v[182:183], s[52:53], 0, v[134:135]
	s_addc_u32 s67, s53, 0
	s_add_i32 s47, s45, s8
	global_load_lds_dwordx4 v[182:183], off
	v_lshl_add_u64 v[234:235], s[66:67], 0, v[130:131]
	s_mov_b32 m0, s47
	v_lshl_add_u64 v[236:237], s[58:59], 0, v[132:133]
	global_load_lds_dwordx4 v[234:235], off
	v_lshl_add_u64 v[234:235], s[66:67], 0, v[134:135]
	s_add_i32 m0, s47, 0x2000
	s_nop 0
	global_load_lds_dwordx4 v[234:235], off
	v_lshl_add_u64 v[234:235], s[58:59], 0, v[128:129]
	s_mov_b32 m0, s9
	s_nop 0
	global_load_lds_dwordx4 v[234:235], off
	s_mov_b32 m0, s10
	s_nop 0
	global_load_lds_dwordx4 v[236:237], off
	s_waitcnt vmcnt(8)
	s_waitcnt lgkmcnt(0)
	s_setprio 1
	s_barrier
; #define PG8_STAGE(bufoff, gbase, voff) do { _Pragma("unroll") for (int _i = 0; _i < 2; ++_i) \
;         __builtin_amdgcn_global_load_lds((const unsigned*)((const char*)(gbase) + (voff)[_i]), (PG8_LAS unsigned*)(lds + (bufoff) + ldsw + _i * 8192), 16, 0, 0); } while (0)
; #define PG8_LDA(dst, b, h) do { _Pragma("unroll") for (int m = 0; m < 4; ++m) _Pragma("unroll") for (int k = 0; k < 2; ++k) dst[m][k] = *(const PG8_LAS bf16x8*)(lds + PG8_SA(b, h) + aoff + m * 2048 + k * 1024); } while (0)
; #define PG8_LDB(dst, b, h) do { _Pragma("unroll") for (int n = 0; n < 2; ++n) _Pragma("unroll") for (int k = 0; k < 2; ++k) dst[n][k] = *(const PG8_LAS bf16x8*)(lds + PG8_SB(b, h) + boff + n * 2048 + k * 1024); } while (0)
; #define PG8_MMA(ai, bj, At, Bt) do { __builtin_amdgcn_s_setprio(1); _Pragma("unroll") for (int m = 0; m < 4; ++m) _Pragma("unroll") for (int n = 0; n < 2; ++n) _Pragma("unroll") for (int k = 0; k < 2; ++k) \
;         acc[ai][bj][m][n] = __builtin_amdgcn_mfma_f32_16x16x32_bf16(Bt[n][k], At[m][k], acc[ai][bj][m][n], 0, 0, 0); __builtin_amdgcn_s_setprio(0); } while (0)
; #define PG8_WAIT_V(n) asm volatile("s_waitcnt vmcnt(" #n ")" ::: "memory")
; #define PG8_WAIT_L(n) asm volatile("s_waitcnt lgkmcnt(" #n ")" ::: "memory")
; #define PG8_BAR __builtin_amdgcn_s_barrier()
; #define PG8_SCHED __builtin_amdgcn_sched_barrier(0)
; template <class Epi, class Sched, bool ALIGN_EPI = false, bool SP2 = false>
; __device__ __forceinline__ void gemm_phase(PG8_LAS unsigned char* lds, const Gemm g, const Sched& S, const Epi& E) {
;     ...
;             PG8_WAIT_V(8); PG8_WAIT_L(0); PG8_BAR; PG8_MMA(1, 0, At, B0); PG8_MMA(1, 1, At, B1); PG8_BAR; PG8_SCHED;
;             PG8_LDB(B0, 1, 0); PG8_LDB(B1, 1, 1); PG8_SCHED; PG8_LDA(At, 1, 0); PG8_STAGE(PG8_SA(0, 1), a2 + hstepA, voffA);
;             PG8_WAIT_V(8); PG8_WAIT_L(0); PG8_BAR; PG8_MMA(0, 0, At, B0); PG8_MMA(0, 1, At, B1); PG8_BAR; PG8_SCHED;
	v_mfma_f32_16x16x32_bf16 v[60:63], v[166:169], v[202:205], v[60:63]
	v_mfma_f32_16x16x32_bf16 v[56:59], v[174:177], v[202:205], v[56:59]
	v_mfma_f32_16x16x32_bf16 v[48:51], v[166:169], v[210:213], v[48:51]
	v_mfma_f32_16x16x32_bf16 v[40:43], v[174:177], v[210:213], v[40:43]
	v_mfma_f32_16x16x32_bf16 v[32:35], v[166:169], v[218:221], v[32:35]
	v_mfma_f32_16x16x32_bf16 v[24:27], v[174:177], v[218:221], v[24:27]
	v_mfma_f32_16x16x32_bf16 v[16:19], v[166:169], v[226:229], v[16:19]
	v_mfma_f32_16x16x32_bf16 v[8:11], v[174:177], v[226:229], v[8:11]
	v_mfma_f32_16x16x32_bf16 v[60:63], v[170:173], v[206:209], v[60:63]
	v_mfma_f32_16x16x32_bf16 v[56:59], v[178:181], v[206:209], v[56:59]
	v_mfma_f32_16x16x32_bf16 v[48:51], v[170:173], v[214:217], v[48:51]
	v_mfma_f32_16x16x32_bf16 v[40:43], v[178:181], v[214:217], v[40:43]
	v_mfma_f32_16x16x32_bf16 v[32:35], v[170:173], v[222:225], v[32:35]
	v_mfma_f32_16x16x32_bf16 v[24:27], v[178:181], v[222:225], v[24:27]
	v_mfma_f32_16x16x32_bf16 v[16:19], v[170:173], v[230:233], v[16:19]
	v_mfma_f32_16x16x32_bf16 v[8:11], v[178:181], v[230:233], v[8:11]
	s_setprio 0
	s_setprio 1
	v_mfma_f32_16x16x32_bf16 v[52:55], v[186:189], v[202:205], v[52:55]
	v_mfma_f32_16x16x32_bf16 v[44:47], v[194:197], v[202:205], v[44:47]
	v_mfma_f32_16x16x32_bf16 v[36:39], v[186:189], v[210:213], v[36:39]
	v_mfma_f32_16x16x32_bf16 v[28:31], v[194:197], v[210:213], v[28:31]
	v_mfma_f32_16x16x32_bf16 v[20:23], v[186:189], v[218:221], v[20:23]
	v_mfma_f32_16x16x32_bf16 v[12:15], v[194:197], v[218:221], v[12:15]
	v_mfma_f32_16x16x32_bf16 v[4:7], v[186:189], v[226:229], v[4:7]
	v_mfma_f32_16x16x32_bf16 v[0:3], v[194:197], v[226:229], v[0:3]
	v_mfma_f32_16x16x32_bf16 v[52:55], v[190:193], v[206:209], v[52:55]
	v_mfma_f32_16x16x32_bf16 v[44:47], v[198:201], v[206:209], v[44:47]
	v_mfma_f32_16x16x32_bf16 v[36:39], v[190:193], v[214:217], v[36:39]
	v_mfma_f32_16x16x32_bf16 v[28:31], v[198:201], v[214:217], v[28:31]
	v_mfma_f32_16x16x32_bf16 v[20:23], v[190:193], v[222:225], v[20:23]
	v_mfma_f32_16x16x32_bf16 v[12:15], v[198:201], v[222:225], v[12:15]
	v_mfma_f32_16x16x32_bf16 v[4:7], v[190:193], v[230:233], v[4:7]
	v_mfma_f32_16x16x32_bf16 v[0:3], v[198:201], v[230:233], v[0:3]
	s_barrier
	s_setprio 0
	s_add_i32 s47, 0, 0x18000
	s_add_i32 s55, 0, 0x1c000
	v_add_u32_e32 v178, s47, v160
	v_add_u32_e32 v185, s55, v160
	ds_read_b128 v[166:169], v178
	ds_read_b128 v[170:173], v178 offset:1024
	ds_read_b128 v[174:177], v178 offset:2048
	ds_read_b128 v[178:181], v178 offset:3072
	ds_read_b128 v[186:189], v185
	ds_read_b128 v[190:193], v185 offset:1024
	ds_read_b128 v[194:197], v185 offset:2048
	ds_read_b128 v[198:201], v185 offset:3072
	s_add_u32 s58, s58, 0x80000
	s_addc_u32 s59, s59, 0
	s_mov_b32 m0, s11
	v_lshl_add_u64 v[238:239], s[58:59], 0, v[128:129]
	ds_read_b128 v[202:205], v165 offset:32768
	ds_read_b128 v[206:209], v165 offset:33792
	ds_read_b128 v[210:213], v165 offset:34816
	ds_read_b128 v[214:217], v165 offset:35840
	ds_read_b128 v[218:221], v165 offset:36864
	ds_read_b128 v[222:225], v165 offset:37888
	ds_read_b128 v[226:229], v165 offset:38912
	ds_read_b128 v[230:233], v165 offset:39936
	global_load_lds_dwordx4 v[238:239], off
	v_lshl_add_u64 v[238:239], s[58:59], 0, v[132:133]
	s_mov_b32 m0, s12
	s_nop 0
	global_load_lds_dwordx4 v[238:239], off
	s_waitcnt vmcnt(8)
	s_waitcnt lgkmcnt(0)
	s_setprio 1
	s_barrier
	v_mfma_f32_16x16x32_bf16 v[124:127], v[166:169], v[202:205], v[124:127]
	v_mfma_f32_16x16x32_bf16 v[120:123], v[174:177], v[202:205], v[120:123]
	v_mfma_f32_16x16x32_bf16 v[112:115], v[166:169], v[210:213], v[112:115]
	v_mfma_f32_16x16x32_bf16 v[104:107], v[174:177], v[210:213], v[104:107]
	v_mfma_f32_16x16x32_bf16 v[96:99], v[166:169], v[218:221], v[96:99]
	v_mfma_f32_16x16x32_bf16 v[88:91], v[174:177], v[218:221], v[88:91]
	v_mfma_f32_16x16x32_bf16 v[80:83], v[166:169], v[226:229], v[80:83]
	v_mfma_f32_16x16x32_bf16 v[72:75], v[174:177], v[226:229], v[72:75]
	v_mfma_f32_16x16x32_bf16 v[124:127], v[170:173], v[206:209], v[124:127]
	v_mfma_f32_16x16x32_bf16 v[120:123], v[178:181], v[206:209], v[120:123]
	v_mfma_f32_16x16x32_bf16 v[112:115], v[170:173], v[214:217], v[112:115]
	v_mfma_f32_16x16x32_bf16 v[104:107], v[178:181], v[214:217], v[104:107]
	v_mfma_f32_16x16x32_bf16 v[96:99], v[170:173], v[222:225], v[96:99]
	v_mfma_f32_16x16x32_bf16 v[88:91], v[178:181], v[222:225], v[88:91]
	v_mfma_f32_16x16x32_bf16 v[80:83], v[170:173], v[230:233], v[80:83]
	v_mfma_f32_16x16x32_bf16 v[72:75], v[178:181], v[230:233], v[72:75]
	s_setprio 0
	s_setprio 1
	v_mfma_f32_16x16x32_bf16 v[116:119], v[186:189], v[202:205], v[116:119]
	v_mfma_f32_16x16x32_bf16 v[108:111], v[194:197], v[202:205], v[108:111]
	v_mfma_f32_16x16x32_bf16 v[100:103], v[186:189], v[210:213], v[100:103]
	v_mfma_f32_16x16x32_bf16 v[92:95], v[194:197], v[210:213], v[92:95]
	v_mfma_f32_16x16x32_bf16 v[84:87], v[186:189], v[218:221], v[84:87]
	v_mfma_f32_16x16x32_bf16 v[76:79], v[194:197], v[218:221], v[76:79]
	v_mfma_f32_16x16x32_bf16 v[68:71], v[186:189], v[226:229], v[68:71]
	v_mfma_f32_16x16x32_bf16 v[64:67], v[194:197], v[226:229], v[64:67]
	v_mfma_f32_16x16x32_bf16 v[116:119], v[190:193], v[206:209], v[116:119]
	v_mfma_f32_16x16x32_bf16 v[108:111], v[198:201], v[206:209], v[108:111]
	v_mfma_f32_16x16x32_bf16 v[100:103], v[190:193], v[214:217], v[100:103]
	v_mfma_f32_16x16x32_bf16 v[92:95], v[198:201], v[214:217], v[92:95]
	v_mfma_f32_16x16x32_bf16 v[84:87], v[190:193], v[222:225], v[84:87]
	v_mfma_f32_16x16x32_bf16 v[76:79], v[198:201], v[222:225], v[76:79]
	v_mfma_f32_16x16x32_bf16 v[68:71], v[190:193], v[230:233], v[68:71]
	v_mfma_f32_16x16x32_bf16 v[64:67], v[198:201], v[230:233], v[64:67]
	s_barrier
; #define PG8_STAGE(bufoff, gbase, voff) do { _Pragma("unroll") for (int _i = 0; _i < 2; ++_i) \
;         __builtin_amdgcn_global_load_lds((const unsigned*)((const char*)(gbase) + (voff)[_i]), (PG8_LAS unsigned*)(lds + (bufoff) + ldsw + _i * 8192), 16, 0, 0); } while (0)
; #define PG8_LDA(dst, b, h) do { _Pragma("unroll") for (int m = 0; m < 4; ++m) _Pragma("unroll") for (int k = 0; k < 2; ++k) dst[m][k] = *(const PG8_LAS bf16x8*)(lds + PG8_SA(b, h) + aoff + m * 2048 + k * 1024); } while (0)
; #define PG8_MMA(ai, bj, At, Bt) do { __builtin_amdgcn_s_setprio(1); _Pragma("unroll") for (int m = 0; m < 4; ++m) _Pragma("unroll") for (int n = 0; n < 2; ++n) _Pragma("unroll") for (int k = 0; k < 2; ++k) \
;         acc[ai][bj][m][n] = __builtin_amdgcn_mfma_f32_16x16x32_bf16(Bt[n][k], At[m][k], acc[ai][bj][m][n], 0, 0, 0); __builtin_amdgcn_s_setprio(0); } while (0)
; #define PG8_WAIT_V(n) asm volatile("s_waitcnt vmcnt(" #n ")" ::: "memory")
; #define PG8_WAIT_L(n) asm volatile("s_waitcnt lgkmcnt(" #n ")" ::: "memory")
; #define PG8_BAR __builtin_amdgcn_s_barrier()
; #define PG8_SCHED __builtin_amdgcn_sched_barrier(0)
; template <class Epi, class Sched, bool ALIGN_EPI = false, bool SP2 = false>
; __device__ __forceinline__ void gemm_phase(PG8_LAS unsigned char* lds, const Gemm g, const Sched& S, const Epi& E) {
;     ...
;             PG8_LDA(At, 1, 1); PG8_STAGE(PG8_SB(1, 0), b3, voffB); PG8_STAGE(PG8_SB(1, 1), b3 + hstepB, voffB); PG8_STAGE(PG8_SA(1, 0), a3, voffA);
;             PG8_WAIT_V(8); PG8_WAIT_L(0); PG8_BAR; PG8_MMA(1, 0, At, B0); PG8_MMA(1, 1, At, B1); PG8_BAR; PG8_SCHED;
;     ...
;         }
;         if constexpr (ALIGN_EPI) { if (wr == 0) PG8_BAR; }
	s_setprio 0
	s_add_i32 s47, s47, s8
	v_lshl_add_u64 v[158:159], v[158:159], 0, s[38:39]
	s_mov_b32 m0, s47
	ds_read_b128 v[202:205], v165 offset:49152
	ds_read_b128 v[206:209], v165 offset:50176
	ds_read_b128 v[210:213], v165 offset:51200
	ds_read_b128 v[214:217], v165 offset:52224
	ds_read_b128 v[218:221], v165 offset:53248
	ds_read_b128 v[222:225], v165 offset:54272
	ds_read_b128 v[226:229], v165 offset:55296
	ds_read_b128 v[230:233], v165 offset:56320
	global_load_lds_dwordx4 v[158:159], off
	s_add_i32 m0, s47, 0x2000
	s_add_u32 s52, s52, 0x80080
	v_lshl_add_u64 v[158:159], v[182:183], 0, s[38:39]
	s_addc_u32 s53, s53, 0
	s_add_i32 s47, s55, s8
	global_load_lds_dwordx4 v[158:159], off
	v_lshl_add_u64 v[158:159], s[52:53], 0, v[130:131]
	s_mov_b32 m0, s47
	s_nop 0
	global_load_lds_dwordx4 v[158:159], off
	v_lshl_add_u64 v[158:159], s[52:53], 0, v[134:135]
	s_add_i32 m0, s47, 0x2000
	s_nop 0
	global_load_lds_dwordx4 v[158:159], off
	v_lshl_add_u64 v[158:159], v[234:235], 0, s[38:39]
	s_mov_b32 m0, s13
	s_nop 0
	global_load_lds_dwordx4 v[158:159], off
	v_lshl_add_u64 v[158:159], v[236:237], 0, s[38:39]
	s_mov_b32 m0, s33
	s_nop 0
	global_load_lds_dwordx4 v[158:159], off
	s_nop 0
	s_waitcnt vmcnt(8)
	s_waitcnt lgkmcnt(0)
	s_setprio 1
	s_barrier
	v_mfma_f32_16x16x32_bf16 v[60:63], v[166:169], v[202:205], v[60:63]
	v_mfma_f32_16x16x32_bf16 v[56:59], v[174:177], v[202:205], v[56:59]
	v_mfma_f32_16x16x32_bf16 v[48:51], v[166:169], v[210:213], v[48:51]
	v_mfma_f32_16x16x32_bf16 v[40:43], v[174:177], v[210:213], v[40:43]
	v_mfma_f32_16x16x32_bf16 v[32:35], v[166:169], v[218:221], v[32:35]
	v_mfma_f32_16x16x32_bf16 v[24:27], v[174:177], v[218:221], v[24:27]
	v_mfma_f32_16x16x32_bf16 v[16:19], v[166:169], v[226:229], v[16:19]
	v_mfma_f32_16x16x32_bf16 v[8:11], v[174:177], v[226:229], v[8:11]
	v_mfma_f32_16x16x32_bf16 v[60:63], v[170:173], v[206:209], v[60:63]
	v_mfma_f32_16x16x32_bf16 v[56:59], v[178:181], v[206:209], v[56:59]
	v_mfma_f32_16x16x32_bf16 v[48:51], v[170:173], v[214:217], v[48:51]
	v_mfma_f32_16x16x32_bf16 v[40:43], v[178:181], v[214:217], v[40:43]
	v_mfma_f32_16x16x32_bf16 v[32:35], v[170:173], v[222:225], v[32:35]
	v_mfma_f32_16x16x32_bf16 v[24:27], v[178:181], v[222:225], v[24:27]
	v_mfma_f32_16x16x32_bf16 v[16:19], v[170:173], v[230:233], v[16:19]
	v_mfma_f32_16x16x32_bf16 v[8:11], v[178:181], v[230:233], v[8:11]
	s_setprio 0
	s_setprio 1
	v_mfma_f32_16x16x32_bf16 v[52:55], v[186:189], v[202:205], v[52:55]
	v_mfma_f32_16x16x32_bf16 v[44:47], v[194:197], v[202:205], v[44:47]
	v_mfma_f32_16x16x32_bf16 v[36:39], v[186:189], v[210:213], v[36:39]
	v_mfma_f32_16x16x32_bf16 v[28:31], v[194:197], v[210:213], v[28:31]
	v_mfma_f32_16x16x32_bf16 v[20:23], v[186:189], v[218:221], v[20:23]
	v_mfma_f32_16x16x32_bf16 v[12:15], v[194:197], v[218:221], v[12:15]
	v_mfma_f32_16x16x32_bf16 v[4:7], v[186:189], v[226:229], v[4:7]
	v_mfma_f32_16x16x32_bf16 v[0:3], v[194:197], v[226:229], v[0:3]
	v_mfma_f32_16x16x32_bf16 v[52:55], v[190:193], v[206:209], v[52:55]
	v_mfma_f32_16x16x32_bf16 v[44:47], v[198:201], v[206:209], v[44:47]
	v_mfma_f32_16x16x32_bf16 v[36:39], v[190:193], v[214:217], v[36:39]
	v_mfma_f32_16x16x32_bf16 v[28:31], v[198:201], v[214:217], v[28:31]
	v_mfma_f32_16x16x32_bf16 v[20:23], v[190:193], v[222:225], v[20:23]
	v_mfma_f32_16x16x32_bf16 v[12:15], v[198:201], v[222:225], v[12:15]
	v_mfma_f32_16x16x32_bf16 v[4:7], v[190:193], v[230:233], v[4:7]
	v_mfma_f32_16x16x32_bf16 v[0:3], v[198:201], v[230:233], v[0:3]
	s_barrier
	s_setprio 0
	s_add_i32 s46, s46, 2
	s_add_u32 s50, s50, 0x100
	s_addc_u32 s51, s51, 0
	s_add_u32 s4, s4, 0x100
	s_addc_u32 s5, s5, 0
	s_cmp_gt_u32 s46, 29
	s_cbranch_scc0 .LBB0_656
	s_and_b64 vcc, exec, s[40:41]
	s_cbranch_vccz .LBB0_659
	s_barrier

; #define PG8_STAGE(bufoff, gbase, voff) do { _Pragma("unroll") for (int _i = 0; _i < 2; ++_i) \
;         __builtin_amdgcn_global_load_lds((const unsigned*)((const char*)(gbase) + (voff)[_i]), (PG8_LAS unsigned*)(lds + (bufoff) + ldsw + _i * 8192), 16, 0, 0); } while (0)
; #define PG8_LDA(dst, b, h) do { _Pragma("unroll") for (int m = 0; m < 4; ++m) _Pragma("unroll") for (int k = 0; k < 2; ++k) dst[m][k] = *(const PG8_LAS bf16x8*)(lds + PG8_SA(b, h) + aoff + m * 2048 + k * 1024); } while (0)
; #define PG8_LDB(dst, b, h) do { _Pragma("unroll") for (int n = 0; n < 2; ++n) _Pragma("unroll") for (int k = 0; k < 2; ++k) dst[n][k] = *(const PG8_LAS bf16x8*)(lds + PG8_SB(b, h) + boff + n * 2048 + k * 1024); } while (0)
; #define PG8_MMA(ai, bj, At, Bt) do { __builtin_amdgcn_s_setprio(1); _Pragma("unroll") for (int m = 0; m < 4; ++m) _Pragma("unroll") for (int n = 0; n < 2; ++n) _Pragma("unroll") for (int k = 0; k < 2; ++k) \
;         acc[ai][bj][m][n] = __builtin_amdgcn_mfma_f32_16x16x32_bf16(Bt[n][k], At[m][k], acc[ai][bj][m][n], 0, 0, 0); __builtin_amdgcn_s_setprio(0); } while (0)
; #define PG8_WAIT_V(n) asm volatile("s_waitcnt vmcnt(" #n ")" ::: "memory")
; #define PG8_BAR __builtin_amdgcn_s_barrier()
; template <class Epi, class Sched, bool ALIGN_EPI = false, bool SP2 = false>
; __device__ __forceinline__ void gemm_phase(PG8_LAS unsigned char* lds, const Gemm g, const Sched& S, const Epi& E) {
;     ...
;         for (int t = 0; t < nt; t += 2) {
;             const bool last = (t == nt - 2);
;             const char* a1 = cA + (size_t)(t + 1) * kstA;
;             const char* a2 = last ? nA : cA + (size_t)(t + 2) * kstA; const char* b2 = last ? nB : cB + (size_t)(t + 2) * kstep;
;             const char* a3 = a2 + kstA; const char* b3 = b2 + kstep;
;             if (last && has_next) S.a_ready(nxt);
;             if constexpr (SP2) {
;             PG8_LDB(B0, 0, 0); PG8_LDB(B1, 0, 1); PG8_SCHED; PG8_LDA(At, 0, 0); PG8_STAGE(PG8_SA(1, 1), a1 + hstepA, voffA);
;             PG8_WAIT_V(8); PG8_WAIT_L(0); PG8_BAR; PG8_MMA(0, 0, At, B0); PG8_MMA(0, 1, At, B1); PG8_BAR; PG8_SCHED;
;             PG8_LDA(At, 0, 1); PG8_STAGE(PG8_SB(0, 0), b2, voffB); PG8_STAGE(PG8_SB(0, 1), b2 + hstepB, voffB); PG8_STAGE(PG8_SA(0, 0), a2, voffA);
;             PG8_WAIT_V(8); PG8_WAIT_L(0); PG8_BAR; PG8_MMA(1, 0, At, B0); PG8_MMA(1, 1, At, B1); PG8_BAR; PG8_SCHED;
.LBB0_1048:
	s_or_b32 s58, s66, 1
	s_add_i32 s66, s66, 2
	s_mov_b32 s67, s59
	v_add_u32_e32 v140, s10, v179
	v_add_u32_e32 v182, s11, v179
	s_lshl_b64 s[4:5], s[58:59], 7
	s_lshl_b64 s[6:7], s[66:67], 7
	ds_read_b128 v[128:131], v140
	ds_read_b128 v[132:135], v140 offset:1024
	ds_read_b128 v[136:139], v140 offset:2048
	ds_read_b128 v[140:143], v140 offset:3072
	ds_read_b128 v[174:177], v182
	ds_read_b128 v[190:193], v182 offset:1024
	ds_read_b128 v[194:197], v182 offset:2048
	ds_read_b128 v[198:201], v182 offset:3072
	s_add_u32 s46, s60, s6
	s_addc_u32 s47, s61, s7
	s_and_b64 s[12:13], s[76:77], exec
	s_cselect_b32 vcc_hi, s47, s49
	s_cselect_b32 vcc_lo, s46, s48
	s_add_u32 s12, s62, s6
	s_addc_u32 s13, s63, s7
	s_and_b64 s[6:7], s[76:77], exec
	s_cselect_b32 s77, s13, s55
	s_cselect_b32 s76, s12, s54
	s_add_u32 s4, s35, s4
	s_addc_u32 s5, s39, s5
	v_lshl_add_u64 v[182:183], s[4:5], 0, v[144:145]
	s_add_i32 m0, s21, 0xc000
	ds_read_b128 v[202:205], v181
	ds_read_b128 v[206:209], v181 offset:1024
	ds_read_b128 v[210:213], v181 offset:2048
	ds_read_b128 v[214:217], v181 offset:3072
	ds_read_b128 v[218:221], v181 offset:4096
	ds_read_b128 v[222:225], v181 offset:5120
	ds_read_b128 v[226:229], v181 offset:6144
	ds_read_b128 v[230:233], v181 offset:7168
	global_load_lds_dwordx4 v[182:183], off
	v_lshl_add_u64 v[182:183], s[4:5], 0, v[148:149]
	s_add_i32 m0, s21, 0xe000
	s_nop 0
	global_load_lds_dwordx4 v[182:183], off
	s_waitcnt vmcnt(8)
	s_waitcnt lgkmcnt(0)
	s_setprio 1
	s_barrier
	v_mfma_f32_16x16x32_bf16 v[124:127], v[128:131], v[202:205], v[124:127]
	v_mfma_f32_16x16x32_bf16 v[120:123], v[136:139], v[202:205], v[120:123]
	v_mfma_f32_16x16x32_bf16 v[116:119], v[128:131], v[210:213], v[116:119]
	v_mfma_f32_16x16x32_bf16 v[112:115], v[136:139], v[210:213], v[112:115]
	v_mfma_f32_16x16x32_bf16 v[108:111], v[128:131], v[218:221], v[108:111]
	v_mfma_f32_16x16x32_bf16 v[104:107], v[136:139], v[218:221], v[104:107]
	v_mfma_f32_16x16x32_bf16 v[100:103], v[128:131], v[226:229], v[100:103]
	v_mfma_f32_16x16x32_bf16 v[96:99], v[136:139], v[226:229], v[96:99]
	v_mfma_f32_16x16x32_bf16 v[124:127], v[132:135], v[206:209], v[124:127]
	v_mfma_f32_16x16x32_bf16 v[120:123], v[140:143], v[206:209], v[120:123]
	v_mfma_f32_16x16x32_bf16 v[116:119], v[132:135], v[214:217], v[116:119]
	v_mfma_f32_16x16x32_bf16 v[112:115], v[140:143], v[214:217], v[112:115]
	v_mfma_f32_16x16x32_bf16 v[108:111], v[132:135], v[222:225], v[108:111]
	v_mfma_f32_16x16x32_bf16 v[104:107], v[140:143], v[222:225], v[104:107]
	v_mfma_f32_16x16x32_bf16 v[100:103], v[132:135], v[230:233], v[100:103]
	v_mfma_f32_16x16x32_bf16 v[96:99], v[140:143], v[230:233], v[96:99]
	s_setprio 0
	s_setprio 1
	v_mfma_f32_16x16x32_bf16 v[92:95], v[174:177], v[202:205], v[92:95]
	v_mfma_f32_16x16x32_bf16 v[88:91], v[194:197], v[202:205], v[88:91]
	v_mfma_f32_16x16x32_bf16 v[84:87], v[174:177], v[210:213], v[84:87]
	v_mfma_f32_16x16x32_bf16 v[80:83], v[194:197], v[210:213], v[80:83]
	v_mfma_f32_16x16x32_bf16 v[76:79], v[174:177], v[218:221], v[76:79]
	v_mfma_f32_16x16x32_bf16 v[72:75], v[194:197], v[218:221], v[72:75]
	v_mfma_f32_16x16x32_bf16 v[68:71], v[174:177], v[226:229], v[68:71]
	v_mfma_f32_16x16x32_bf16 v[64:67], v[194:197], v[226:229], v[64:67]
	v_mfma_f32_16x16x32_bf16 v[92:95], v[190:193], v[206:209], v[92:95]
	v_mfma_f32_16x16x32_bf16 v[88:91], v[198:201], v[206:209], v[88:91]
	v_mfma_f32_16x16x32_bf16 v[84:87], v[190:193], v[214:217], v[84:87]
	v_mfma_f32_16x16x32_bf16 v[80:83], v[198:201], v[214:217], v[80:83]
	v_mfma_f32_16x16x32_bf16 v[76:79], v[190:193], v[222:225], v[76:79]
	v_mfma_f32_16x16x32_bf16 v[72:75], v[198:201], v[222:225], v[72:75]
	v_mfma_f32_16x16x32_bf16 v[68:71], v[190:193], v[230:233], v[68:71]
	v_mfma_f32_16x16x32_bf16 v[64:67], v[198:201], v[230:233], v[64:67]
	s_barrier
	s_setprio 0
	s_add_i32 s4, s10, s94
	v_lshl_add_u64 v[182:183], s[76:77], 0, v[146:147]
	s_mov_b32 m0, s4
	ds_read_b128 v[202:205], v181 offset:16384
	ds_read_b128 v[206:209], v181 offset:17408
	ds_read_b128 v[210:213], v181 offset:18432
	ds_read_b128 v[214:217], v181 offset:19456
	ds_read_b128 v[218:221], v181 offset:20480
	ds_read_b128 v[222:225], v181 offset:21504
	ds_read_b128 v[226:229], v181 offset:22528
	ds_read_b128 v[230:233], v181 offset:23552
	global_load_lds_dwordx4 v[182:183], off
	s_add_i32 m0, s4, 0x2000
	s_add_u32 s4, s76, 0x80000
	v_lshl_add_u64 v[234:235], s[76:77], 0, v[150:151]
	s_addc_u32 s5, s77, 0
	s_add_i32 s6, s11, s94
	global_load_lds_dwordx4 v[234:235], off
	v_lshl_add_u64 v[236:237], s[4:5], 0, v[146:147]
	s_mov_b32 m0, s6
	v_lshl_add_u64 v[238:239], vcc, 0, v[148:149]
	global_load_lds_dwordx4 v[236:237], off
	v_lshl_add_u64 v[236:237], s[4:5], 0, v[150:151]
	s_add_i32 m0, s6, 0x2000
	s_nop 0
	global_load_lds_dwordx4 v[236:237], off
	v_lshl_add_u64 v[236:237], vcc, 0, v[144:145]
	s_mov_b32 m0, s21
	s_nop 0
	global_load_lds_dwordx4 v[236:237], off
	s_mov_b32 m0, s95
	s_nop 0
	global_load_lds_dwordx4 v[238:239], off
	s_waitcnt vmcnt(8)
	s_waitcnt lgkmcnt(0)
	s_setprio 1
	s_barrier
; #define PG8_STAGE(bufoff, gbase, voff) do { _Pragma("unroll") for (int _i = 0; _i < 2; ++_i) \
;         __builtin_amdgcn_global_load_lds((const unsigned*)((const char*)(gbase) + (voff)[_i]), (PG8_LAS unsigned*)(lds + (bufoff) + ldsw + _i * 8192), 16, 0, 0); } while (0)
; #define PG8_LDA(dst, b, h) do { _Pragma("unroll") for (int m = 0; m < 4; ++m) _Pragma("unroll") for (int k = 0; k < 2; ++k) dst[m][k] = *(const PG8_LAS bf16x8*)(lds + PG8_SA(b, h) + aoff + m * 2048 + k * 1024); } while (0)
; #define PG8_LDB(dst, b, h) do { _Pragma("unroll") for (int n = 0; n < 2; ++n) _Pragma("unroll") for (int k = 0; k < 2; ++k) dst[n][k] = *(const PG8_LAS bf16x8*)(lds + PG8_SB(b, h) + boff + n * 2048 + k * 1024); } while (0)
; #define PG8_MMA(ai, bj, At, Bt) do { __builtin_amdgcn_s_setprio(1); _Pragma("unroll") for (int m = 0; m < 4; ++m) _Pragma("unroll") for (int n = 0; n < 2; ++n) _Pragma("unroll") for (int k = 0; k < 2; ++k) \
;         acc[ai][bj][m][n] = __builtin_amdgcn_mfma_f32_16x16x32_bf16(Bt[n][k], At[m][k], acc[ai][bj][m][n], 0, 0, 0); __builtin_amdgcn_s_setprio(0); } while (0)
; #define PG8_WAIT_V(n) asm volatile("s_waitcnt vmcnt(" #n ")" ::: "memory")
; #define PG8_WAIT_L(n) asm volatile("s_waitcnt lgkmcnt(" #n ")" ::: "memory")
; #define PG8_BAR __builtin_amdgcn_s_barrier()
; #define PG8_SCHED __builtin_amdgcn_sched_barrier(0)
; template <class Epi, class Sched, bool ALIGN_EPI = false, bool SP2 = false>
; __device__ __forceinline__ void gemm_phase(PG8_LAS unsigned char* lds, const Gemm g, const Sched& S, const Epi& E) {
;     ...
;             PG8_WAIT_V(8); PG8_WAIT_L(0); PG8_BAR; PG8_MMA(1, 0, At, B0); PG8_MMA(1, 1, At, B1); PG8_BAR; PG8_SCHED;
;             PG8_LDB(B0, 1, 0); PG8_LDB(B1, 1, 1); PG8_SCHED; PG8_LDA(At, 1, 0); PG8_STAGE(PG8_SA(0, 1), a2 + hstepA, voffA);
;             PG8_WAIT_V(8); PG8_WAIT_L(0); PG8_BAR; PG8_MMA(0, 0, At, B0); PG8_MMA(0, 1, At, B1); PG8_BAR; PG8_SCHED;
	v_mfma_f32_16x16x32_bf16 v[60:63], v[128:131], v[202:205], v[60:63]
	v_mfma_f32_16x16x32_bf16 v[56:59], v[136:139], v[202:205], v[56:59]
	v_mfma_f32_16x16x32_bf16 v[52:55], v[128:131], v[210:213], v[52:55]
	v_mfma_f32_16x16x32_bf16 v[48:51], v[136:139], v[210:213], v[48:51]
	v_mfma_f32_16x16x32_bf16 v[44:47], v[128:131], v[218:221], v[44:47]
	v_mfma_f32_16x16x32_bf16 v[40:43], v[136:139], v[218:221], v[40:43]
	v_mfma_f32_16x16x32_bf16 v[36:39], v[128:131], v[226:229], v[36:39]
	v_mfma_f32_16x16x32_bf16 v[32:35], v[136:139], v[226:229], v[32:35]
	v_mfma_f32_16x16x32_bf16 v[60:63], v[132:135], v[206:209], v[60:63]
	v_mfma_f32_16x16x32_bf16 v[56:59], v[140:143], v[206:209], v[56:59]
	v_mfma_f32_16x16x32_bf16 v[52:55], v[132:135], v[214:217], v[52:55]
	v_mfma_f32_16x16x32_bf16 v[48:51], v[140:143], v[214:217], v[48:51]
	v_mfma_f32_16x16x32_bf16 v[44:47], v[132:135], v[222:225], v[44:47]
	v_mfma_f32_16x16x32_bf16 v[40:43], v[140:143], v[222:225], v[40:43]
	v_mfma_f32_16x16x32_bf16 v[36:39], v[132:135], v[230:233], v[36:39]
	v_mfma_f32_16x16x32_bf16 v[32:35], v[140:143], v[230:233], v[32:35]
	s_setprio 0
	s_setprio 1
	v_mfma_f32_16x16x32_bf16 v[28:31], v[174:177], v[202:205], v[28:31]
	v_mfma_f32_16x16x32_bf16 v[24:27], v[194:197], v[202:205], v[24:27]
	v_mfma_f32_16x16x32_bf16 v[20:23], v[174:177], v[210:213], v[20:23]
	v_mfma_f32_16x16x32_bf16 v[16:19], v[194:197], v[210:213], v[16:19]
	v_mfma_f32_16x16x32_bf16 v[12:15], v[174:177], v[218:221], v[12:15]
	v_mfma_f32_16x16x32_bf16 v[8:11], v[194:197], v[218:221], v[8:11]
	v_mfma_f32_16x16x32_bf16 v[4:7], v[174:177], v[226:229], v[4:7]
	v_mfma_f32_16x16x32_bf16 v[0:3], v[194:197], v[226:229], v[0:3]
	v_mfma_f32_16x16x32_bf16 v[28:31], v[190:193], v[206:209], v[28:31]
	v_mfma_f32_16x16x32_bf16 v[24:27], v[198:201], v[206:209], v[24:27]
	v_mfma_f32_16x16x32_bf16 v[20:23], v[190:193], v[214:217], v[20:23]
	v_mfma_f32_16x16x32_bf16 v[16:19], v[198:201], v[214:217], v[16:19]
	v_mfma_f32_16x16x32_bf16 v[12:15], v[190:193], v[222:225], v[12:15]
	v_mfma_f32_16x16x32_bf16 v[8:11], v[198:201], v[222:225], v[8:11]
	v_mfma_f32_16x16x32_bf16 v[4:7], v[190:193], v[230:233], v[4:7]
	v_mfma_f32_16x16x32_bf16 v[0:3], v[198:201], v[230:233], v[0:3]
	s_barrier
	s_setprio 0
	s_add_i32 s6, 0, 0x18000
	s_add_i32 s7, 0, 0x1c000
	v_add_u32_e32 v140, s6, v179
	v_add_u32_e32 v198, s7, v179
	ds_read_b128 v[128:131], v140
	ds_read_b128 v[132:135], v140 offset:1024
	ds_read_b128 v[136:139], v140 offset:2048
	ds_read_b128 v[140:143], v140 offset:3072
	ds_read_b128 v[174:177], v198
	ds_read_b128 v[190:193], v198 offset:1024
	ds_read_b128 v[194:197], v198 offset:2048
	ds_read_b128 v[198:201], v198 offset:3072
	s_add_u32 s4, vcc_lo, 0x80000
	s_addc_u32 s5, vcc_hi, 0
	s_mov_b32 m0, s96
	v_lshl_add_u64 v[240:241], s[4:5], 0, v[144:145]
	ds_read_b128 v[202:205], v181 offset:32768
	ds_read_b128 v[206:209], v181 offset:33792
	ds_read_b128 v[210:213], v181 offset:34816
	ds_read_b128 v[214:217], v181 offset:35840
	ds_read_b128 v[218:221], v181 offset:36864
	ds_read_b128 v[222:225], v181 offset:37888
	ds_read_b128 v[226:229], v181 offset:38912
	ds_read_b128 v[230:233], v181 offset:39936
	global_load_lds_dwordx4 v[240:241], off
	v_lshl_add_u64 v[240:241], s[4:5], 0, v[148:149]
	s_mov_b32 m0, s97
	s_nop 0
	global_load_lds_dwordx4 v[240:241], off
	s_waitcnt vmcnt(8)
	s_waitcnt lgkmcnt(0)
	s_setprio 1
	s_barrier
	v_mfma_f32_16x16x32_bf16 v[124:127], v[128:131], v[202:205], v[124:127]
	v_mfma_f32_16x16x32_bf16 v[120:123], v[136:139], v[202:205], v[120:123]
	v_mfma_f32_16x16x32_bf16 v[116:119], v[128:131], v[210:213], v[116:119]
	v_mfma_f32_16x16x32_bf16 v[112:115], v[136:139], v[210:213], v[112:115]
	v_mfma_f32_16x16x32_bf16 v[108:111], v[128:131], v[218:221], v[108:111]
	v_mfma_f32_16x16x32_bf16 v[104:107], v[136:139], v[218:221], v[104:107]
	v_mfma_f32_16x16x32_bf16 v[100:103], v[128:131], v[226:229], v[100:103]
	v_mfma_f32_16x16x32_bf16 v[96:99], v[136:139], v[226:229], v[96:99]
	v_mfma_f32_16x16x32_bf16 v[124:127], v[132:135], v[206:209], v[124:127]
	v_mfma_f32_16x16x32_bf16 v[120:123], v[140:143], v[206:209], v[120:123]
	v_mfma_f32_16x16x32_bf16 v[116:119], v[132:135], v[214:217], v[116:119]
	v_mfma_f32_16x16x32_bf16 v[112:115], v[140:143], v[214:217], v[112:115]
	v_mfma_f32_16x16x32_bf16 v[108:111], v[132:135], v[222:225], v[108:111]
	v_mfma_f32_16x16x32_bf16 v[104:107], v[140:143], v[222:225], v[104:107]
	v_mfma_f32_16x16x32_bf16 v[100:103], v[132:135], v[230:233], v[100:103]
	v_mfma_f32_16x16x32_bf16 v[96:99], v[140:143], v[230:233], v[96:99]
	s_setprio 0
	s_setprio 1
	v_mfma_f32_16x16x32_bf16 v[92:95], v[174:177], v[202:205], v[92:95]
	v_mfma_f32_16x16x32_bf16 v[88:91], v[194:197], v[202:205], v[88:91]
	v_mfma_f32_16x16x32_bf16 v[84:87], v[174:177], v[210:213], v[84:87]
	v_mfma_f32_16x16x32_bf16 v[80:83], v[194:197], v[210:213], v[80:83]
	v_mfma_f32_16x16x32_bf16 v[76:79], v[174:177], v[218:221], v[76:79]
	v_mfma_f32_16x16x32_bf16 v[72:75], v[194:197], v[218:221], v[72:75]
	v_mfma_f32_16x16x32_bf16 v[68:71], v[174:177], v[226:229], v[68:71]
	v_mfma_f32_16x16x32_bf16 v[64:67], v[194:197], v[226:229], v[64:67]
	v_mfma_f32_16x16x32_bf16 v[92:95], v[190:193], v[206:209], v[92:95]
	v_mfma_f32_16x16x32_bf16 v[88:91], v[198:201], v[206:209], v[88:91]
	v_mfma_f32_16x16x32_bf16 v[84:87], v[190:193], v[214:217], v[84:87]
	v_mfma_f32_16x16x32_bf16 v[80:83], v[198:201], v[214:217], v[80:83]
	v_mfma_f32_16x16x32_bf16 v[76:79], v[190:193], v[222:225], v[76:79]
	v_mfma_f32_16x16x32_bf16 v[72:75], v[198:201], v[222:225], v[72:75]
	v_mfma_f32_16x16x32_bf16 v[68:71], v[190:193], v[230:233], v[68:71]
	v_mfma_f32_16x16x32_bf16 v[64:67], v[198:201], v[230:233], v[64:67]
	s_barrier
; #define PG8_STAGE(bufoff, gbase, voff) do { _Pragma("unroll") for (int _i = 0; _i < 2; ++_i) \
;         __builtin_amdgcn_global_load_lds((const unsigned*)((const char*)(gbase) + (voff)[_i]), (PG8_LAS unsigned*)(lds + (bufoff) + ldsw + _i * 8192), 16, 0, 0); } while (0)
; #define PG8_LDA(dst, b, h) do { _Pragma("unroll") for (int m = 0; m < 4; ++m) _Pragma("unroll") for (int k = 0; k < 2; ++k) dst[m][k] = *(const PG8_LAS bf16x8*)(lds + PG8_SA(b, h) + aoff + m * 2048 + k * 1024); } while (0)
; #define PG8_MMA(ai, bj, At, Bt) do { __builtin_amdgcn_s_setprio(1); _Pragma("unroll") for (int m = 0; m < 4; ++m) _Pragma("unroll") for (int n = 0; n < 2; ++n) _Pragma("unroll") for (int k = 0; k < 2; ++k) \
;         acc[ai][bj][m][n] = __builtin_amdgcn_mfma_f32_16x16x32_bf16(Bt[n][k], At[m][k], acc[ai][bj][m][n], 0, 0, 0); __builtin_amdgcn_s_setprio(0); } while (0)
; #define PG8_WAIT_V(n) asm volatile("s_waitcnt vmcnt(" #n ")" ::: "memory")
; #define PG8_WAIT_L(n) asm volatile("s_waitcnt lgkmcnt(" #n ")" ::: "memory")
; #define PG8_BAR __builtin_amdgcn_s_barrier()
; #define PG8_SCHED __builtin_amdgcn_sched_barrier(0)
; template <class Epi, class Sched, bool ALIGN_EPI = false, bool SP2 = false>
; __device__ __forceinline__ void gemm_phase(PG8_LAS unsigned char* lds, const Gemm g, const Sched& S, const Epi& E) {
;     ...
;         for (int t = 0; t < nt; t += 2) {
;             const bool last = (t == nt - 2);
;     ...
;             PG8_LDA(At, 1, 1); PG8_STAGE(PG8_SB(1, 0), b3, voffB); PG8_STAGE(PG8_SB(1, 1), b3 + hstepB, voffB); PG8_STAGE(PG8_SA(1, 0), a3, voffA);
;             PG8_WAIT_V(8); PG8_WAIT_L(0); PG8_BAR; PG8_MMA(1, 0, At, B0); PG8_MMA(1, 1, At, B1); PG8_BAR; PG8_SCHED;
	s_setprio 0
	s_add_i32 s4, s6, s94
	v_lshl_add_u64 v[182:183], v[182:183], 0, s[70:71]
	s_mov_b32 m0, s4
	ds_read_b128 v[202:205], v181 offset:49152
	ds_read_b128 v[206:209], v181 offset:50176
	ds_read_b128 v[210:213], v181 offset:51200
	ds_read_b128 v[214:217], v181 offset:52224
	ds_read_b128 v[218:221], v181 offset:53248
	ds_read_b128 v[222:225], v181 offset:54272
	ds_read_b128 v[226:229], v181 offset:55296
	ds_read_b128 v[230:233], v181 offset:56320
	global_load_lds_dwordx4 v[182:183], off
	s_add_i32 m0, s4, 0x2000
	s_add_u32 s4, s76, 0x80080
	v_lshl_add_u64 v[182:183], v[234:235], 0, s[70:71]
	s_addc_u32 s5, s77, 0
	s_add_i32 s6, s7, s94
	global_load_lds_dwordx4 v[182:183], off
	v_lshl_add_u64 v[182:183], s[4:5], 0, v[146:147]
	s_mov_b32 m0, s6
	s_nop 0
	global_load_lds_dwordx4 v[182:183], off
	v_lshl_add_u64 v[182:183], s[4:5], 0, v[150:151]
	s_add_i32 m0, s6, 0x2000
	s_nop 0
	global_load_lds_dwordx4 v[182:183], off
	v_lshl_add_u64 v[182:183], v[236:237], 0, s[70:71]
	s_mov_b32 m0, s56
	s_nop 0
	global_load_lds_dwordx4 v[182:183], off
	v_lshl_add_u64 v[182:183], v[238:239], 0, s[70:71]
	s_mov_b32 m0, s57
	s_nop 0
	global_load_lds_dwordx4 v[182:183], off
	s_nop 0
	s_waitcnt vmcnt(8)
	s_waitcnt lgkmcnt(0)
	s_setprio 1
	s_barrier
	v_mfma_f32_16x16x32_bf16 v[60:63], v[128:131], v[202:205], v[60:63]
	v_mfma_f32_16x16x32_bf16 v[56:59], v[136:139], v[202:205], v[56:59]
	v_mfma_f32_16x16x32_bf16 v[52:55], v[128:131], v[210:213], v[52:55]
	v_mfma_f32_16x16x32_bf16 v[48:51], v[136:139], v[210:213], v[48:51]
	v_mfma_f32_16x16x32_bf16 v[44:47], v[128:131], v[218:221], v[44:47]
	v_mfma_f32_16x16x32_bf16 v[40:43], v[136:139], v[218:221], v[40:43]
	v_mfma_f32_16x16x32_bf16 v[36:39], v[128:131], v[226:229], v[36:39]
	v_mfma_f32_16x16x32_bf16 v[32:35], v[136:139], v[226:229], v[32:35]
	v_mfma_f32_16x16x32_bf16 v[60:63], v[132:135], v[206:209], v[60:63]
	v_mfma_f32_16x16x32_bf16 v[56:59], v[140:143], v[206:209], v[56:59]
	v_mfma_f32_16x16x32_bf16 v[52:55], v[132:135], v[214:217], v[52:55]
	v_mfma_f32_16x16x32_bf16 v[48:51], v[140:143], v[214:217], v[48:51]
	v_mfma_f32_16x16x32_bf16 v[44:47], v[132:135], v[222:225], v[44:47]
	v_mfma_f32_16x16x32_bf16 v[40:43], v[140:143], v[222:225], v[40:43]
	v_mfma_f32_16x16x32_bf16 v[36:39], v[132:135], v[230:233], v[36:39]
	v_mfma_f32_16x16x32_bf16 v[32:35], v[140:143], v[230:233], v[32:35]
	s_setprio 0
	s_setprio 1
	v_mfma_f32_16x16x32_bf16 v[28:31], v[174:177], v[202:205], v[28:31]
	v_mfma_f32_16x16x32_bf16 v[24:27], v[194:197], v[202:205], v[24:27]
	v_mfma_f32_16x16x32_bf16 v[20:23], v[174:177], v[210:213], v[20:23]
	v_mfma_f32_16x16x32_bf16 v[16:19], v[194:197], v[210:213], v[16:19]
	v_mfma_f32_16x16x32_bf16 v[12:15], v[174:177], v[218:221], v[12:15]
	v_mfma_f32_16x16x32_bf16 v[8:11], v[194:197], v[218:221], v[8:11]
	v_mfma_f32_16x16x32_bf16 v[4:7], v[174:177], v[226:229], v[4:7]
	v_mfma_f32_16x16x32_bf16 v[0:3], v[194:197], v[226:229], v[0:3]
	v_mfma_f32_16x16x32_bf16 v[28:31], v[190:193], v[206:209], v[28:31]
	v_mfma_f32_16x16x32_bf16 v[24:27], v[198:201], v[206:209], v[24:27]
	v_mfma_f32_16x16x32_bf16 v[20:23], v[190:193], v[214:217], v[20:23]
	v_mfma_f32_16x16x32_bf16 v[16:19], v[198:201], v[214:217], v[16:19]
	v_mfma_f32_16x16x32_bf16 v[12:15], v[190:193], v[222:225], v[12:15]
	v_mfma_f32_16x16x32_bf16 v[8:11], v[198:201], v[222:225], v[8:11]
	v_mfma_f32_16x16x32_bf16 v[4:7], v[190:193], v[230:233], v[4:7]
	v_mfma_f32_16x16x32_bf16 v[0:3], v[198:201], v[230:233], v[0:3]
	s_barrier
	s_setprio 0
	s_cmp_ge_i32 s66, s44
	s_cbranch_scc1 .LBB0_1066

; #define PG8_STAGE(bufoff, gbase, voff) do { _Pragma("unroll") for (int _i = 0; _i < 2; ++_i) \
;         __builtin_amdgcn_global_load_lds((const unsigned*)((const char*)(gbase) + (voff)[_i]), (PG8_LAS unsigned*)(lds + (bufoff) + ldsw + _i * 8192), 16, 0, 0); } while (0)
; #define PG8_LDA(dst, b, h) do { _Pragma("unroll") for (int m = 0; m < 4; ++m) _Pragma("unroll") for (int k = 0; k < 2; ++k) dst[m][k] = *(const PG8_LAS bf16x8*)(lds + PG8_SA(b, h) + aoff + m * 2048 + k * 1024); } while (0)
; #define PG8_LDB(dst, b, h) do { _Pragma("unroll") for (int n = 0; n < 2; ++n) _Pragma("unroll") for (int k = 0; k < 2; ++k) dst[n][k] = *(const PG8_LAS bf16x8*)(lds + PG8_SB(b, h) + boff + n * 2048 + k * 1024); } while (0)
; #define PG8_MMA(ai, bj, At, Bt) do { __builtin_amdgcn_s_setprio(1); _Pragma("unroll") for (int m = 0; m < 4; ++m) _Pragma("unroll") for (int n = 0; n < 2; ++n) _Pragma("unroll") for (int k = 0; k < 2; ++k) \
;         acc[ai][bj][m][n] = __builtin_amdgcn_mfma_f32_16x16x32_bf16(Bt[n][k], At[m][k], acc[ai][bj][m][n], 0, 0, 0); __builtin_amdgcn_s_setprio(0); } while (0)
; #define PG8_WAIT_V(n) asm volatile("s_waitcnt vmcnt(" #n ")" ::: "memory")
; #define PG8_WAIT_L(n) asm volatile("s_waitcnt lgkmcnt(" #n ")" ::: "memory")
; #define PG8_BAR __builtin_amdgcn_s_barrier()
; #define PG8_SCHED __builtin_amdgcn_sched_barrier(0)
; template <class Epi, class Sched, bool ALIGN_EPI = false, bool SP2 = false>
; __device__ __forceinline__ void gemm_phase(PG8_LAS unsigned char* lds, const Gemm g, const Sched& S, const Epi& E) {
;     ...
;             PG8_LDB(B0, 0, 0); PG8_LDB(B1, 0, 1); PG8_SCHED; PG8_LDA(At, 0, 0); PG8_STAGE(PG8_SA(1, 1), a1 + hstepA, voffA);
;             PG8_WAIT_V(8); PG8_WAIT_L(0); PG8_BAR; PG8_MMA(0, 0, At, B0); PG8_MMA(0, 1, At, B1); PG8_BAR; PG8_SCHED;
;             PG8_LDA(At, 0, 1); PG8_STAGE(PG8_SB(0, 0), b2, voffB); PG8_STAGE(PG8_SB(0, 1), b2 + hstepB, voffB); PG8_STAGE(PG8_SA(0, 0), a2, voffA);
;             PG8_WAIT_V(8); PG8_WAIT_L(0); PG8_BAR; PG8_MMA(1, 0, At, B0); PG8_MMA(1, 1, At, B1); PG8_BAR; PG8_SCHED;
.LBB0_1307:
	ds_read_b128 v[156:159], v152
	ds_read_b128 v[160:163], v152 offset:1024
	ds_read_b128 v[164:167], v152 offset:2048
	ds_read_b128 v[168:171], v152 offset:3072
	ds_read_b128 v[172:175], v153
	ds_read_b128 v[176:179], v153 offset:1024
	ds_read_b128 v[180:183], v153 offset:2048
	ds_read_b128 v[190:193], v153 offset:3072
	s_add_u32 s52, s50, 0xfff80080
	s_addc_u32 s53, s51, -1
	s_cmp_eq_u32 s63, 28
	s_cselect_b32 s59, s4, s53
	s_cselect_b32 s58, s5, s52
	s_cselect_b32 s53, s12, s41
	s_cselect_b32 s52, s13, s39
	v_lshl_add_u64 v[226:227], s[50:51], 0, v[142:143]
	s_add_i32 m0, s7, 0xc000
	ds_read_b128 v[194:197], v154
	ds_read_b128 v[198:201], v154 offset:1024
	ds_read_b128 v[202:205], v154 offset:2048
	ds_read_b128 v[206:209], v154 offset:3072
	ds_read_b128 v[210:213], v154 offset:4096
	ds_read_b128 v[214:217], v154 offset:5120
	ds_read_b128 v[218:221], v154 offset:6144
	ds_read_b128 v[222:225], v154 offset:7168
	global_load_lds_dwordx4 v[226:227], off
	v_lshl_add_u64 v[226:227], s[50:51], 0, v[144:145]
	s_add_i32 m0, s7, 0xe000
	s_nop 0
	global_load_lds_dwordx4 v[226:227], off
	s_waitcnt vmcnt(8)
	s_waitcnt lgkmcnt(0)
	s_setprio 1
	s_barrier
	v_mfma_f32_16x16x32_bf16 v[124:127], v[156:159], v[194:197], v[124:127]
	v_mfma_f32_16x16x32_bf16 v[120:123], v[164:167], v[194:197], v[120:123]
	v_mfma_f32_16x16x32_bf16 v[108:111], v[156:159], v[202:205], v[108:111]
	v_mfma_f32_16x16x32_bf16 v[104:107], v[164:167], v[202:205], v[104:107]
	v_mfma_f32_16x16x32_bf16 v[92:95], v[156:159], v[210:213], v[92:95]
	v_mfma_f32_16x16x32_bf16 v[88:91], v[164:167], v[210:213], v[88:91]
	v_mfma_f32_16x16x32_bf16 v[76:79], v[156:159], v[218:221], v[76:79]
	v_mfma_f32_16x16x32_bf16 v[72:75], v[164:167], v[218:221], v[72:75]
	v_mfma_f32_16x16x32_bf16 v[124:127], v[160:163], v[198:201], v[124:127]
	v_mfma_f32_16x16x32_bf16 v[120:123], v[168:171], v[198:201], v[120:123]
	v_mfma_f32_16x16x32_bf16 v[108:111], v[160:163], v[206:209], v[108:111]
	v_mfma_f32_16x16x32_bf16 v[104:107], v[168:171], v[206:209], v[104:107]
	v_mfma_f32_16x16x32_bf16 v[92:95], v[160:163], v[214:217], v[92:95]
	v_mfma_f32_16x16x32_bf16 v[88:91], v[168:171], v[214:217], v[88:91]
	v_mfma_f32_16x16x32_bf16 v[76:79], v[160:163], v[222:225], v[76:79]
	v_mfma_f32_16x16x32_bf16 v[72:75], v[168:171], v[222:225], v[72:75]
	s_setprio 0
	s_setprio 1
	v_mfma_f32_16x16x32_bf16 v[116:119], v[172:175], v[194:197], v[116:119]
	v_mfma_f32_16x16x32_bf16 v[112:115], v[180:183], v[194:197], v[112:115]
	v_mfma_f32_16x16x32_bf16 v[100:103], v[172:175], v[202:205], v[100:103]
	v_mfma_f32_16x16x32_bf16 v[96:99], v[180:183], v[202:205], v[96:99]
	v_mfma_f32_16x16x32_bf16 v[84:87], v[172:175], v[210:213], v[84:87]
	v_mfma_f32_16x16x32_bf16 v[80:83], v[180:183], v[210:213], v[80:83]
	v_mfma_f32_16x16x32_bf16 v[68:71], v[172:175], v[218:221], v[68:71]
	v_mfma_f32_16x16x32_bf16 v[64:67], v[180:183], v[218:221], v[64:67]
	v_mfma_f32_16x16x32_bf16 v[116:119], v[176:179], v[198:201], v[116:119]
	v_mfma_f32_16x16x32_bf16 v[112:115], v[190:193], v[198:201], v[112:115]
	v_mfma_f32_16x16x32_bf16 v[100:103], v[176:179], v[206:209], v[100:103]
	v_mfma_f32_16x16x32_bf16 v[96:99], v[190:193], v[206:209], v[96:99]
	v_mfma_f32_16x16x32_bf16 v[84:87], v[176:179], v[214:217], v[84:87]
	v_mfma_f32_16x16x32_bf16 v[80:83], v[190:193], v[214:217], v[80:83]
	v_mfma_f32_16x16x32_bf16 v[68:71], v[176:179], v[222:225], v[68:71]
	v_mfma_f32_16x16x32_bf16 v[64:67], v[190:193], v[222:225], v[64:67]
	s_barrier
	s_setprio 0
	s_add_i32 s64, s57, s6
	v_lshl_add_u64 v[226:227], s[52:53], 0, v[130:131]
	s_mov_b32 m0, s64
	ds_read_b128 v[194:197], v154 offset:16384
	ds_read_b128 v[198:201], v154 offset:17408
	ds_read_b128 v[202:205], v154 offset:18432
	ds_read_b128 v[206:209], v154 offset:19456
	ds_read_b128 v[210:213], v154 offset:20480
	ds_read_b128 v[214:217], v154 offset:21504
	ds_read_b128 v[218:221], v154 offset:22528
	ds_read_b128 v[222:225], v154 offset:23552
	global_load_lds_dwordx4 v[226:227], off
	s_add_i32 m0, s64, 0x2000
	s_add_u32 s64, s52, 0x80000
	v_lshl_add_u64 v[228:229], s[52:53], 0, v[134:135]
	s_addc_u32 s65, s53, 0
	s_add_i32 s66, s61, s6
	global_load_lds_dwordx4 v[228:229], off
	v_lshl_add_u64 v[230:231], s[64:65], 0, v[130:131]
	s_mov_b32 m0, s66
	v_lshl_add_u64 v[232:233], s[58:59], 0, v[132:133]
	global_load_lds_dwordx4 v[230:231], off
	v_lshl_add_u64 v[230:231], s[64:65], 0, v[134:135]
	s_add_i32 m0, s66, 0x2000
	s_nop 0
	global_load_lds_dwordx4 v[230:231], off
	v_lshl_add_u64 v[230:231], s[58:59], 0, v[128:129]
	s_mov_b32 m0, s7
	s_nop 0
	global_load_lds_dwordx4 v[230:231], off
	s_mov_b32 m0, s8
	s_nop 0
	global_load_lds_dwordx4 v[232:233], off
	s_waitcnt vmcnt(8)
	s_waitcnt lgkmcnt(0)
	s_setprio 1
	s_barrier
; #define PG8_STAGE(bufoff, gbase, voff) do { _Pragma("unroll") for (int _i = 0; _i < 2; ++_i) \
;         __builtin_amdgcn_global_load_lds((const unsigned*)((const char*)(gbase) + (voff)[_i]), (PG8_LAS unsigned*)(lds + (bufoff) + ldsw + _i * 8192), 16, 0, 0); } while (0)
; #define PG8_LDA(dst, b, h) do { _Pragma("unroll") for (int m = 0; m < 4; ++m) _Pragma("unroll") for (int k = 0; k < 2; ++k) dst[m][k] = *(const PG8_LAS bf16x8*)(lds + PG8_SA(b, h) + aoff + m * 2048 + k * 1024); } while (0)
; #define PG8_LDB(dst, b, h) do { _Pragma("unroll") for (int n = 0; n < 2; ++n) _Pragma("unroll") for (int k = 0; k < 2; ++k) dst[n][k] = *(const PG8_LAS bf16x8*)(lds + PG8_SB(b, h) + boff + n * 2048 + k * 1024); } while (0)
; #define PG8_MMA(ai, bj, At, Bt) do { __builtin_amdgcn_s_setprio(1); _Pragma("unroll") for (int m = 0; m < 4; ++m) _Pragma("unroll") for (int n = 0; n < 2; ++n) _Pragma("unroll") for (int k = 0; k < 2; ++k) \
;         acc[ai][bj][m][n] = __builtin_amdgcn_mfma_f32_16x16x32_bf16(Bt[n][k], At[m][k], acc[ai][bj][m][n], 0, 0, 0); __builtin_amdgcn_s_setprio(0); } while (0)
; #define PG8_WAIT_V(n) asm volatile("s_waitcnt vmcnt(" #n ")" ::: "memory")
; template <class Epi, class Sched, bool ALIGN_EPI = false, bool SP2 = false>
; __device__ __forceinline__ void gemm_phase(PG8_LAS unsigned char* lds, const Gemm g, const Sched& S, const Epi& E) {
;     ...
;             PG8_LDB(B0, 0, 0); PG8_LDB(B1, 0, 1); PG8_SCHED; PG8_LDA(At, 0, 0); PG8_STAGE(PG8_SA(1, 1), a1 + hstepA, voffA);
;             PG8_WAIT_V(8); PG8_WAIT_L(0); PG8_BAR; PG8_MMA(0, 0, At, B0); PG8_MMA(0, 1, At, B1); PG8_BAR; PG8_SCHED;
;             PG8_LDA(At, 0, 1); PG8_STAGE(PG8_SB(0, 0), b2, voffB); PG8_STAGE(PG8_SB(0, 1), b2 + hstepB, voffB); PG8_STAGE(PG8_SA(0, 0), a2, voffA);
;             PG8_WAIT_V(8); PG8_WAIT_L(0); PG8_BAR; PG8_MMA(1, 0, At, B0); PG8_MMA(1, 1, At, B1); PG8_BAR; PG8_SCHED;
;             PG8_LDB(B0, 1, 0); PG8_LDB(B1, 1, 1); PG8_SCHED; PG8_LDA(At, 1, 0); PG8_STAGE(PG8_SA(0, 1), a2 + hstepA, voffA);
;             PG8_WAIT_V(8); PG8_WAIT_L(0); PG8_BAR; PG8_MMA(0, 0, At, B0); PG8_MMA(0, 1, At, B1); PG8_BAR; PG8_SCHED;
;             PG8_LDA(At, 1, 1); PG8_STAGE(PG8_SB(1, 0), b3, voffB); PG8_STAGE(PG8_SB(1, 1), b3 + hstepB, voffB); PG8_STAGE(PG8_SA(1, 0), a3, voffA);
;             PG8_WAIT_V(8); PG8_WAIT_L(0); PG8_BAR; PG8_MMA(1, 0, At, B0); PG8_MMA(1, 1, At, B1); PG8_BAR; PG8_SCHED;
	v_mfma_f32_16x16x32_bf16 v[60:63], v[156:159], v[194:197], v[60:63]
	v_mfma_f32_16x16x32_bf16 v[56:59], v[164:167], v[194:197], v[56:59]
	v_mfma_f32_16x16x32_bf16 v[44:47], v[156:159], v[202:205], v[44:47]
	v_mfma_f32_16x16x32_bf16 v[40:43], v[164:167], v[202:205], v[40:43]
	v_mfma_f32_16x16x32_bf16 v[28:31], v[156:159], v[210:213], v[28:31]
	v_mfma_f32_16x16x32_bf16 v[24:27], v[164:167], v[210:213], v[24:27]
	v_mfma_f32_16x16x32_bf16 v[12:15], v[156:159], v[218:221], v[12:15]
	v_mfma_f32_16x16x32_bf16 v[8:11], v[164:167], v[218:221], v[8:11]
	v_mfma_f32_16x16x32_bf16 v[60:63], v[160:163], v[198:201], v[60:63]
	v_mfma_f32_16x16x32_bf16 v[56:59], v[168:171], v[198:201], v[56:59]
	v_mfma_f32_16x16x32_bf16 v[44:47], v[160:163], v[206:209], v[44:47]
	v_mfma_f32_16x16x32_bf16 v[40:43], v[168:171], v[206:209], v[40:43]
	v_mfma_f32_16x16x32_bf16 v[28:31], v[160:163], v[214:217], v[28:31]
	v_mfma_f32_16x16x32_bf16 v[24:27], v[168:171], v[214:217], v[24:27]
	v_mfma_f32_16x16x32_bf16 v[12:15], v[160:163], v[222:225], v[12:15]
	v_mfma_f32_16x16x32_bf16 v[8:11], v[168:171], v[222:225], v[8:11]
	s_setprio 0
	s_setprio 1
	v_mfma_f32_16x16x32_bf16 v[52:55], v[172:175], v[194:197], v[52:55]
	v_mfma_f32_16x16x32_bf16 v[48:51], v[180:183], v[194:197], v[48:51]
	v_mfma_f32_16x16x32_bf16 v[36:39], v[172:175], v[202:205], v[36:39]
	v_mfma_f32_16x16x32_bf16 v[32:35], v[180:183], v[202:205], v[32:35]
	v_mfma_f32_16x16x32_bf16 v[20:23], v[172:175], v[210:213], v[20:23]
	v_mfma_f32_16x16x32_bf16 v[16:19], v[180:183], v[210:213], v[16:19]
	v_mfma_f32_16x16x32_bf16 v[4:7], v[172:175], v[218:221], v[4:7]
	v_mfma_f32_16x16x32_bf16 v[0:3], v[180:183], v[218:221], v[0:3]
	v_mfma_f32_16x16x32_bf16 v[52:55], v[176:179], v[198:201], v[52:55]
	v_mfma_f32_16x16x32_bf16 v[48:51], v[190:193], v[198:201], v[48:51]
	v_mfma_f32_16x16x32_bf16 v[36:39], v[176:179], v[206:209], v[36:39]
	v_mfma_f32_16x16x32_bf16 v[32:35], v[190:193], v[206:209], v[32:35]
	v_mfma_f32_16x16x32_bf16 v[20:23], v[176:179], v[214:217], v[20:23]
	v_mfma_f32_16x16x32_bf16 v[16:19], v[190:193], v[214:217], v[16:19]
	v_mfma_f32_16x16x32_bf16 v[4:7], v[176:179], v[222:225], v[4:7]
	v_mfma_f32_16x16x32_bf16 v[0:3], v[190:193], v[222:225], v[0:3]
	s_barrier
	s_setprio 0
	s_add_i32 s64, 0, 0x18000
	v_add_u32_e32 v155, s64, v150
	s_add_i32 s65, 0, 0x1c000
	ds_read_b128 v[156:159], v155
	ds_read_b128 v[160:163], v155 offset:1024
	ds_read_b128 v[164:167], v155 offset:2048
	ds_read_b128 v[168:171], v155 offset:3072
	v_add_u32_e32 v155, s65, v150
	ds_read_b128 v[172:175], v155
	ds_read_b128 v[176:179], v155 offset:1024
	ds_read_b128 v[180:183], v155 offset:2048
	ds_read_b128 v[190:193], v155 offset:3072
	s_add_u32 s58, s58, 0x80000
	s_addc_u32 s59, s59, 0
	s_mov_b32 m0, s9
	v_lshl_add_u64 v[234:235], s[58:59], 0, v[128:129]
	ds_read_b128 v[194:197], v154 offset:32768
	ds_read_b128 v[198:201], v154 offset:33792
	ds_read_b128 v[202:205], v154 offset:34816
	ds_read_b128 v[206:209], v154 offset:35840
	ds_read_b128 v[210:213], v154 offset:36864
	ds_read_b128 v[214:217], v154 offset:37888
	ds_read_b128 v[218:221], v154 offset:38912
	ds_read_b128 v[222:225], v154 offset:39936
	global_load_lds_dwordx4 v[234:235], off
	v_lshl_add_u64 v[234:235], s[58:59], 0, v[132:133]
	s_mov_b32 m0, s11
	s_nop 0
	global_load_lds_dwordx4 v[234:235], off
	s_waitcnt vmcnt(8)
	s_waitcnt lgkmcnt(0)
	s_setprio 1
	s_barrier
	v_mfma_f32_16x16x32_bf16 v[124:127], v[156:159], v[194:197], v[124:127]
	v_mfma_f32_16x16x32_bf16 v[120:123], v[164:167], v[194:197], v[120:123]
	v_mfma_f32_16x16x32_bf16 v[108:111], v[156:159], v[202:205], v[108:111]
	v_mfma_f32_16x16x32_bf16 v[104:107], v[164:167], v[202:205], v[104:107]
	v_mfma_f32_16x16x32_bf16 v[92:95], v[156:159], v[210:213], v[92:95]
	v_mfma_f32_16x16x32_bf16 v[88:91], v[164:167], v[210:213], v[88:91]
	v_mfma_f32_16x16x32_bf16 v[76:79], v[156:159], v[218:221], v[76:79]
	v_mfma_f32_16x16x32_bf16 v[72:75], v[164:167], v[218:221], v[72:75]
	v_mfma_f32_16x16x32_bf16 v[124:127], v[160:163], v[198:201], v[124:127]
	v_mfma_f32_16x16x32_bf16 v[120:123], v[168:171], v[198:201], v[120:123]
	v_mfma_f32_16x16x32_bf16 v[108:111], v[160:163], v[206:209], v[108:111]
	v_mfma_f32_16x16x32_bf16 v[104:107], v[168:171], v[206:209], v[104:107]
	v_mfma_f32_16x16x32_bf16 v[92:95], v[160:163], v[214:217], v[92:95]
	v_mfma_f32_16x16x32_bf16 v[88:91], v[168:171], v[214:217], v[88:91]
	v_mfma_f32_16x16x32_bf16 v[76:79], v[160:163], v[222:225], v[76:79]
	v_mfma_f32_16x16x32_bf16 v[72:75], v[168:171], v[222:225], v[72:75]
	s_setprio 0
	s_setprio 1
	v_mfma_f32_16x16x32_bf16 v[116:119], v[172:175], v[194:197], v[116:119]
	v_mfma_f32_16x16x32_bf16 v[112:115], v[180:183], v[194:197], v[112:115]
	v_mfma_f32_16x16x32_bf16 v[100:103], v[172:175], v[202:205], v[100:103]
	v_mfma_f32_16x16x32_bf16 v[96:99], v[180:183], v[202:205], v[96:99]
	v_mfma_f32_16x16x32_bf16 v[84:87], v[172:175], v[210:213], v[84:87]
	v_mfma_f32_16x16x32_bf16 v[80:83], v[180:183], v[210:213], v[80:83]
	v_mfma_f32_16x16x32_bf16 v[68:71], v[172:175], v[218:221], v[68:71]
	v_mfma_f32_16x16x32_bf16 v[64:67], v[180:183], v[218:221], v[64:67]
	v_mfma_f32_16x16x32_bf16 v[116:119], v[176:179], v[198:201], v[116:119]
	v_mfma_f32_16x16x32_bf16 v[112:115], v[190:193], v[198:201], v[112:115]
	v_mfma_f32_16x16x32_bf16 v[100:103], v[176:179], v[206:209], v[100:103]
	v_mfma_f32_16x16x32_bf16 v[96:99], v[190:193], v[206:209], v[96:99]
	v_mfma_f32_16x16x32_bf16 v[84:87], v[176:179], v[214:217], v[84:87]
	v_mfma_f32_16x16x32_bf16 v[80:83], v[190:193], v[214:217], v[80:83]
	v_mfma_f32_16x16x32_bf16 v[68:71], v[176:179], v[222:225], v[68:71]
	v_mfma_f32_16x16x32_bf16 v[64:67], v[190:193], v[222:225], v[64:67]
	s_barrier
; #define PG8_STAGE(bufoff, gbase, voff) do { _Pragma("unroll") for (int _i = 0; _i < 2; ++_i) \
;         __builtin_amdgcn_global_load_lds((const unsigned*)((const char*)(gbase) + (voff)[_i]), (PG8_LAS unsigned*)(lds + (bufoff) + ldsw + _i * 8192), 16, 0, 0); } while (0)
; #define PG8_LDA(dst, b, h) do { _Pragma("unroll") for (int m = 0; m < 4; ++m) _Pragma("unroll") for (int k = 0; k < 2; ++k) dst[m][k] = *(const PG8_LAS bf16x8*)(lds + PG8_SA(b, h) + aoff + m * 2048 + k * 1024); } while (0)
; #define PG8_MMA(ai, bj, At, Bt) do { __builtin_amdgcn_s_setprio(1); _Pragma("unroll") for (int m = 0; m < 4; ++m) _Pragma("unroll") for (int n = 0; n < 2; ++n) _Pragma("unroll") for (int k = 0; k < 2; ++k) \
;         acc[ai][bj][m][n] = __builtin_amdgcn_mfma_f32_16x16x32_bf16(Bt[n][k], At[m][k], acc[ai][bj][m][n], 0, 0, 0); __builtin_amdgcn_s_setprio(0); } while (0)
; #define PG8_WAIT_V(n) asm volatile("s_waitcnt vmcnt(" #n ")" ::: "memory")
; #define PG8_WAIT_L(n) asm volatile("s_waitcnt lgkmcnt(" #n ")" ::: "memory")
; #define PG8_BAR __builtin_amdgcn_s_barrier()
; #define PG8_SCHED __builtin_amdgcn_sched_barrier(0)
; template <class Epi, class Sched, bool ALIGN_EPI = false, bool SP2 = false>
; __device__ __forceinline__ void gemm_phase(PG8_LAS unsigned char* lds, const Gemm g, const Sched& S, const Epi& E) {
;     ...
;         for (int t = 0; t < nt; t += 2) {
;     ...
;             PG8_LDA(At, 1, 1); PG8_STAGE(PG8_SB(1, 0), b3, voffB); PG8_STAGE(PG8_SB(1, 1), b3 + hstepB, voffB); PG8_STAGE(PG8_SA(1, 0), a3, voffA);
;             PG8_WAIT_V(8); PG8_WAIT_L(0); PG8_BAR; PG8_MMA(1, 0, At, B0); PG8_MMA(1, 1, At, B1); PG8_BAR; PG8_SCHED;
	s_setprio 0
	s_add_i32 s58, s64, s6
	v_lshl_add_u64 v[226:227], v[226:227], 0, s[20:21]
	s_mov_b32 m0, s58
	ds_read_b128 v[194:197], v154 offset:49152
	ds_read_b128 v[198:201], v154 offset:50176
	ds_read_b128 v[202:205], v154 offset:51200
	ds_read_b128 v[206:209], v154 offset:52224
	ds_read_b128 v[210:213], v154 offset:53248
	ds_read_b128 v[214:217], v154 offset:54272
	ds_read_b128 v[218:221], v154 offset:55296
	ds_read_b128 v[222:225], v154 offset:56320
	global_load_lds_dwordx4 v[226:227], off
	s_add_i32 m0, s58, 0x2000
	s_add_u32 s52, s52, 0x80080
	v_lshl_add_u64 v[226:227], v[228:229], 0, s[20:21]
	s_addc_u32 s53, s53, 0
	s_add_i32 s58, s65, s6
	global_load_lds_dwordx4 v[226:227], off
	v_lshl_add_u64 v[226:227], s[52:53], 0, v[130:131]
	s_mov_b32 m0, s58
	s_nop 0
	global_load_lds_dwordx4 v[226:227], off
	v_lshl_add_u64 v[226:227], s[52:53], 0, v[134:135]
	s_add_i32 m0, s58, 0x2000
	s_nop 0
	global_load_lds_dwordx4 v[226:227], off
	v_lshl_add_u64 v[226:227], v[230:231], 0, s[20:21]
	s_mov_b32 m0, s55
	s_nop 0
	global_load_lds_dwordx4 v[226:227], off
	v_lshl_add_u64 v[226:227], v[232:233], 0, s[20:21]
	s_mov_b32 m0, s56
	s_nop 0
	global_load_lds_dwordx4 v[226:227], off
	s_nop 0
	s_waitcnt vmcnt(8)
	s_waitcnt lgkmcnt(0)
	s_setprio 1
	s_barrier
	v_mfma_f32_16x16x32_bf16 v[60:63], v[156:159], v[194:197], v[60:63]
	v_mfma_f32_16x16x32_bf16 v[56:59], v[164:167], v[194:197], v[56:59]
	v_mfma_f32_16x16x32_bf16 v[44:47], v[156:159], v[202:205], v[44:47]
	v_mfma_f32_16x16x32_bf16 v[40:43], v[164:167], v[202:205], v[40:43]
	v_mfma_f32_16x16x32_bf16 v[28:31], v[156:159], v[210:213], v[28:31]
	v_mfma_f32_16x16x32_bf16 v[24:27], v[164:167], v[210:213], v[24:27]
	v_mfma_f32_16x16x32_bf16 v[12:15], v[156:159], v[218:221], v[12:15]
	v_mfma_f32_16x16x32_bf16 v[8:11], v[164:167], v[218:221], v[8:11]
	v_mfma_f32_16x16x32_bf16 v[60:63], v[160:163], v[198:201], v[60:63]
	v_mfma_f32_16x16x32_bf16 v[56:59], v[168:171], v[198:201], v[56:59]
	v_mfma_f32_16x16x32_bf16 v[44:47], v[160:163], v[206:209], v[44:47]
	v_mfma_f32_16x16x32_bf16 v[40:43], v[168:171], v[206:209], v[40:43]
	v_mfma_f32_16x16x32_bf16 v[28:31], v[160:163], v[214:217], v[28:31]
	v_mfma_f32_16x16x32_bf16 v[24:27], v[168:171], v[214:217], v[24:27]
	v_mfma_f32_16x16x32_bf16 v[12:15], v[160:163], v[222:225], v[12:15]
	v_mfma_f32_16x16x32_bf16 v[8:11], v[168:171], v[222:225], v[8:11]
	s_setprio 0
	s_setprio 1
	v_mfma_f32_16x16x32_bf16 v[52:55], v[172:175], v[194:197], v[52:55]
	v_mfma_f32_16x16x32_bf16 v[48:51], v[180:183], v[194:197], v[48:51]
	v_mfma_f32_16x16x32_bf16 v[36:39], v[172:175], v[202:205], v[36:39]
	v_mfma_f32_16x16x32_bf16 v[32:35], v[180:183], v[202:205], v[32:35]
	v_mfma_f32_16x16x32_bf16 v[20:23], v[172:175], v[210:213], v[20:23]
	v_mfma_f32_16x16x32_bf16 v[16:19], v[180:183], v[210:213], v[16:19]
	v_mfma_f32_16x16x32_bf16 v[4:7], v[172:175], v[218:221], v[4:7]
	v_mfma_f32_16x16x32_bf16 v[0:3], v[180:183], v[218:221], v[0:3]
	v_mfma_f32_16x16x32_bf16 v[52:55], v[176:179], v[198:201], v[52:55]
	v_mfma_f32_16x16x32_bf16 v[48:51], v[190:193], v[198:201], v[48:51]
	v_mfma_f32_16x16x32_bf16 v[36:39], v[176:179], v[206:209], v[36:39]
	v_mfma_f32_16x16x32_bf16 v[32:35], v[190:193], v[206:209], v[32:35]
	v_mfma_f32_16x16x32_bf16 v[20:23], v[176:179], v[214:217], v[20:23]
	v_mfma_f32_16x16x32_bf16 v[16:19], v[190:193], v[214:217], v[16:19]
	v_mfma_f32_16x16x32_bf16 v[4:7], v[176:179], v[222:225], v[4:7]
	v_mfma_f32_16x16x32_bf16 v[0:3], v[190:193], v[222:225], v[0:3]
	s_barrier
	s_setprio 0
	s_add_i32 s63, s63, 2
	s_add_u32 s50, s50, 0x100
	s_addc_u32 s51, s51, 0
	s_add_u32 s39, s39, 0x100
	s_addc_u32 s41, s41, 0
	s_cmp_gt_u32 s63, 29
	s_cbranch_scc0 .LBB0_1307
	s_and_b64 vcc, exec, s[34:35]
	s_cbranch_vccz .LBB0_1310
	s_barrier

; #define PG8_STAGE(bufoff, gbase, voff) do { _Pragma("unroll") for (int _i = 0; _i < 2; ++_i) \
;         __builtin_amdgcn_global_load_lds((const unsigned*)((const char*)(gbase) + (voff)[_i]), (PG8_LAS unsigned*)(lds + (bufoff) + ldsw + _i * 8192), 16, 0, 0); } while (0)
; #define PG8_LDA(dst, b, h) do { _Pragma("unroll") for (int m = 0; m < 4; ++m) _Pragma("unroll") for (int k = 0; k < 2; ++k) dst[m][k] = *(const PG8_LAS bf16x8*)(lds + PG8_SA(b, h) + aoff + m * 2048 + k * 1024); } while (0)
; #define PG8_LDB(dst, b, h) do { _Pragma("unroll") for (int n = 0; n < 2; ++n) _Pragma("unroll") for (int k = 0; k < 2; ++k) dst[n][k] = *(const PG8_LAS bf16x8*)(lds + PG8_SB(b, h) + boff + n * 2048 + k * 1024); } while (0)
; #define PG8_WAIT_V(n) asm volatile("s_waitcnt vmcnt(" #n ")" ::: "memory")
; template <class Epi, class Sched, bool ALIGN_EPI = false, bool SP2 = false>
; __device__ __forceinline__ void gemm_phase(PG8_LAS unsigned char* lds, const Gemm g, const Sched& S, const Epi& E) {
;     ...
;             const char* a1 = cA + (size_t)(t + 1) * kstA;
;             const char* a2 = last ? nA : cA + (size_t)(t + 2) * kstA; const char* b2 = last ? nB : cB + (size_t)(t + 2) * kstep;
;             const char* a3 = a2 + kstA; const char* b3 = b2 + kstep;
;             if (last && has_next) S.a_ready(nxt);
;             if constexpr (SP2) {
;             PG8_LDB(B0, 0, 0); PG8_LDB(B1, 0, 1); PG8_SCHED; PG8_LDA(At, 0, 0); PG8_STAGE(PG8_SA(1, 1), a1 + hstepA, voffA);
;             PG8_WAIT_V(8); PG8_WAIT_L(0); PG8_BAR; PG8_MMA(0, 0, At, B0); PG8_MMA(0, 1, At, B1); PG8_BAR; PG8_SCHED;
;             PG8_LDA(At, 0, 1); PG8_STAGE(PG8_SB(0, 0), b2, voffB); PG8_STAGE(PG8_SB(0, 1), b2 + hstepB, voffB); PG8_STAGE(PG8_SA(0, 0), a2, voffA);
;             PG8_WAIT_V(8); PG8_WAIT_L(0); PG8_BAR; PG8_MMA(1, 0, At, B0); PG8_MMA(1, 1, At, B1); PG8_BAR; PG8_SCHED;
;             PG8_LDB(B0, 1, 0); PG8_LDB(B1, 1, 1); PG8_SCHED; PG8_LDA(At, 1, 0); PG8_STAGE(PG8_SA(0, 1), a2 + hstepA, voffA);
;             PG8_WAIT_V(8); PG8_WAIT_L(0); PG8_BAR; PG8_MMA(0, 0, At, B0); PG8_MMA(0, 1, At, B1); PG8_BAR; PG8_SCHED;
;             PG8_LDA(At, 1, 1); PG8_STAGE(PG8_SB(1, 0), b3, voffB); PG8_STAGE(PG8_SB(1, 1), b3 + hstepB, voffB); PG8_STAGE(PG8_SA(1, 0), a3, voffA);
;             PG8_WAIT_V(8); PG8_WAIT_L(0); PG8_BAR; PG8_MMA(1, 0, At, B0); PG8_MMA(1, 1, At, B1); PG8_BAR; PG8_SCHED;
.LBB0_1404:
	s_or_b32 s48, s68, 1
	s_add_i32 s68, s68, 2
	s_mov_b32 s69, s49
	s_lshl_b64 s[4:5], s[48:49], 15
	s_lshl_b64 s[6:7], s[68:69], 15
	s_add_u32 s12, s34, s6
	v_add_u32_e32 v170, s10, v177
	v_add_u32_e32 v174, s11, v177
	s_addc_u32 s13, s35, s7
	ds_read_b128 v[158:161], v170
	ds_read_b128 v[162:165], v170 offset:1024
	ds_read_b128 v[166:169], v170 offset:2048
	ds_read_b128 v[170:173], v170 offset:3072
	ds_read_b128 v[180:183], v174
	ds_read_b128 v[190:193], v174 offset:1024
	ds_read_b128 v[194:197], v174 offset:2048
	ds_read_b128 v[198:201], v174 offset:3072
	s_and_b64 s[6:7], s[50:51], exec
	s_cselect_b32 s59, s13, s61
	s_cselect_b32 s58, s12, s60
	s_lshl_b64 s[6:7], s[68:69], 7
	s_add_u32 s12, s40, s6
	s_addc_u32 s13, s41, s7
	s_and_b64 s[6:7], s[50:51], exec
	s_cselect_b32 s53, s13, s63
	s_cselect_b32 s52, s12, s62
	s_add_u32 s50, s58, 0x8000
	s_addc_u32 s51, s59, 0
	s_add_u32 s4, s21, s4
	s_addc_u32 s5, s39, s5
	v_lshl_add_u64 v[174:175], s[4:5], 0, v[128:129]
	s_add_i32 m0, s74, 0xc000
	ds_read_b128 v[202:205], v179
	ds_read_b128 v[206:209], v179 offset:1024
	ds_read_b128 v[210:213], v179 offset:2048
	ds_read_b128 v[214:217], v179 offset:3072
	ds_read_b128 v[218:221], v179 offset:4096
	ds_read_b128 v[222:225], v179 offset:5120
	ds_read_b128 v[226:229], v179 offset:6144
	ds_read_b128 v[230:233], v179 offset:7168
	global_load_lds_dwordx4 v[174:175], off
	v_lshl_add_u64 v[174:175], s[4:5], 0, v[132:133]
	s_add_i32 m0, s74, 0xe000
	s_nop 0
	global_load_lds_dwordx4 v[174:175], off
	s_waitcnt vmcnt(8)
	s_waitcnt lgkmcnt(0)
	s_setprio 1
	s_barrier
	v_mfma_f32_16x16x32_bf16 v[124:127], v[158:161], v[202:205], v[124:127]
	v_mfma_f32_16x16x32_bf16 v[120:123], v[166:169], v[202:205], v[120:123]
	v_mfma_f32_16x16x32_bf16 v[116:119], v[158:161], v[210:213], v[116:119]
	v_mfma_f32_16x16x32_bf16 v[112:115], v[166:169], v[210:213], v[112:115]
	v_mfma_f32_16x16x32_bf16 v[108:111], v[158:161], v[218:221], v[108:111]
	v_mfma_f32_16x16x32_bf16 v[104:107], v[166:169], v[218:221], v[104:107]
	v_mfma_f32_16x16x32_bf16 v[100:103], v[158:161], v[226:229], v[100:103]
	v_mfma_f32_16x16x32_bf16 v[96:99], v[166:169], v[226:229], v[96:99]
	v_mfma_f32_16x16x32_bf16 v[124:127], v[162:165], v[206:209], v[124:127]
	v_mfma_f32_16x16x32_bf16 v[120:123], v[170:173], v[206:209], v[120:123]
	v_mfma_f32_16x16x32_bf16 v[116:119], v[162:165], v[214:217], v[116:119]
	v_mfma_f32_16x16x32_bf16 v[112:115], v[170:173], v[214:217], v[112:115]
	v_mfma_f32_16x16x32_bf16 v[108:111], v[162:165], v[222:225], v[108:111]
	v_mfma_f32_16x16x32_bf16 v[104:107], v[170:173], v[222:225], v[104:107]
	v_mfma_f32_16x16x32_bf16 v[100:103], v[162:165], v[230:233], v[100:103]
	v_mfma_f32_16x16x32_bf16 v[96:99], v[170:173], v[230:233], v[96:99]
	s_setprio 0
	s_setprio 1
	v_mfma_f32_16x16x32_bf16 v[92:95], v[180:183], v[202:205], v[92:95]
	v_mfma_f32_16x16x32_bf16 v[88:91], v[194:197], v[202:205], v[88:91]
	v_mfma_f32_16x16x32_bf16 v[84:87], v[180:183], v[210:213], v[84:87]
	v_mfma_f32_16x16x32_bf16 v[80:83], v[194:197], v[210:213], v[80:83]
	v_mfma_f32_16x16x32_bf16 v[76:79], v[180:183], v[218:221], v[76:79]
	v_mfma_f32_16x16x32_bf16 v[72:75], v[194:197], v[218:221], v[72:75]
	v_mfma_f32_16x16x32_bf16 v[68:71], v[180:183], v[226:229], v[68:71]
	v_mfma_f32_16x16x32_bf16 v[64:67], v[194:197], v[226:229], v[64:67]
	v_mfma_f32_16x16x32_bf16 v[92:95], v[190:193], v[206:209], v[92:95]
	v_mfma_f32_16x16x32_bf16 v[88:91], v[198:201], v[206:209], v[88:91]
	v_mfma_f32_16x16x32_bf16 v[84:87], v[190:193], v[214:217], v[84:87]
	v_mfma_f32_16x16x32_bf16 v[80:83], v[198:201], v[214:217], v[80:83]
	v_mfma_f32_16x16x32_bf16 v[76:79], v[190:193], v[222:225], v[76:79]
	v_mfma_f32_16x16x32_bf16 v[72:75], v[198:201], v[222:225], v[72:75]
	v_mfma_f32_16x16x32_bf16 v[68:71], v[190:193], v[230:233], v[68:71]
	v_mfma_f32_16x16x32_bf16 v[64:67], v[198:201], v[230:233], v[64:67]
	s_barrier
	s_setprio 0
	s_add_i32 s4, s10, s77
	v_lshl_add_u64 v[174:175], s[52:53], 0, v[130:131]
	s_mov_b32 m0, s4
	ds_read_b128 v[202:205], v179 offset:16384
	ds_read_b128 v[206:209], v179 offset:17408
	ds_read_b128 v[210:213], v179 offset:18432
	ds_read_b128 v[214:217], v179 offset:19456
	ds_read_b128 v[218:221], v179 offset:20480
	ds_read_b128 v[222:225], v179 offset:21504
	ds_read_b128 v[226:229], v179 offset:22528
	ds_read_b128 v[230:233], v179 offset:23552
	global_load_lds_dwordx4 v[174:175], off
	s_add_i32 m0, s4, 0x2000
	s_add_u32 s4, s52, 0x160000
	v_lshl_add_u64 v[234:235], s[52:53], 0, v[134:135]
	s_addc_u32 s5, s53, 0
	s_add_i32 s6, s11, s77
	global_load_lds_dwordx4 v[234:235], off
	v_lshl_add_u64 v[236:237], s[4:5], 0, v[130:131]
	s_mov_b32 m0, s6
	s_nop 0
	global_load_lds_dwordx4 v[236:237], off
	v_lshl_add_u64 v[236:237], s[4:5], 0, v[134:135]
	s_add_i32 m0, s6, 0x2000
	s_nop 0
	global_load_lds_dwordx4 v[236:237], off
	v_lshl_add_u64 v[236:237], s[58:59], 0, v[128:129]
	s_mov_b32 m0, s74
	s_nop 0
	global_load_lds_dwordx4 v[236:237], off
	v_lshl_add_u64 v[236:237], s[58:59], 0, v[132:133]
	s_mov_b32 m0, s96
	s_nop 0
	global_load_lds_dwordx4 v[236:237], off
	s_nop 0
	s_waitcnt vmcnt(8)
	s_waitcnt lgkmcnt(0)
	s_setprio 1
	s_barrier
; #define PG8_STAGE(bufoff, gbase, voff) do { _Pragma("unroll") for (int _i = 0; _i < 2; ++_i) \
;         __builtin_amdgcn_global_load_lds((const unsigned*)((const char*)(gbase) + (voff)[_i]), (PG8_LAS unsigned*)(lds + (bufoff) + ldsw + _i * 8192), 16, 0, 0); } while (0)
; #define PG8_LDA(dst, b, h) do { _Pragma("unroll") for (int m = 0; m < 4; ++m) _Pragma("unroll") for (int k = 0; k < 2; ++k) dst[m][k] = *(const PG8_LAS bf16x8*)(lds + PG8_SA(b, h) + aoff + m * 2048 + k * 1024); } while (0)
; #define PG8_LDB(dst, b, h) do { _Pragma("unroll") for (int n = 0; n < 2; ++n) _Pragma("unroll") for (int k = 0; k < 2; ++k) dst[n][k] = *(const PG8_LAS bf16x8*)(lds + PG8_SB(b, h) + boff + n * 2048 + k * 1024); } while (0)
; #define PG8_MMA(ai, bj, At, Bt) do { __builtin_amdgcn_s_setprio(1); _Pragma("unroll") for (int m = 0; m < 4; ++m) _Pragma("unroll") for (int n = 0; n < 2; ++n) _Pragma("unroll") for (int k = 0; k < 2; ++k) \
;         acc[ai][bj][m][n] = __builtin_amdgcn_mfma_f32_16x16x32_bf16(Bt[n][k], At[m][k], acc[ai][bj][m][n], 0, 0, 0); __builtin_amdgcn_s_setprio(0); } while (0)
; #define PG8_WAIT_V(n) asm volatile("s_waitcnt vmcnt(" #n ")" ::: "memory")
; #define PG8_WAIT_L(n) asm volatile("s_waitcnt lgkmcnt(" #n ")" ::: "memory")
; #define PG8_BAR __builtin_amdgcn_s_barrier()
; #define PG8_SCHED __builtin_amdgcn_sched_barrier(0)
; template <class Epi, class Sched, bool ALIGN_EPI = false, bool SP2 = false>
; __device__ __forceinline__ void gemm_phase(PG8_LAS unsigned char* lds, const Gemm g, const Sched& S, const Epi& E) {
;     ...
;             PG8_WAIT_V(8); PG8_WAIT_L(0); PG8_BAR; PG8_MMA(1, 0, At, B0); PG8_MMA(1, 1, At, B1); PG8_BAR; PG8_SCHED;
;             PG8_LDB(B0, 1, 0); PG8_LDB(B1, 1, 1); PG8_SCHED; PG8_LDA(At, 1, 0); PG8_STAGE(PG8_SA(0, 1), a2 + hstepA, voffA);
;             PG8_WAIT_V(8); PG8_WAIT_L(0); PG8_BAR; PG8_MMA(0, 0, At, B0); PG8_MMA(0, 1, At, B1); PG8_BAR; PG8_SCHED;
	v_mfma_f32_16x16x32_bf16 v[60:63], v[158:161], v[202:205], v[60:63]
	v_mfma_f32_16x16x32_bf16 v[56:59], v[166:169], v[202:205], v[56:59]
	v_mfma_f32_16x16x32_bf16 v[52:55], v[158:161], v[210:213], v[52:55]
	v_mfma_f32_16x16x32_bf16 v[48:51], v[166:169], v[210:213], v[48:51]
	v_mfma_f32_16x16x32_bf16 v[44:47], v[158:161], v[218:221], v[44:47]
	v_mfma_f32_16x16x32_bf16 v[40:43], v[166:169], v[218:221], v[40:43]
	v_mfma_f32_16x16x32_bf16 v[36:39], v[158:161], v[226:229], v[36:39]
	v_mfma_f32_16x16x32_bf16 v[32:35], v[166:169], v[226:229], v[32:35]
	v_mfma_f32_16x16x32_bf16 v[60:63], v[162:165], v[206:209], v[60:63]
	v_mfma_f32_16x16x32_bf16 v[56:59], v[170:173], v[206:209], v[56:59]
	v_mfma_f32_16x16x32_bf16 v[52:55], v[162:165], v[214:217], v[52:55]
	v_mfma_f32_16x16x32_bf16 v[48:51], v[170:173], v[214:217], v[48:51]
	v_mfma_f32_16x16x32_bf16 v[44:47], v[162:165], v[222:225], v[44:47]
	v_mfma_f32_16x16x32_bf16 v[40:43], v[170:173], v[222:225], v[40:43]
	v_mfma_f32_16x16x32_bf16 v[36:39], v[162:165], v[230:233], v[36:39]
	v_mfma_f32_16x16x32_bf16 v[32:35], v[170:173], v[230:233], v[32:35]
	s_setprio 0
	s_setprio 1
	v_mfma_f32_16x16x32_bf16 v[28:31], v[180:183], v[202:205], v[28:31]
	v_mfma_f32_16x16x32_bf16 v[24:27], v[194:197], v[202:205], v[24:27]
	v_mfma_f32_16x16x32_bf16 v[20:23], v[180:183], v[210:213], v[20:23]
	v_mfma_f32_16x16x32_bf16 v[16:19], v[194:197], v[210:213], v[16:19]
	v_mfma_f32_16x16x32_bf16 v[12:15], v[180:183], v[218:221], v[12:15]
	v_mfma_f32_16x16x32_bf16 v[8:11], v[194:197], v[218:221], v[8:11]
	v_mfma_f32_16x16x32_bf16 v[4:7], v[180:183], v[226:229], v[4:7]
	v_mfma_f32_16x16x32_bf16 v[0:3], v[194:197], v[226:229], v[0:3]
	v_mfma_f32_16x16x32_bf16 v[28:31], v[190:193], v[206:209], v[28:31]
	v_mfma_f32_16x16x32_bf16 v[24:27], v[198:201], v[206:209], v[24:27]
	v_mfma_f32_16x16x32_bf16 v[20:23], v[190:193], v[214:217], v[20:23]
	v_mfma_f32_16x16x32_bf16 v[16:19], v[198:201], v[214:217], v[16:19]
	v_mfma_f32_16x16x32_bf16 v[12:15], v[190:193], v[222:225], v[12:15]
	v_mfma_f32_16x16x32_bf16 v[8:11], v[198:201], v[222:225], v[8:11]
	v_mfma_f32_16x16x32_bf16 v[4:7], v[190:193], v[230:233], v[4:7]
	v_mfma_f32_16x16x32_bf16 v[0:3], v[198:201], v[230:233], v[0:3]
	s_barrier
	s_setprio 0
	s_add_i32 s6, 0, 0x18000
	s_add_i32 s7, 0, 0x1c000
	v_add_u32_e32 v170, s6, v177
	v_add_u32_e32 v198, s7, v177
	ds_read_b128 v[158:161], v170
	ds_read_b128 v[162:165], v170 offset:1024
	ds_read_b128 v[166:169], v170 offset:2048
	ds_read_b128 v[170:173], v170 offset:3072
	ds_read_b128 v[180:183], v198
	ds_read_b128 v[190:193], v198 offset:1024
	ds_read_b128 v[194:197], v198 offset:2048
	ds_read_b128 v[198:201], v198 offset:3072
	s_add_u32 s4, s58, 0x4000
	s_addc_u32 s5, s59, 0
	s_mov_b32 m0, s97
	v_lshl_add_u64 v[236:237], s[4:5], 0, v[128:129]
	ds_read_b128 v[202:205], v179 offset:32768
	ds_read_b128 v[206:209], v179 offset:33792
	ds_read_b128 v[210:213], v179 offset:34816
	ds_read_b128 v[214:217], v179 offset:35840
	ds_read_b128 v[218:221], v179 offset:36864
	ds_read_b128 v[222:225], v179 offset:37888
	ds_read_b128 v[226:229], v179 offset:38912
	ds_read_b128 v[230:233], v179 offset:39936
	global_load_lds_dwordx4 v[236:237], off
	v_lshl_add_u64 v[236:237], s[4:5], 0, v[132:133]
	s_mov_b32 m0, s75
	s_nop 0
	global_load_lds_dwordx4 v[236:237], off
	s_waitcnt vmcnt(8)
	s_waitcnt lgkmcnt(0)
	s_setprio 1
	s_barrier
	v_mfma_f32_16x16x32_bf16 v[124:127], v[158:161], v[202:205], v[124:127]
	v_mfma_f32_16x16x32_bf16 v[120:123], v[166:169], v[202:205], v[120:123]
	v_mfma_f32_16x16x32_bf16 v[116:119], v[158:161], v[210:213], v[116:119]
	v_mfma_f32_16x16x32_bf16 v[112:115], v[166:169], v[210:213], v[112:115]
	v_mfma_f32_16x16x32_bf16 v[108:111], v[158:161], v[218:221], v[108:111]
	v_mfma_f32_16x16x32_bf16 v[104:107], v[166:169], v[218:221], v[104:107]
	v_mfma_f32_16x16x32_bf16 v[100:103], v[158:161], v[226:229], v[100:103]
	v_mfma_f32_16x16x32_bf16 v[96:99], v[166:169], v[226:229], v[96:99]
	v_mfma_f32_16x16x32_bf16 v[124:127], v[162:165], v[206:209], v[124:127]
	v_mfma_f32_16x16x32_bf16 v[120:123], v[170:173], v[206:209], v[120:123]
	v_mfma_f32_16x16x32_bf16 v[116:119], v[162:165], v[214:217], v[116:119]
	v_mfma_f32_16x16x32_bf16 v[112:115], v[170:173], v[214:217], v[112:115]
	v_mfma_f32_16x16x32_bf16 v[108:111], v[162:165], v[222:225], v[108:111]
	v_mfma_f32_16x16x32_bf16 v[104:107], v[170:173], v[222:225], v[104:107]
	v_mfma_f32_16x16x32_bf16 v[100:103], v[162:165], v[230:233], v[100:103]
	v_mfma_f32_16x16x32_bf16 v[96:99], v[170:173], v[230:233], v[96:99]
	s_setprio 0
	s_setprio 1
	v_mfma_f32_16x16x32_bf16 v[92:95], v[180:183], v[202:205], v[92:95]
	v_mfma_f32_16x16x32_bf16 v[88:91], v[194:197], v[202:205], v[88:91]
	v_mfma_f32_16x16x32_bf16 v[84:87], v[180:183], v[210:213], v[84:87]
	v_mfma_f32_16x16x32_bf16 v[80:83], v[194:197], v[210:213], v[80:83]
	v_mfma_f32_16x16x32_bf16 v[76:79], v[180:183], v[218:221], v[76:79]
	v_mfma_f32_16x16x32_bf16 v[72:75], v[194:197], v[218:221], v[72:75]
	v_mfma_f32_16x16x32_bf16 v[68:71], v[180:183], v[226:229], v[68:71]
	v_mfma_f32_16x16x32_bf16 v[64:67], v[194:197], v[226:229], v[64:67]
	v_mfma_f32_16x16x32_bf16 v[92:95], v[190:193], v[206:209], v[92:95]
	v_mfma_f32_16x16x32_bf16 v[88:91], v[198:201], v[206:209], v[88:91]
	v_mfma_f32_16x16x32_bf16 v[84:87], v[190:193], v[214:217], v[84:87]
	v_mfma_f32_16x16x32_bf16 v[80:83], v[198:201], v[214:217], v[80:83]
	v_mfma_f32_16x16x32_bf16 v[76:79], v[190:193], v[222:225], v[76:79]
	v_mfma_f32_16x16x32_bf16 v[72:75], v[198:201], v[222:225], v[72:75]
	v_mfma_f32_16x16x32_bf16 v[68:71], v[190:193], v[230:233], v[68:71]
	v_mfma_f32_16x16x32_bf16 v[64:67], v[198:201], v[230:233], v[64:67]
	s_barrier
; #define PG8_STAGE(bufoff, gbase, voff) do { _Pragma("unroll") for (int _i = 0; _i < 2; ++_i) \
;         __builtin_amdgcn_global_load_lds((const unsigned*)((const char*)(gbase) + (voff)[_i]), (PG8_LAS unsigned*)(lds + (bufoff) + ldsw + _i * 8192), 16, 0, 0); } while (0)
; #define PG8_LDA(dst, b, h) do { _Pragma("unroll") for (int m = 0; m < 4; ++m) _Pragma("unroll") for (int k = 0; k < 2; ++k) dst[m][k] = *(const PG8_LAS bf16x8*)(lds + PG8_SA(b, h) + aoff + m * 2048 + k * 1024); } while (0)
; #define PG8_MMA(ai, bj, At, Bt) do { __builtin_amdgcn_s_setprio(1); _Pragma("unroll") for (int m = 0; m < 4; ++m) _Pragma("unroll") for (int n = 0; n < 2; ++n) _Pragma("unroll") for (int k = 0; k < 2; ++k) \
;         acc[ai][bj][m][n] = __builtin_amdgcn_mfma_f32_16x16x32_bf16(Bt[n][k], At[m][k], acc[ai][bj][m][n], 0, 0, 0); __builtin_amdgcn_s_setprio(0); } while (0)
; #define PG8_WAIT_V(n) asm volatile("s_waitcnt vmcnt(" #n ")" ::: "memory")
; #define PG8_WAIT_L(n) asm volatile("s_waitcnt lgkmcnt(" #n ")" ::: "memory")
; #define PG8_BAR __builtin_amdgcn_s_barrier()
; #define PG8_SCHED __builtin_amdgcn_sched_barrier(0)
; template <class Epi, class Sched, bool ALIGN_EPI = false, bool SP2 = false>
; __device__ __forceinline__ void gemm_phase(PG8_LAS unsigned char* lds, const Gemm g, const Sched& S, const Epi& E) {
;     ...
;             PG8_LDA(At, 1, 1); PG8_STAGE(PG8_SB(1, 0), b3, voffB); PG8_STAGE(PG8_SB(1, 1), b3 + hstepB, voffB); PG8_STAGE(PG8_SA(1, 0), a3, voffA);
;             PG8_WAIT_V(8); PG8_WAIT_L(0); PG8_BAR; PG8_MMA(1, 0, At, B0); PG8_MMA(1, 1, At, B1); PG8_BAR; PG8_SCHED;
	s_setprio 0
	s_add_i32 s4, s6, s77
	v_lshl_add_u64 v[174:175], v[174:175], 0, s[64:65]
	s_mov_b32 m0, s4
	ds_read_b128 v[202:205], v179 offset:49152
	ds_read_b128 v[206:209], v179 offset:50176
	ds_read_b128 v[210:213], v179 offset:51200
	ds_read_b128 v[214:217], v179 offset:52224
	ds_read_b128 v[218:221], v179 offset:53248
	ds_read_b128 v[222:225], v179 offset:54272
	ds_read_b128 v[226:229], v179 offset:55296
	ds_read_b128 v[230:233], v179 offset:56320
	global_load_lds_dwordx4 v[174:175], off
	s_add_i32 m0, s4, 0x2000
	s_add_u32 s4, s52, 0x160080
	v_lshl_add_u64 v[174:175], v[234:235], 0, s[64:65]
	s_addc_u32 s5, s53, 0
	s_add_i32 s6, s7, s77
	global_load_lds_dwordx4 v[174:175], off
	v_lshl_add_u64 v[174:175], s[4:5], 0, v[130:131]
	s_mov_b32 m0, s6
	s_nop 0
	global_load_lds_dwordx4 v[174:175], off
	v_lshl_add_u64 v[174:175], s[4:5], 0, v[134:135]
	s_add_i32 m0, s6, 0x2000
	s_nop 0
	global_load_lds_dwordx4 v[174:175], off
	v_lshl_add_u64 v[174:175], s[50:51], 0, v[128:129]
	s_mov_b32 m0, s43
	s_nop 0
	global_load_lds_dwordx4 v[174:175], off
	v_lshl_add_u64 v[174:175], s[50:51], 0, v[132:133]
	s_mov_b32 m0, s56
	s_nop 0
	global_load_lds_dwordx4 v[174:175], off
	s_nop 0
	s_waitcnt vmcnt(8)
	s_waitcnt lgkmcnt(0)
	s_setprio 1
	s_barrier
	v_mfma_f32_16x16x32_bf16 v[60:63], v[158:161], v[202:205], v[60:63]
	v_mfma_f32_16x16x32_bf16 v[56:59], v[166:169], v[202:205], v[56:59]
	v_mfma_f32_16x16x32_bf16 v[52:55], v[158:161], v[210:213], v[52:55]
	v_mfma_f32_16x16x32_bf16 v[48:51], v[166:169], v[210:213], v[48:51]
	v_mfma_f32_16x16x32_bf16 v[44:47], v[158:161], v[218:221], v[44:47]
	v_mfma_f32_16x16x32_bf16 v[40:43], v[166:169], v[218:221], v[40:43]
	v_mfma_f32_16x16x32_bf16 v[36:39], v[158:161], v[226:229], v[36:39]
	v_mfma_f32_16x16x32_bf16 v[32:35], v[166:169], v[226:229], v[32:35]
	v_mfma_f32_16x16x32_bf16 v[60:63], v[162:165], v[206:209], v[60:63]
	v_mfma_f32_16x16x32_bf16 v[56:59], v[170:173], v[206:209], v[56:59]
	v_mfma_f32_16x16x32_bf16 v[52:55], v[162:165], v[214:217], v[52:55]
	v_mfma_f32_16x16x32_bf16 v[48:51], v[170:173], v[214:217], v[48:51]
	v_mfma_f32_16x16x32_bf16 v[44:47], v[162:165], v[222:225], v[44:47]
	v_mfma_f32_16x16x32_bf16 v[40:43], v[170:173], v[222:225], v[40:43]
	v_mfma_f32_16x16x32_bf16 v[36:39], v[162:165], v[230:233], v[36:39]
	v_mfma_f32_16x16x32_bf16 v[32:35], v[170:173], v[230:233], v[32:35]
	s_setprio 0
	s_setprio 1
	v_mfma_f32_16x16x32_bf16 v[28:31], v[180:183], v[202:205], v[28:31]
	v_mfma_f32_16x16x32_bf16 v[24:27], v[194:197], v[202:205], v[24:27]
	v_mfma_f32_16x16x32_bf16 v[20:23], v[180:183], v[210:213], v[20:23]
	v_mfma_f32_16x16x32_bf16 v[16:19], v[194:197], v[210:213], v[16:19]
	v_mfma_f32_16x16x32_bf16 v[12:15], v[180:183], v[218:221], v[12:15]
	v_mfma_f32_16x16x32_bf16 v[8:11], v[194:197], v[218:221], v[8:11]
	v_mfma_f32_16x16x32_bf16 v[4:7], v[180:183], v[226:229], v[4:7]
	v_mfma_f32_16x16x32_bf16 v[0:3], v[194:197], v[226:229], v[0:3]
	v_mfma_f32_16x16x32_bf16 v[28:31], v[190:193], v[206:209], v[28:31]
	v_mfma_f32_16x16x32_bf16 v[24:27], v[198:201], v[206:209], v[24:27]
	v_mfma_f32_16x16x32_bf16 v[20:23], v[190:193], v[214:217], v[20:23]
	v_mfma_f32_16x16x32_bf16 v[16:19], v[198:201], v[214:217], v[16:19]
	v_mfma_f32_16x16x32_bf16 v[12:15], v[190:193], v[222:225], v[12:15]
	v_mfma_f32_16x16x32_bf16 v[8:11], v[198:201], v[222:225], v[8:11]
	v_mfma_f32_16x16x32_bf16 v[4:7], v[190:193], v[230:233], v[4:7]
	v_mfma_f32_16x16x32_bf16 v[0:3], v[198:201], v[230:233], v[0:3]
	s_barrier
	s_setprio 0
	s_cmp_ge_i32 s68, s57
	s_cbranch_scc1 .LBB0_1416

; #define PG8_STAGE(bufoff, gbase, voff) do { _Pragma("unroll") for (int _i = 0; _i < 2; ++_i) \
;         __builtin_amdgcn_global_load_lds((const unsigned*)((const char*)(gbase) + (voff)[_i]), (PG8_LAS unsigned*)(lds + (bufoff) + ldsw + _i * 8192), 16, 0, 0); } while (0)
; #define PG8_LDA(dst, b, h) do { _Pragma("unroll") for (int m = 0; m < 4; ++m) _Pragma("unroll") for (int k = 0; k < 2; ++k) dst[m][k] = *(const PG8_LAS bf16x8*)(lds + PG8_SA(b, h) + aoff + m * 2048 + k * 1024); } while (0)
; #define PG8_LDB(dst, b, h) do { _Pragma("unroll") for (int n = 0; n < 2; ++n) _Pragma("unroll") for (int k = 0; k < 2; ++k) dst[n][k] = *(const PG8_LAS bf16x8*)(lds + PG8_SB(b, h) + boff + n * 2048 + k * 1024); } while (0)
; #define PG8_WAIT_V(n) asm volatile("s_waitcnt vmcnt(" #n ")" ::: "memory")
; template <class Epi, class Sched, bool ALIGN_EPI = false, bool SP2 = false>
; __device__ __forceinline__ void gemm_phase(PG8_LAS unsigned char* lds, const Gemm g, const Sched& S, const Epi& E) {
;     ...
;             const char* a1 = cA + (size_t)(t + 1) * kstA;
;             const char* a2 = last ? nA : cA + (size_t)(t + 2) * kstA; const char* b2 = last ? nB : cB + (size_t)(t + 2) * kstep;
;             const char* a3 = a2 + kstA; const char* b3 = b2 + kstep;
;             if (last && has_next) S.a_ready(nxt);
;             if constexpr (SP2) {
;             PG8_LDB(B0, 0, 0); PG8_LDB(B1, 0, 1); PG8_SCHED; PG8_LDA(At, 0, 0); PG8_STAGE(PG8_SA(1, 1), a1 + hstepA, voffA);
;             PG8_WAIT_V(8); PG8_WAIT_L(0); PG8_BAR; PG8_MMA(0, 0, At, B0); PG8_MMA(0, 1, At, B1); PG8_BAR; PG8_SCHED;
;             PG8_LDA(At, 0, 1); PG8_STAGE(PG8_SB(0, 0), b2, voffB); PG8_STAGE(PG8_SB(0, 1), b2 + hstepB, voffB); PG8_STAGE(PG8_SA(0, 0), a2, voffA);
;             PG8_WAIT_V(8); PG8_WAIT_L(0); PG8_BAR; PG8_MMA(1, 0, At, B0); PG8_MMA(1, 1, At, B1); PG8_BAR; PG8_SCHED;
;             PG8_LDB(B0, 1, 0); PG8_LDB(B1, 1, 1); PG8_SCHED; PG8_LDA(At, 1, 0); PG8_STAGE(PG8_SA(0, 1), a2 + hstepA, voffA);
;             PG8_WAIT_V(8); PG8_WAIT_L(0); PG8_BAR; PG8_MMA(0, 0, At, B0); PG8_MMA(0, 1, At, B1); PG8_BAR; PG8_SCHED;
;             PG8_LDA(At, 1, 1); PG8_STAGE(PG8_SB(1, 0), b3, voffB); PG8_STAGE(PG8_SB(1, 1), b3 + hstepB, voffB); PG8_STAGE(PG8_SA(1, 0), a3, voffA);
;             PG8_WAIT_V(8); PG8_WAIT_L(0); PG8_BAR; PG8_MMA(1, 0, At, B0); PG8_MMA(1, 1, At, B1); PG8_BAR; PG8_SCHED;
.LBB0_1657:
	ds_read_b128 v[156:159], v152
	ds_read_b128 v[160:163], v152 offset:1024
	ds_read_b128 v[164:167], v152 offset:2048
	ds_read_b128 v[168:171], v152 offset:3072
	ds_read_b128 v[172:175], v153
	ds_read_b128 v[176:179], v153 offset:1024
	ds_read_b128 v[180:183], v153 offset:2048
	ds_read_b128 v[190:193], v153 offset:3072
	s_add_u32 s52, s50, 0xfff80080
	s_addc_u32 s53, s51, -1
	s_cmp_eq_u32 s63, 28
	s_cselect_b32 s59, s4, s53
	s_cselect_b32 s58, s5, s52
	s_cselect_b32 s53, s12, s41
	s_cselect_b32 s52, s13, s39
	v_lshl_add_u64 v[226:227], s[50:51], 0, v[142:143]
	s_add_i32 m0, s7, 0xc000
	ds_read_b128 v[194:197], v154
	ds_read_b128 v[198:201], v154 offset:1024
	ds_read_b128 v[202:205], v154 offset:2048
	ds_read_b128 v[206:209], v154 offset:3072
	ds_read_b128 v[210:213], v154 offset:4096
	ds_read_b128 v[214:217], v154 offset:5120
	ds_read_b128 v[218:221], v154 offset:6144
	ds_read_b128 v[222:225], v154 offset:7168
	global_load_lds_dwordx4 v[226:227], off
	v_lshl_add_u64 v[226:227], s[50:51], 0, v[144:145]
	s_add_i32 m0, s7, 0xe000
	s_nop 0
	global_load_lds_dwordx4 v[226:227], off
	s_waitcnt vmcnt(8)
	s_waitcnt lgkmcnt(0)
	s_setprio 1
	s_barrier
	v_mfma_f32_16x16x32_bf16 v[124:127], v[156:159], v[194:197], v[124:127]
	v_mfma_f32_16x16x32_bf16 v[120:123], v[164:167], v[194:197], v[120:123]
	v_mfma_f32_16x16x32_bf16 v[108:111], v[156:159], v[202:205], v[108:111]
	v_mfma_f32_16x16x32_bf16 v[104:107], v[164:167], v[202:205], v[104:107]
	v_mfma_f32_16x16x32_bf16 v[92:95], v[156:159], v[210:213], v[92:95]
	v_mfma_f32_16x16x32_bf16 v[88:91], v[164:167], v[210:213], v[88:91]
	v_mfma_f32_16x16x32_bf16 v[76:79], v[156:159], v[218:221], v[76:79]
	v_mfma_f32_16x16x32_bf16 v[72:75], v[164:167], v[218:221], v[72:75]
	v_mfma_f32_16x16x32_bf16 v[124:127], v[160:163], v[198:201], v[124:127]
	v_mfma_f32_16x16x32_bf16 v[120:123], v[168:171], v[198:201], v[120:123]
	v_mfma_f32_16x16x32_bf16 v[108:111], v[160:163], v[206:209], v[108:111]
	v_mfma_f32_16x16x32_bf16 v[104:107], v[168:171], v[206:209], v[104:107]
	v_mfma_f32_16x16x32_bf16 v[92:95], v[160:163], v[214:217], v[92:95]
	v_mfma_f32_16x16x32_bf16 v[88:91], v[168:171], v[214:217], v[88:91]
	v_mfma_f32_16x16x32_bf16 v[76:79], v[160:163], v[222:225], v[76:79]
	v_mfma_f32_16x16x32_bf16 v[72:75], v[168:171], v[222:225], v[72:75]
	s_setprio 0
	s_setprio 1
	v_mfma_f32_16x16x32_bf16 v[116:119], v[172:175], v[194:197], v[116:119]
	v_mfma_f32_16x16x32_bf16 v[112:115], v[180:183], v[194:197], v[112:115]
	v_mfma_f32_16x16x32_bf16 v[100:103], v[172:175], v[202:205], v[100:103]
	v_mfma_f32_16x16x32_bf16 v[96:99], v[180:183], v[202:205], v[96:99]
	v_mfma_f32_16x16x32_bf16 v[84:87], v[172:175], v[210:213], v[84:87]
	v_mfma_f32_16x16x32_bf16 v[80:83], v[180:183], v[210:213], v[80:83]
	v_mfma_f32_16x16x32_bf16 v[68:71], v[172:175], v[218:221], v[68:71]
	v_mfma_f32_16x16x32_bf16 v[64:67], v[180:183], v[218:221], v[64:67]
	v_mfma_f32_16x16x32_bf16 v[116:119], v[176:179], v[198:201], v[116:119]
	v_mfma_f32_16x16x32_bf16 v[112:115], v[190:193], v[198:201], v[112:115]
	v_mfma_f32_16x16x32_bf16 v[100:103], v[176:179], v[206:209], v[100:103]
	v_mfma_f32_16x16x32_bf16 v[96:99], v[190:193], v[206:209], v[96:99]
	v_mfma_f32_16x16x32_bf16 v[84:87], v[176:179], v[214:217], v[84:87]
	v_mfma_f32_16x16x32_bf16 v[80:83], v[190:193], v[214:217], v[80:83]
	v_mfma_f32_16x16x32_bf16 v[68:71], v[176:179], v[222:225], v[68:71]
	v_mfma_f32_16x16x32_bf16 v[64:67], v[190:193], v[222:225], v[64:67]
	s_barrier
	s_setprio 0
	s_add_i32 s64, s56, s6
	v_lshl_add_u64 v[226:227], s[52:53], 0, v[130:131]
	s_mov_b32 m0, s64
	ds_read_b128 v[194:197], v154 offset:16384
	ds_read_b128 v[198:201], v154 offset:17408
	ds_read_b128 v[202:205], v154 offset:18432
	ds_read_b128 v[206:209], v154 offset:19456
	ds_read_b128 v[210:213], v154 offset:20480
	ds_read_b128 v[214:217], v154 offset:21504
	ds_read_b128 v[218:221], v154 offset:22528
	ds_read_b128 v[222:225], v154 offset:23552
	global_load_lds_dwordx4 v[226:227], off
	s_add_i32 m0, s64, 0x2000
	s_add_u32 s64, s52, 0x80000
	v_lshl_add_u64 v[228:229], s[52:53], 0, v[134:135]
	s_addc_u32 s65, s53, 0
	s_add_i32 s66, s57, s6
	global_load_lds_dwordx4 v[228:229], off
	v_lshl_add_u64 v[230:231], s[64:65], 0, v[130:131]
	s_mov_b32 m0, s66
	v_lshl_add_u64 v[232:233], s[58:59], 0, v[132:133]
	global_load_lds_dwordx4 v[230:231], off
	v_lshl_add_u64 v[230:231], s[64:65], 0, v[134:135]
	s_add_i32 m0, s66, 0x2000
	s_nop 0
	global_load_lds_dwordx4 v[230:231], off
	v_lshl_add_u64 v[230:231], s[58:59], 0, v[128:129]
	s_mov_b32 m0, s7
	s_nop 0
	global_load_lds_dwordx4 v[230:231], off
	s_mov_b32 m0, s8
	s_nop 0
	global_load_lds_dwordx4 v[232:233], off
	s_waitcnt vmcnt(8)
	s_waitcnt lgkmcnt(0)
	s_setprio 1
	s_barrier
; #define PG8_STAGE(bufoff, gbase, voff) do { _Pragma("unroll") for (int _i = 0; _i < 2; ++_i) \
;         __builtin_amdgcn_global_load_lds((const unsigned*)((const char*)(gbase) + (voff)[_i]), (PG8_LAS unsigned*)(lds + (bufoff) + ldsw + _i * 8192), 16, 0, 0); } while (0)
; #define PG8_LDA(dst, b, h) do { _Pragma("unroll") for (int m = 0; m < 4; ++m) _Pragma("unroll") for (int k = 0; k < 2; ++k) dst[m][k] = *(const PG8_LAS bf16x8*)(lds + PG8_SA(b, h) + aoff + m * 2048 + k * 1024); } while (0)
; #define PG8_LDB(dst, b, h) do { _Pragma("unroll") for (int n = 0; n < 2; ++n) _Pragma("unroll") for (int k = 0; k < 2; ++k) dst[n][k] = *(const PG8_LAS bf16x8*)(lds + PG8_SB(b, h) + boff + n * 2048 + k * 1024); } while (0)
; #define PG8_MMA(ai, bj, At, Bt) do { __builtin_amdgcn_s_setprio(1); _Pragma("unroll") for (int m = 0; m < 4; ++m) _Pragma("unroll") for (int n = 0; n < 2; ++n) _Pragma("unroll") for (int k = 0; k < 2; ++k) \
;         acc[ai][bj][m][n] = __builtin_amdgcn_mfma_f32_16x16x32_bf16(Bt[n][k], At[m][k], acc[ai][bj][m][n], 0, 0, 0); __builtin_amdgcn_s_setprio(0); } while (0)
; #define PG8_WAIT_V(n) asm volatile("s_waitcnt vmcnt(" #n ")" ::: "memory")
; #define PG8_WAIT_L(n) asm volatile("s_waitcnt lgkmcnt(" #n ")" ::: "memory")
; #define PG8_BAR __builtin_amdgcn_s_barrier()
; #define PG8_SCHED __builtin_amdgcn_sched_barrier(0)
; template <class Epi, class Sched, bool ALIGN_EPI = false, bool SP2 = false>
; __device__ __forceinline__ void gemm_phase(PG8_LAS unsigned char* lds, const Gemm g, const Sched& S, const Epi& E) {
;     ...
;             PG8_WAIT_V(8); PG8_WAIT_L(0); PG8_BAR; PG8_MMA(1, 0, At, B0); PG8_MMA(1, 1, At, B1); PG8_BAR; PG8_SCHED;
;             PG8_LDB(B0, 1, 0); PG8_LDB(B1, 1, 1); PG8_SCHED; PG8_LDA(At, 1, 0); PG8_STAGE(PG8_SA(0, 1), a2 + hstepA, voffA);
;             PG8_WAIT_V(8); PG8_WAIT_L(0); PG8_BAR; PG8_MMA(0, 0, At, B0); PG8_MMA(0, 1, At, B1); PG8_BAR; PG8_SCHED;
	v_mfma_f32_16x16x32_bf16 v[60:63], v[156:159], v[194:197], v[60:63]
	v_mfma_f32_16x16x32_bf16 v[56:59], v[164:167], v[194:197], v[56:59]
	v_mfma_f32_16x16x32_bf16 v[44:47], v[156:159], v[202:205], v[44:47]
	v_mfma_f32_16x16x32_bf16 v[40:43], v[164:167], v[202:205], v[40:43]
	v_mfma_f32_16x16x32_bf16 v[28:31], v[156:159], v[210:213], v[28:31]
	v_mfma_f32_16x16x32_bf16 v[24:27], v[164:167], v[210:213], v[24:27]
	v_mfma_f32_16x16x32_bf16 v[12:15], v[156:159], v[218:221], v[12:15]
	v_mfma_f32_16x16x32_bf16 v[8:11], v[164:167], v[218:221], v[8:11]
	v_mfma_f32_16x16x32_bf16 v[60:63], v[160:163], v[198:201], v[60:63]
	v_mfma_f32_16x16x32_bf16 v[56:59], v[168:171], v[198:201], v[56:59]
	v_mfma_f32_16x16x32_bf16 v[44:47], v[160:163], v[206:209], v[44:47]
	v_mfma_f32_16x16x32_bf16 v[40:43], v[168:171], v[206:209], v[40:43]
	v_mfma_f32_16x16x32_bf16 v[28:31], v[160:163], v[214:217], v[28:31]
	v_mfma_f32_16x16x32_bf16 v[24:27], v[168:171], v[214:217], v[24:27]
	v_mfma_f32_16x16x32_bf16 v[12:15], v[160:163], v[222:225], v[12:15]
	v_mfma_f32_16x16x32_bf16 v[8:11], v[168:171], v[222:225], v[8:11]
	s_setprio 0
	s_setprio 1
	v_mfma_f32_16x16x32_bf16 v[52:55], v[172:175], v[194:197], v[52:55]
	v_mfma_f32_16x16x32_bf16 v[48:51], v[180:183], v[194:197], v[48:51]
	v_mfma_f32_16x16x32_bf16 v[36:39], v[172:175], v[202:205], v[36:39]
	v_mfma_f32_16x16x32_bf16 v[32:35], v[180:183], v[202:205], v[32:35]
	v_mfma_f32_16x16x32_bf16 v[20:23], v[172:175], v[210:213], v[20:23]
	v_mfma_f32_16x16x32_bf16 v[16:19], v[180:183], v[210:213], v[16:19]
	v_mfma_f32_16x16x32_bf16 v[4:7], v[172:175], v[218:221], v[4:7]
	v_mfma_f32_16x16x32_bf16 v[0:3], v[180:183], v[218:221], v[0:3]
	v_mfma_f32_16x16x32_bf16 v[52:55], v[176:179], v[198:201], v[52:55]
	v_mfma_f32_16x16x32_bf16 v[48:51], v[190:193], v[198:201], v[48:51]
	v_mfma_f32_16x16x32_bf16 v[36:39], v[176:179], v[206:209], v[36:39]
	v_mfma_f32_16x16x32_bf16 v[32:35], v[190:193], v[206:209], v[32:35]
	v_mfma_f32_16x16x32_bf16 v[20:23], v[176:179], v[214:217], v[20:23]
	v_mfma_f32_16x16x32_bf16 v[16:19], v[190:193], v[214:217], v[16:19]
	v_mfma_f32_16x16x32_bf16 v[4:7], v[176:179], v[222:225], v[4:7]
	v_mfma_f32_16x16x32_bf16 v[0:3], v[190:193], v[222:225], v[0:3]
	s_barrier
	s_setprio 0
	s_add_i32 s64, 0, 0x18000
	v_add_u32_e32 v155, s64, v150
	s_add_i32 s65, 0, 0x1c000
	ds_read_b128 v[156:159], v155
	ds_read_b128 v[160:163], v155 offset:1024
	ds_read_b128 v[164:167], v155 offset:2048
	ds_read_b128 v[168:171], v155 offset:3072
	v_add_u32_e32 v155, s65, v150
	ds_read_b128 v[172:175], v155
	ds_read_b128 v[176:179], v155 offset:1024
	ds_read_b128 v[180:183], v155 offset:2048
	ds_read_b128 v[190:193], v155 offset:3072
	s_add_u32 s58, s58, 0x80000
	s_addc_u32 s59, s59, 0
	s_mov_b32 m0, s9
	v_lshl_add_u64 v[234:235], s[58:59], 0, v[128:129]
	ds_read_b128 v[194:197], v154 offset:32768
	ds_read_b128 v[198:201], v154 offset:33792
	ds_read_b128 v[202:205], v154 offset:34816
	ds_read_b128 v[206:209], v154 offset:35840
	ds_read_b128 v[210:213], v154 offset:36864
	ds_read_b128 v[214:217], v154 offset:37888
	ds_read_b128 v[218:221], v154 offset:38912
	ds_read_b128 v[222:225], v154 offset:39936
	global_load_lds_dwordx4 v[234:235], off
	v_lshl_add_u64 v[234:235], s[58:59], 0, v[132:133]
	s_mov_b32 m0, s11
	s_nop 0
	global_load_lds_dwordx4 v[234:235], off
	s_waitcnt vmcnt(8)
	s_waitcnt lgkmcnt(0)
	s_setprio 1
	s_barrier
	v_mfma_f32_16x16x32_bf16 v[124:127], v[156:159], v[194:197], v[124:127]
	v_mfma_f32_16x16x32_bf16 v[120:123], v[164:167], v[194:197], v[120:123]
	v_mfma_f32_16x16x32_bf16 v[108:111], v[156:159], v[202:205], v[108:111]
	v_mfma_f32_16x16x32_bf16 v[104:107], v[164:167], v[202:205], v[104:107]
	v_mfma_f32_16x16x32_bf16 v[92:95], v[156:159], v[210:213], v[92:95]
	v_mfma_f32_16x16x32_bf16 v[88:91], v[164:167], v[210:213], v[88:91]
	v_mfma_f32_16x16x32_bf16 v[76:79], v[156:159], v[218:221], v[76:79]
	v_mfma_f32_16x16x32_bf16 v[72:75], v[164:167], v[218:221], v[72:75]
	v_mfma_f32_16x16x32_bf16 v[124:127], v[160:163], v[198:201], v[124:127]
	v_mfma_f32_16x16x32_bf16 v[120:123], v[168:171], v[198:201], v[120:123]
	v_mfma_f32_16x16x32_bf16 v[108:111], v[160:163], v[206:209], v[108:111]
	v_mfma_f32_16x16x32_bf16 v[104:107], v[168:171], v[206:209], v[104:107]
	v_mfma_f32_16x16x32_bf16 v[92:95], v[160:163], v[214:217], v[92:95]
	v_mfma_f32_16x16x32_bf16 v[88:91], v[168:171], v[214:217], v[88:91]
	v_mfma_f32_16x16x32_bf16 v[76:79], v[160:163], v[222:225], v[76:79]
	v_mfma_f32_16x16x32_bf16 v[72:75], v[168:171], v[222:225], v[72:75]
	s_setprio 0
	s_setprio 1
	v_mfma_f32_16x16x32_bf16 v[116:119], v[172:175], v[194:197], v[116:119]
	v_mfma_f32_16x16x32_bf16 v[112:115], v[180:183], v[194:197], v[112:115]
	v_mfma_f32_16x16x32_bf16 v[100:103], v[172:175], v[202:205], v[100:103]
	v_mfma_f32_16x16x32_bf16 v[96:99], v[180:183], v[202:205], v[96:99]
	v_mfma_f32_16x16x32_bf16 v[84:87], v[172:175], v[210:213], v[84:87]
	v_mfma_f32_16x16x32_bf16 v[80:83], v[180:183], v[210:213], v[80:83]
	v_mfma_f32_16x16x32_bf16 v[68:71], v[172:175], v[218:221], v[68:71]
	v_mfma_f32_16x16x32_bf16 v[64:67], v[180:183], v[218:221], v[64:67]
	v_mfma_f32_16x16x32_bf16 v[116:119], v[176:179], v[198:201], v[116:119]
	v_mfma_f32_16x16x32_bf16 v[112:115], v[190:193], v[198:201], v[112:115]
	v_mfma_f32_16x16x32_bf16 v[100:103], v[176:179], v[206:209], v[100:103]
	v_mfma_f32_16x16x32_bf16 v[96:99], v[190:193], v[206:209], v[96:99]
	v_mfma_f32_16x16x32_bf16 v[84:87], v[176:179], v[214:217], v[84:87]
	v_mfma_f32_16x16x32_bf16 v[80:83], v[190:193], v[214:217], v[80:83]
	v_mfma_f32_16x16x32_bf16 v[68:71], v[176:179], v[222:225], v[68:71]
	v_mfma_f32_16x16x32_bf16 v[64:67], v[190:193], v[222:225], v[64:67]
	s_barrier
; #define PG8_STAGE(bufoff, gbase, voff) do { _Pragma("unroll") for (int _i = 0; _i < 2; ++_i) \
;         __builtin_amdgcn_global_load_lds((const unsigned*)((const char*)(gbase) + (voff)[_i]), (PG8_LAS unsigned*)(lds + (bufoff) + ldsw + _i * 8192), 16, 0, 0); } while (0)
; #define PG8_LDA(dst, b, h) do { _Pragma("unroll") for (int m = 0; m < 4; ++m) _Pragma("unroll") for (int k = 0; k < 2; ++k) dst[m][k] = *(const PG8_LAS bf16x8*)(lds + PG8_SA(b, h) + aoff + m * 2048 + k * 1024); } while (0)
; #define PG8_MMA(ai, bj, At, Bt) do { __builtin_amdgcn_s_setprio(1); _Pragma("unroll") for (int m = 0; m < 4; ++m) _Pragma("unroll") for (int n = 0; n < 2; ++n) _Pragma("unroll") for (int k = 0; k < 2; ++k) \
;         acc[ai][bj][m][n] = __builtin_amdgcn_mfma_f32_16x16x32_bf16(Bt[n][k], At[m][k], acc[ai][bj][m][n], 0, 0, 0); __builtin_amdgcn_s_setprio(0); } while (0)
; #define PG8_WAIT_V(n) asm volatile("s_waitcnt vmcnt(" #n ")" ::: "memory")
; #define PG8_WAIT_L(n) asm volatile("s_waitcnt lgkmcnt(" #n ")" ::: "memory")
; #define PG8_BAR __builtin_amdgcn_s_barrier()
; #define PG8_SCHED __builtin_amdgcn_sched_barrier(0)
; template <class Epi, class Sched, bool ALIGN_EPI = false, bool SP2 = false>
; __device__ __forceinline__ void gemm_phase(PG8_LAS unsigned char* lds, const Gemm g, const Sched& S, const Epi& E) {
;     ...
;         for (int t = 0; t < nt; t += 2) {
;     ...
;             PG8_LDA(At, 1, 1); PG8_STAGE(PG8_SB(1, 0), b3, voffB); PG8_STAGE(PG8_SB(1, 1), b3 + hstepB, voffB); PG8_STAGE(PG8_SA(1, 0), a3, voffA);
;             PG8_WAIT_V(8); PG8_WAIT_L(0); PG8_BAR; PG8_MMA(1, 0, At, B0); PG8_MMA(1, 1, At, B1); PG8_BAR; PG8_SCHED;
	s_setprio 0
	s_add_i32 s58, s64, s6
	v_lshl_add_u64 v[226:227], v[226:227], 0, s[20:21]
	s_mov_b32 m0, s58
	ds_read_b128 v[194:197], v154 offset:49152
	ds_read_b128 v[198:201], v154 offset:50176
	ds_read_b128 v[202:205], v154 offset:51200
	ds_read_b128 v[206:209], v154 offset:52224
	ds_read_b128 v[210:213], v154 offset:53248
	ds_read_b128 v[214:217], v154 offset:54272
	ds_read_b128 v[218:221], v154 offset:55296
	ds_read_b128 v[222:225], v154 offset:56320
	global_load_lds_dwordx4 v[226:227], off
	s_add_i32 m0, s58, 0x2000
	s_add_u32 s52, s52, 0x80080
	v_lshl_add_u64 v[226:227], v[228:229], 0, s[20:21]
	s_addc_u32 s53, s53, 0
	s_add_i32 s58, s65, s6
	global_load_lds_dwordx4 v[226:227], off
	v_lshl_add_u64 v[226:227], s[52:53], 0, v[130:131]
	s_mov_b32 m0, s58
	s_nop 0
	global_load_lds_dwordx4 v[226:227], off
	v_lshl_add_u64 v[226:227], s[52:53], 0, v[134:135]
	s_add_i32 m0, s58, 0x2000
	s_nop 0
	global_load_lds_dwordx4 v[226:227], off
	v_lshl_add_u64 v[226:227], v[230:231], 0, s[20:21]
	s_mov_b32 m0, s46
	s_nop 0
	global_load_lds_dwordx4 v[226:227], off
	v_lshl_add_u64 v[226:227], v[232:233], 0, s[20:21]
	s_mov_b32 m0, s47
	s_nop 0
	global_load_lds_dwordx4 v[226:227], off
	s_nop 0
	s_waitcnt vmcnt(8)
	s_waitcnt lgkmcnt(0)
	s_setprio 1
	s_barrier
	v_mfma_f32_16x16x32_bf16 v[60:63], v[156:159], v[194:197], v[60:63]
	v_mfma_f32_16x16x32_bf16 v[56:59], v[164:167], v[194:197], v[56:59]
	v_mfma_f32_16x16x32_bf16 v[44:47], v[156:159], v[202:205], v[44:47]
	v_mfma_f32_16x16x32_bf16 v[40:43], v[164:167], v[202:205], v[40:43]
	v_mfma_f32_16x16x32_bf16 v[28:31], v[156:159], v[210:213], v[28:31]
	v_mfma_f32_16x16x32_bf16 v[24:27], v[164:167], v[210:213], v[24:27]
	v_mfma_f32_16x16x32_bf16 v[12:15], v[156:159], v[218:221], v[12:15]
	v_mfma_f32_16x16x32_bf16 v[8:11], v[164:167], v[218:221], v[8:11]
	v_mfma_f32_16x16x32_bf16 v[60:63], v[160:163], v[198:201], v[60:63]
	v_mfma_f32_16x16x32_bf16 v[56:59], v[168:171], v[198:201], v[56:59]
	v_mfma_f32_16x16x32_bf16 v[44:47], v[160:163], v[206:209], v[44:47]
	v_mfma_f32_16x16x32_bf16 v[40:43], v[168:171], v[206:209], v[40:43]
	v_mfma_f32_16x16x32_bf16 v[28:31], v[160:163], v[214:217], v[28:31]
	v_mfma_f32_16x16x32_bf16 v[24:27], v[168:171], v[214:217], v[24:27]
	v_mfma_f32_16x16x32_bf16 v[12:15], v[160:163], v[222:225], v[12:15]
	v_mfma_f32_16x16x32_bf16 v[8:11], v[168:171], v[222:225], v[8:11]
	s_setprio 0
	s_setprio 1
	v_mfma_f32_16x16x32_bf16 v[52:55], v[172:175], v[194:197], v[52:55]
	v_mfma_f32_16x16x32_bf16 v[48:51], v[180:183], v[194:197], v[48:51]
	v_mfma_f32_16x16x32_bf16 v[36:39], v[172:175], v[202:205], v[36:39]
	v_mfma_f32_16x16x32_bf16 v[32:35], v[180:183], v[202:205], v[32:35]
	v_mfma_f32_16x16x32_bf16 v[20:23], v[172:175], v[210:213], v[20:23]
	v_mfma_f32_16x16x32_bf16 v[16:19], v[180:183], v[210:213], v[16:19]
	v_mfma_f32_16x16x32_bf16 v[4:7], v[172:175], v[218:221], v[4:7]
	v_mfma_f32_16x16x32_bf16 v[0:3], v[180:183], v[218:221], v[0:3]
	v_mfma_f32_16x16x32_bf16 v[52:55], v[176:179], v[198:201], v[52:55]
	v_mfma_f32_16x16x32_bf16 v[48:51], v[190:193], v[198:201], v[48:51]
	v_mfma_f32_16x16x32_bf16 v[36:39], v[176:179], v[206:209], v[36:39]
	v_mfma_f32_16x16x32_bf16 v[32:35], v[190:193], v[206:209], v[32:35]
	v_mfma_f32_16x16x32_bf16 v[20:23], v[176:179], v[214:217], v[20:23]
	v_mfma_f32_16x16x32_bf16 v[16:19], v[190:193], v[214:217], v[16:19]
	v_mfma_f32_16x16x32_bf16 v[4:7], v[176:179], v[222:225], v[4:7]
	v_mfma_f32_16x16x32_bf16 v[0:3], v[190:193], v[222:225], v[0:3]
	s_barrier
	s_setprio 0
	s_add_i32 s63, s63, 2
	s_add_u32 s50, s50, 0x100
	s_addc_u32 s51, s51, 0
	s_add_u32 s39, s39, 0x100
	s_addc_u32 s41, s41, 0
	s_cmp_gt_u32 s63, 29
	s_cbranch_scc0 .LBB0_1657
	s_and_b64 vcc, exec, s[34:35]
	s_cbranch_vccz .LBB0_1660
	s_barrier

; #define PG8_STAGE(bufoff, gbase, voff) do { _Pragma("unroll") for (int _i = 0; _i < 2; ++_i) \
;         __builtin_amdgcn_global_load_lds((const unsigned*)((const char*)(gbase) + (voff)[_i]), (PG8_LAS unsigned*)(lds + (bufoff) + ldsw + _i * 8192), 16, 0, 0); } while (0)
; #define PG8_LDA(dst, b, h) do { _Pragma("unroll") for (int m = 0; m < 4; ++m) _Pragma("unroll") for (int k = 0; k < 2; ++k) dst[m][k] = *(const PG8_LAS bf16x8*)(lds + PG8_SA(b, h) + aoff + m * 2048 + k * 1024); } while (0)
; #define PG8_LDB(dst, b, h) do { _Pragma("unroll") for (int n = 0; n < 2; ++n) _Pragma("unroll") for (int k = 0; k < 2; ++k) dst[n][k] = *(const PG8_LAS bf16x8*)(lds + PG8_SB(b, h) + boff + n * 2048 + k * 1024); } while (0)
; #define PG8_WAIT_V(n) asm volatile("s_waitcnt vmcnt(" #n ")" ::: "memory")
; template <class Epi, class Sched, bool ALIGN_EPI = false, bool SP2 = false>
; __device__ __forceinline__ void gemm_phase(PG8_LAS unsigned char* lds, const Gemm g, const Sched& S, const Epi& E) {
;     ...
;             const char* a1 = cA + (size_t)(t + 1) * kstA;
;             const char* a2 = last ? nA : cA + (size_t)(t + 2) * kstA; const char* b2 = last ? nB : cB + (size_t)(t + 2) * kstep;
;             const char* a3 = a2 + kstA; const char* b3 = b2 + kstep;
;             if (last && has_next) S.a_ready(nxt);
;             if constexpr (SP2) {
;             PG8_LDB(B0, 0, 0); PG8_LDB(B1, 0, 1); PG8_SCHED; PG8_LDA(At, 0, 0); PG8_STAGE(PG8_SA(1, 1), a1 + hstepA, voffA);
;             PG8_WAIT_V(8); PG8_WAIT_L(0); PG8_BAR; PG8_MMA(0, 0, At, B0); PG8_MMA(0, 1, At, B1); PG8_BAR; PG8_SCHED;
;             PG8_LDA(At, 0, 1); PG8_STAGE(PG8_SB(0, 0), b2, voffB); PG8_STAGE(PG8_SB(0, 1), b2 + hstepB, voffB); PG8_STAGE(PG8_SA(0, 0), a2, voffA);
;             PG8_WAIT_V(8); PG8_WAIT_L(0); PG8_BAR; PG8_MMA(1, 0, At, B0); PG8_MMA(1, 1, At, B1); PG8_BAR; PG8_SCHED;
;             PG8_LDB(B0, 1, 0); PG8_LDB(B1, 1, 1); PG8_SCHED; PG8_LDA(At, 1, 0); PG8_STAGE(PG8_SA(0, 1), a2 + hstepA, voffA);
;             PG8_WAIT_V(8); PG8_WAIT_L(0); PG8_BAR; PG8_MMA(0, 0, At, B0); PG8_MMA(0, 1, At, B1); PG8_BAR; PG8_SCHED;
;             PG8_LDA(At, 1, 1); PG8_STAGE(PG8_SB(1, 0), b3, voffB); PG8_STAGE(PG8_SB(1, 1), b3 + hstepB, voffB); PG8_STAGE(PG8_SA(1, 0), a3, voffA);
;             PG8_WAIT_V(8); PG8_WAIT_L(0); PG8_BAR; PG8_MMA(1, 0, At, B0); PG8_MMA(1, 1, At, B1); PG8_BAR; PG8_SCHED;
.LBB0_1754:
	s_or_b32 s44, s62, 1
	s_add_i32 s62, s62, 2
	s_mov_b32 s63, s45
	s_lshl_b64 s[4:5], s[44:45], 15
	s_lshl_b64 s[6:7], s[62:63], 15
	s_add_u32 s12, s34, s6
	v_add_u32_e32 v170, s10, v177
	v_add_u32_e32 v174, s11, v177
	s_addc_u32 s13, s35, s7
	ds_read_b128 v[158:161], v170
	ds_read_b128 v[162:165], v170 offset:1024
	ds_read_b128 v[166:169], v170 offset:2048
	ds_read_b128 v[170:173], v170 offset:3072
	ds_read_b128 v[180:183], v174
	ds_read_b128 v[190:193], v174 offset:1024
	ds_read_b128 v[194:197], v174 offset:2048
	ds_read_b128 v[198:201], v174 offset:3072
	s_and_b64 s[6:7], s[50:51], exec
	s_cselect_b32 s69, s13, s59
	s_cselect_b32 s68, s12, s58
	s_lshl_b64 s[6:7], s[62:63], 7
	s_add_u32 s12, s40, s6
	s_addc_u32 s13, s41, s7
	s_and_b64 s[6:7], s[50:51], exec
	s_cselect_b32 s53, s13, s61
	s_cselect_b32 s52, s12, s60
	s_add_u32 s50, s68, 0x8000
	s_addc_u32 s51, s69, 0
	s_add_u32 s4, s21, s4
	s_addc_u32 s5, s39, s5
	v_lshl_add_u64 v[174:175], s[4:5], 0, v[128:129]
	s_add_i32 m0, s74, 0xc000
	ds_read_b128 v[202:205], v179
	ds_read_b128 v[206:209], v179 offset:1024
	ds_read_b128 v[210:213], v179 offset:2048
	ds_read_b128 v[214:217], v179 offset:3072
	ds_read_b128 v[218:221], v179 offset:4096
	ds_read_b128 v[222:225], v179 offset:5120
	ds_read_b128 v[226:229], v179 offset:6144
	ds_read_b128 v[230:233], v179 offset:7168
	global_load_lds_dwordx4 v[174:175], off
	v_lshl_add_u64 v[174:175], s[4:5], 0, v[132:133]
	s_add_i32 m0, s74, 0xe000
	s_nop 0
	global_load_lds_dwordx4 v[174:175], off
	s_waitcnt vmcnt(8)
	s_waitcnt lgkmcnt(0)
	s_setprio 1
	s_barrier
	v_mfma_f32_16x16x32_bf16 v[124:127], v[158:161], v[202:205], v[124:127]
	v_mfma_f32_16x16x32_bf16 v[120:123], v[166:169], v[202:205], v[120:123]
	v_mfma_f32_16x16x32_bf16 v[116:119], v[158:161], v[210:213], v[116:119]
	v_mfma_f32_16x16x32_bf16 v[112:115], v[166:169], v[210:213], v[112:115]
	v_mfma_f32_16x16x32_bf16 v[108:111], v[158:161], v[218:221], v[108:111]
	v_mfma_f32_16x16x32_bf16 v[104:107], v[166:169], v[218:221], v[104:107]
	v_mfma_f32_16x16x32_bf16 v[100:103], v[158:161], v[226:229], v[100:103]
	v_mfma_f32_16x16x32_bf16 v[96:99], v[166:169], v[226:229], v[96:99]
	v_mfma_f32_16x16x32_bf16 v[124:127], v[162:165], v[206:209], v[124:127]
	v_mfma_f32_16x16x32_bf16 v[120:123], v[170:173], v[206:209], v[120:123]
	v_mfma_f32_16x16x32_bf16 v[116:119], v[162:165], v[214:217], v[116:119]
	v_mfma_f32_16x16x32_bf16 v[112:115], v[170:173], v[214:217], v[112:115]
	v_mfma_f32_16x16x32_bf16 v[108:111], v[162:165], v[222:225], v[108:111]
	v_mfma_f32_16x16x32_bf16 v[104:107], v[170:173], v[222:225], v[104:107]
	v_mfma_f32_16x16x32_bf16 v[100:103], v[162:165], v[230:233], v[100:103]
	v_mfma_f32_16x16x32_bf16 v[96:99], v[170:173], v[230:233], v[96:99]
	s_setprio 0
	s_setprio 1
	v_mfma_f32_16x16x32_bf16 v[92:95], v[180:183], v[202:205], v[92:95]
	v_mfma_f32_16x16x32_bf16 v[88:91], v[194:197], v[202:205], v[88:91]
	v_mfma_f32_16x16x32_bf16 v[84:87], v[180:183], v[210:213], v[84:87]
	v_mfma_f32_16x16x32_bf16 v[80:83], v[194:197], v[210:213], v[80:83]
	v_mfma_f32_16x16x32_bf16 v[76:79], v[180:183], v[218:221], v[76:79]
	v_mfma_f32_16x16x32_bf16 v[72:75], v[194:197], v[218:221], v[72:75]
	v_mfma_f32_16x16x32_bf16 v[68:71], v[180:183], v[226:229], v[68:71]
	v_mfma_f32_16x16x32_bf16 v[64:67], v[194:197], v[226:229], v[64:67]
	v_mfma_f32_16x16x32_bf16 v[92:95], v[190:193], v[206:209], v[92:95]
	v_mfma_f32_16x16x32_bf16 v[88:91], v[198:201], v[206:209], v[88:91]
	v_mfma_f32_16x16x32_bf16 v[84:87], v[190:193], v[214:217], v[84:87]
	v_mfma_f32_16x16x32_bf16 v[80:83], v[198:201], v[214:217], v[80:83]
	v_mfma_f32_16x16x32_bf16 v[76:79], v[190:193], v[222:225], v[76:79]
	v_mfma_f32_16x16x32_bf16 v[72:75], v[198:201], v[222:225], v[72:75]
	v_mfma_f32_16x16x32_bf16 v[68:71], v[190:193], v[230:233], v[68:71]
	v_mfma_f32_16x16x32_bf16 v[64:67], v[198:201], v[230:233], v[64:67]
	s_barrier
	s_setprio 0
	s_add_i32 s4, s10, s71
	v_lshl_add_u64 v[174:175], s[52:53], 0, v[130:131]
	s_mov_b32 m0, s4
	ds_read_b128 v[202:205], v179 offset:16384
	ds_read_b128 v[206:209], v179 offset:17408
	ds_read_b128 v[210:213], v179 offset:18432
	ds_read_b128 v[214:217], v179 offset:19456
	ds_read_b128 v[218:221], v179 offset:20480
	ds_read_b128 v[222:225], v179 offset:21504
	ds_read_b128 v[226:229], v179 offset:22528
	ds_read_b128 v[230:233], v179 offset:23552
	global_load_lds_dwordx4 v[174:175], off
	s_add_i32 m0, s4, 0x2000
	s_add_u32 s4, s52, 0x160000
	v_lshl_add_u64 v[234:235], s[52:53], 0, v[134:135]
	s_addc_u32 s5, s53, 0
	s_add_i32 s6, s11, s71
	global_load_lds_dwordx4 v[234:235], off
	v_lshl_add_u64 v[236:237], s[4:5], 0, v[130:131]
	s_mov_b32 m0, s6
	s_nop 0
	global_load_lds_dwordx4 v[236:237], off
	v_lshl_add_u64 v[236:237], s[4:5], 0, v[134:135]
	s_add_i32 m0, s6, 0x2000
	s_nop 0
	global_load_lds_dwordx4 v[236:237], off
	v_lshl_add_u64 v[236:237], s[68:69], 0, v[128:129]
	s_mov_b32 m0, s74
	s_nop 0
	global_load_lds_dwordx4 v[236:237], off
	v_lshl_add_u64 v[236:237], s[68:69], 0, v[132:133]
	s_mov_b32 m0, s76
	s_nop 0
	global_load_lds_dwordx4 v[236:237], off
	s_nop 0
	s_waitcnt vmcnt(8)
	s_waitcnt lgkmcnt(0)
	s_setprio 1
	s_barrier
; #define PG8_STAGE(bufoff, gbase, voff) do { _Pragma("unroll") for (int _i = 0; _i < 2; ++_i) \
;         __builtin_amdgcn_global_load_lds((const unsigned*)((const char*)(gbase) + (voff)[_i]), (PG8_LAS unsigned*)(lds + (bufoff) + ldsw + _i * 8192), 16, 0, 0); } while (0)
; #define PG8_LDA(dst, b, h) do { _Pragma("unroll") for (int m = 0; m < 4; ++m) _Pragma("unroll") for (int k = 0; k < 2; ++k) dst[m][k] = *(const PG8_LAS bf16x8*)(lds + PG8_SA(b, h) + aoff + m * 2048 + k * 1024); } while (0)
; #define PG8_LDB(dst, b, h) do { _Pragma("unroll") for (int n = 0; n < 2; ++n) _Pragma("unroll") for (int k = 0; k < 2; ++k) dst[n][k] = *(const PG8_LAS bf16x8*)(lds + PG8_SB(b, h) + boff + n * 2048 + k * 1024); } while (0)
; #define PG8_MMA(ai, bj, At, Bt) do { __builtin_amdgcn_s_setprio(1); _Pragma("unroll") for (int m = 0; m < 4; ++m) _Pragma("unroll") for (int n = 0; n < 2; ++n) _Pragma("unroll") for (int k = 0; k < 2; ++k) \
;         acc[ai][bj][m][n] = __builtin_amdgcn_mfma_f32_16x16x32_bf16(Bt[n][k], At[m][k], acc[ai][bj][m][n], 0, 0, 0); __builtin_amdgcn_s_setprio(0); } while (0)
; #define PG8_WAIT_V(n) asm volatile("s_waitcnt vmcnt(" #n ")" ::: "memory")
; #define PG8_WAIT_L(n) asm volatile("s_waitcnt lgkmcnt(" #n ")" ::: "memory")
; #define PG8_BAR __builtin_amdgcn_s_barrier()
; #define PG8_SCHED __builtin_amdgcn_sched_barrier(0)
; template <class Epi, class Sched, bool ALIGN_EPI = false, bool SP2 = false>
; __device__ __forceinline__ void gemm_phase(PG8_LAS unsigned char* lds, const Gemm g, const Sched& S, const Epi& E) {
;     ...
;             PG8_WAIT_V(8); PG8_WAIT_L(0); PG8_BAR; PG8_MMA(1, 0, At, B0); PG8_MMA(1, 1, At, B1); PG8_BAR; PG8_SCHED;
;             PG8_LDB(B0, 1, 0); PG8_LDB(B1, 1, 1); PG8_SCHED; PG8_LDA(At, 1, 0); PG8_STAGE(PG8_SA(0, 1), a2 + hstepA, voffA);
;             PG8_WAIT_V(8); PG8_WAIT_L(0); PG8_BAR; PG8_MMA(0, 0, At, B0); PG8_MMA(0, 1, At, B1); PG8_BAR; PG8_SCHED;
	v_mfma_f32_16x16x32_bf16 v[60:63], v[158:161], v[202:205], v[60:63]
	v_mfma_f32_16x16x32_bf16 v[56:59], v[166:169], v[202:205], v[56:59]
	v_mfma_f32_16x16x32_bf16 v[52:55], v[158:161], v[210:213], v[52:55]
	v_mfma_f32_16x16x32_bf16 v[48:51], v[166:169], v[210:213], v[48:51]
	v_mfma_f32_16x16x32_bf16 v[44:47], v[158:161], v[218:221], v[44:47]
	v_mfma_f32_16x16x32_bf16 v[40:43], v[166:169], v[218:221], v[40:43]
	v_mfma_f32_16x16x32_bf16 v[36:39], v[158:161], v[226:229], v[36:39]
	v_mfma_f32_16x16x32_bf16 v[32:35], v[166:169], v[226:229], v[32:35]
	v_mfma_f32_16x16x32_bf16 v[60:63], v[162:165], v[206:209], v[60:63]
	v_mfma_f32_16x16x32_bf16 v[56:59], v[170:173], v[206:209], v[56:59]
	v_mfma_f32_16x16x32_bf16 v[52:55], v[162:165], v[214:217], v[52:55]
	v_mfma_f32_16x16x32_bf16 v[48:51], v[170:173], v[214:217], v[48:51]
	v_mfma_f32_16x16x32_bf16 v[44:47], v[162:165], v[222:225], v[44:47]
	v_mfma_f32_16x16x32_bf16 v[40:43], v[170:173], v[222:225], v[40:43]
	v_mfma_f32_16x16x32_bf16 v[36:39], v[162:165], v[230:233], v[36:39]
	v_mfma_f32_16x16x32_bf16 v[32:35], v[170:173], v[230:233], v[32:35]
	s_setprio 0
	s_setprio 1
	v_mfma_f32_16x16x32_bf16 v[28:31], v[180:183], v[202:205], v[28:31]
	v_mfma_f32_16x16x32_bf16 v[24:27], v[194:197], v[202:205], v[24:27]
	v_mfma_f32_16x16x32_bf16 v[20:23], v[180:183], v[210:213], v[20:23]
	v_mfma_f32_16x16x32_bf16 v[16:19], v[194:197], v[210:213], v[16:19]
	v_mfma_f32_16x16x32_bf16 v[12:15], v[180:183], v[218:221], v[12:15]
	v_mfma_f32_16x16x32_bf16 v[8:11], v[194:197], v[218:221], v[8:11]
	v_mfma_f32_16x16x32_bf16 v[4:7], v[180:183], v[226:229], v[4:7]
	v_mfma_f32_16x16x32_bf16 v[0:3], v[194:197], v[226:229], v[0:3]
	v_mfma_f32_16x16x32_bf16 v[28:31], v[190:193], v[206:209], v[28:31]
	v_mfma_f32_16x16x32_bf16 v[24:27], v[198:201], v[206:209], v[24:27]
	v_mfma_f32_16x16x32_bf16 v[20:23], v[190:193], v[214:217], v[20:23]
	v_mfma_f32_16x16x32_bf16 v[16:19], v[198:201], v[214:217], v[16:19]
	v_mfma_f32_16x16x32_bf16 v[12:15], v[190:193], v[222:225], v[12:15]
	v_mfma_f32_16x16x32_bf16 v[8:11], v[198:201], v[222:225], v[8:11]
	v_mfma_f32_16x16x32_bf16 v[4:7], v[190:193], v[230:233], v[4:7]
	v_mfma_f32_16x16x32_bf16 v[0:3], v[198:201], v[230:233], v[0:3]
	s_barrier
	s_setprio 0
	s_add_i32 s6, 0, 0x18000
	s_add_i32 s7, 0, 0x1c000
	v_add_u32_e32 v170, s6, v177
	v_add_u32_e32 v198, s7, v177
	ds_read_b128 v[158:161], v170
	ds_read_b128 v[162:165], v170 offset:1024
	ds_read_b128 v[166:169], v170 offset:2048
	ds_read_b128 v[170:173], v170 offset:3072
	ds_read_b128 v[180:183], v198
	ds_read_b128 v[190:193], v198 offset:1024
	ds_read_b128 v[194:197], v198 offset:2048
	ds_read_b128 v[198:201], v198 offset:3072
	s_add_u32 s4, s68, 0x4000
	s_addc_u32 s5, s69, 0
	s_mov_b32 m0, s77
	v_lshl_add_u64 v[236:237], s[4:5], 0, v[128:129]
	ds_read_b128 v[202:205], v179 offset:32768
	ds_read_b128 v[206:209], v179 offset:33792
	ds_read_b128 v[210:213], v179 offset:34816
	ds_read_b128 v[214:217], v179 offset:35840
	ds_read_b128 v[218:221], v179 offset:36864
	ds_read_b128 v[222:225], v179 offset:37888
	ds_read_b128 v[226:229], v179 offset:38912
	ds_read_b128 v[230:233], v179 offset:39936
	global_load_lds_dwordx4 v[236:237], off
	v_lshl_add_u64 v[236:237], s[4:5], 0, v[132:133]
	s_mov_b32 m0, s75
	s_nop 0
	global_load_lds_dwordx4 v[236:237], off
	s_waitcnt vmcnt(8)
	s_waitcnt lgkmcnt(0)
	s_setprio 1
	s_barrier
	v_mfma_f32_16x16x32_bf16 v[124:127], v[158:161], v[202:205], v[124:127]
	v_mfma_f32_16x16x32_bf16 v[120:123], v[166:169], v[202:205], v[120:123]
	v_mfma_f32_16x16x32_bf16 v[116:119], v[158:161], v[210:213], v[116:119]
	v_mfma_f32_16x16x32_bf16 v[112:115], v[166:169], v[210:213], v[112:115]
	v_mfma_f32_16x16x32_bf16 v[108:111], v[158:161], v[218:221], v[108:111]
	v_mfma_f32_16x16x32_bf16 v[104:107], v[166:169], v[218:221], v[104:107]
	v_mfma_f32_16x16x32_bf16 v[100:103], v[158:161], v[226:229], v[100:103]
	v_mfma_f32_16x16x32_bf16 v[96:99], v[166:169], v[226:229], v[96:99]
	v_mfma_f32_16x16x32_bf16 v[124:127], v[162:165], v[206:209], v[124:127]
	v_mfma_f32_16x16x32_bf16 v[120:123], v[170:173], v[206:209], v[120:123]
	v_mfma_f32_16x16x32_bf16 v[116:119], v[162:165], v[214:217], v[116:119]
	v_mfma_f32_16x16x32_bf16 v[112:115], v[170:173], v[214:217], v[112:115]
	v_mfma_f32_16x16x32_bf16 v[108:111], v[162:165], v[222:225], v[108:111]
	v_mfma_f32_16x16x32_bf16 v[104:107], v[170:173], v[222:225], v[104:107]
	v_mfma_f32_16x16x32_bf16 v[100:103], v[162:165], v[230:233], v[100:103]
	v_mfma_f32_16x16x32_bf16 v[96:99], v[170:173], v[230:233], v[96:99]
	s_setprio 0
	s_setprio 1
	v_mfma_f32_16x16x32_bf16 v[92:95], v[180:183], v[202:205], v[92:95]
	v_mfma_f32_16x16x32_bf16 v[88:91], v[194:197], v[202:205], v[88:91]
	v_mfma_f32_16x16x32_bf16 v[84:87], v[180:183], v[210:213], v[84:87]
	v_mfma_f32_16x16x32_bf16 v[80:83], v[194:197], v[210:213], v[80:83]
	v_mfma_f32_16x16x32_bf16 v[76:79], v[180:183], v[218:221], v[76:79]
	v_mfma_f32_16x16x32_bf16 v[72:75], v[194:197], v[218:221], v[72:75]
	v_mfma_f32_16x16x32_bf16 v[68:71], v[180:183], v[226:229], v[68:71]
	v_mfma_f32_16x16x32_bf16 v[64:67], v[194:197], v[226:229], v[64:67]
	v_mfma_f32_16x16x32_bf16 v[92:95], v[190:193], v[206:209], v[92:95]
	v_mfma_f32_16x16x32_bf16 v[88:91], v[198:201], v[206:209], v[88:91]
	v_mfma_f32_16x16x32_bf16 v[84:87], v[190:193], v[214:217], v[84:87]
	v_mfma_f32_16x16x32_bf16 v[80:83], v[198:201], v[214:217], v[80:83]
	v_mfma_f32_16x16x32_bf16 v[76:79], v[190:193], v[222:225], v[76:79]
	v_mfma_f32_16x16x32_bf16 v[72:75], v[198:201], v[222:225], v[72:75]
	v_mfma_f32_16x16x32_bf16 v[68:71], v[190:193], v[230:233], v[68:71]
	v_mfma_f32_16x16x32_bf16 v[64:67], v[198:201], v[230:233], v[64:67]
	s_barrier
; #define PG8_STAGE(bufoff, gbase, voff) do { _Pragma("unroll") for (int _i = 0; _i < 2; ++_i) \
;         __builtin_amdgcn_global_load_lds((const unsigned*)((const char*)(gbase) + (voff)[_i]), (PG8_LAS unsigned*)(lds + (bufoff) + ldsw + _i * 8192), 16, 0, 0); } while (0)
; #define PG8_LDA(dst, b, h) do { _Pragma("unroll") for (int m = 0; m < 4; ++m) _Pragma("unroll") for (int k = 0; k < 2; ++k) dst[m][k] = *(const PG8_LAS bf16x8*)(lds + PG8_SA(b, h) + aoff + m * 2048 + k * 1024); } while (0)
; #define PG8_MMA(ai, bj, At, Bt) do { __builtin_amdgcn_s_setprio(1); _Pragma("unroll") for (int m = 0; m < 4; ++m) _Pragma("unroll") for (int n = 0; n < 2; ++n) _Pragma("unroll") for (int k = 0; k < 2; ++k) \
;         acc[ai][bj][m][n] = __builtin_amdgcn_mfma_f32_16x16x32_bf16(Bt[n][k], At[m][k], acc[ai][bj][m][n], 0, 0, 0); __builtin_amdgcn_s_setprio(0); } while (0)
; #define PG8_WAIT_V(n) asm volatile("s_waitcnt vmcnt(" #n ")" ::: "memory")
; #define PG8_WAIT_L(n) asm volatile("s_waitcnt lgkmcnt(" #n ")" ::: "memory")
; #define PG8_BAR __builtin_amdgcn_s_barrier()
; #define PG8_SCHED __builtin_amdgcn_sched_barrier(0)
; template <class Epi, class Sched, bool ALIGN_EPI = false, bool SP2 = false>
; __device__ __forceinline__ void gemm_phase(PG8_LAS unsigned char* lds, const Gemm g, const Sched& S, const Epi& E) {
;     ...
;             PG8_LDA(At, 1, 1); PG8_STAGE(PG8_SB(1, 0), b3, voffB); PG8_STAGE(PG8_SB(1, 1), b3 + hstepB, voffB); PG8_STAGE(PG8_SA(1, 0), a3, voffA);
;             PG8_WAIT_V(8); PG8_WAIT_L(0); PG8_BAR; PG8_MMA(1, 0, At, B0); PG8_MMA(1, 1, At, B1); PG8_BAR; PG8_SCHED;
	s_setprio 0
	s_add_i32 s4, s6, s71
	v_lshl_add_u64 v[174:175], v[174:175], 0, s[54:55]
	s_mov_b32 m0, s4
	ds_read_b128 v[202:205], v179 offset:49152
	ds_read_b128 v[206:209], v179 offset:50176
	ds_read_b128 v[210:213], v179 offset:51200
	ds_read_b128 v[214:217], v179 offset:52224
	ds_read_b128 v[218:221], v179 offset:53248
	ds_read_b128 v[222:225], v179 offset:54272
	ds_read_b128 v[226:229], v179 offset:55296
	ds_read_b128 v[230:233], v179 offset:56320
	global_load_lds_dwordx4 v[174:175], off
	s_add_i32 m0, s4, 0x2000
	s_add_u32 s4, s52, 0x160080
	v_lshl_add_u64 v[174:175], v[234:235], 0, s[54:55]
	s_addc_u32 s5, s53, 0
	s_add_i32 s6, s7, s71
	global_load_lds_dwordx4 v[174:175], off
	v_lshl_add_u64 v[174:175], s[4:5], 0, v[130:131]
	s_mov_b32 m0, s6
	s_nop 0
	global_load_lds_dwordx4 v[174:175], off
	v_lshl_add_u64 v[174:175], s[4:5], 0, v[134:135]
	s_add_i32 m0, s6, 0x2000
	s_nop 0
	global_load_lds_dwordx4 v[174:175], off
	v_lshl_add_u64 v[174:175], s[50:51], 0, v[128:129]
	s_mov_b32 m0, s95
	s_nop 0
	global_load_lds_dwordx4 v[174:175], off
	v_lshl_add_u64 v[174:175], s[50:51], 0, v[132:133]
	s_mov_b32 m0, s96
	s_nop 0
	global_load_lds_dwordx4 v[174:175], off
	s_nop 0
	s_waitcnt vmcnt(8)
	s_waitcnt lgkmcnt(0)
	s_setprio 1
	s_barrier
	v_mfma_f32_16x16x32_bf16 v[60:63], v[158:161], v[202:205], v[60:63]
	v_mfma_f32_16x16x32_bf16 v[56:59], v[166:169], v[202:205], v[56:59]
	v_mfma_f32_16x16x32_bf16 v[52:55], v[158:161], v[210:213], v[52:55]
	v_mfma_f32_16x16x32_bf16 v[48:51], v[166:169], v[210:213], v[48:51]
	v_mfma_f32_16x16x32_bf16 v[44:47], v[158:161], v[218:221], v[44:47]
	v_mfma_f32_16x16x32_bf16 v[40:43], v[166:169], v[218:221], v[40:43]
	v_mfma_f32_16x16x32_bf16 v[36:39], v[158:161], v[226:229], v[36:39]
	v_mfma_f32_16x16x32_bf16 v[32:35], v[166:169], v[226:229], v[32:35]
	v_mfma_f32_16x16x32_bf16 v[60:63], v[162:165], v[206:209], v[60:63]
	v_mfma_f32_16x16x32_bf16 v[56:59], v[170:173], v[206:209], v[56:59]
	v_mfma_f32_16x16x32_bf16 v[52:55], v[162:165], v[214:217], v[52:55]
	v_mfma_f32_16x16x32_bf16 v[48:51], v[170:173], v[214:217], v[48:51]
	v_mfma_f32_16x16x32_bf16 v[44:47], v[162:165], v[222:225], v[44:47]
	v_mfma_f32_16x16x32_bf16 v[40:43], v[170:173], v[222:225], v[40:43]
	v_mfma_f32_16x16x32_bf16 v[36:39], v[162:165], v[230:233], v[36:39]
	v_mfma_f32_16x16x32_bf16 v[32:35], v[170:173], v[230:233], v[32:35]
	s_setprio 0
	s_setprio 1
	v_mfma_f32_16x16x32_bf16 v[28:31], v[180:183], v[202:205], v[28:31]
	v_mfma_f32_16x16x32_bf16 v[24:27], v[194:197], v[202:205], v[24:27]
	v_mfma_f32_16x16x32_bf16 v[20:23], v[180:183], v[210:213], v[20:23]
	v_mfma_f32_16x16x32_bf16 v[16:19], v[194:197], v[210:213], v[16:19]
	v_mfma_f32_16x16x32_bf16 v[12:15], v[180:183], v[218:221], v[12:15]
	v_mfma_f32_16x16x32_bf16 v[8:11], v[194:197], v[218:221], v[8:11]
	v_mfma_f32_16x16x32_bf16 v[4:7], v[180:183], v[226:229], v[4:7]
	v_mfma_f32_16x16x32_bf16 v[0:3], v[194:197], v[226:229], v[0:3]
	v_mfma_f32_16x16x32_bf16 v[28:31], v[190:193], v[206:209], v[28:31]
	v_mfma_f32_16x16x32_bf16 v[24:27], v[198:201], v[206:209], v[24:27]
	v_mfma_f32_16x16x32_bf16 v[20:23], v[190:193], v[214:217], v[20:23]
	v_mfma_f32_16x16x32_bf16 v[16:19], v[198:201], v[214:217], v[16:19]
	v_mfma_f32_16x16x32_bf16 v[12:15], v[190:193], v[222:225], v[12:15]
	v_mfma_f32_16x16x32_bf16 v[8:11], v[198:201], v[222:225], v[8:11]
	v_mfma_f32_16x16x32_bf16 v[4:7], v[190:193], v[230:233], v[4:7]
	v_mfma_f32_16x16x32_bf16 v[0:3], v[198:201], v[230:233], v[0:3]
	s_barrier
	s_setprio 0
	s_cmp_ge_i32 s62, s97
	s_cbranch_scc1 .LBB0_1766

; #define PG8_STAGE(bufoff, gbase, voff) do { _Pragma("unroll") for (int _i = 0; _i < 2; ++_i) \
;         __builtin_amdgcn_global_load_lds((const unsigned*)((const char*)(gbase) + (voff)[_i]), (PG8_LAS unsigned*)(lds + (bufoff) + ldsw + _i * 8192), 16, 0, 0); } while (0)
; #define PG8_LDA(dst, b, h) do { _Pragma("unroll") for (int m = 0; m < 4; ++m) _Pragma("unroll") for (int k = 0; k < 2; ++k) dst[m][k] = *(const PG8_LAS bf16x8*)(lds + PG8_SA(b, h) + aoff + m * 2048 + k * 1024); } while (0)
; #define PG8_LDB(dst, b, h) do { _Pragma("unroll") for (int n = 0; n < 2; ++n) _Pragma("unroll") for (int k = 0; k < 2; ++k) dst[n][k] = *(const PG8_LAS bf16x8*)(lds + PG8_SB(b, h) + boff + n * 2048 + k * 1024); } while (0)
; #define PG8_WAIT_V(n) asm volatile("s_waitcnt vmcnt(" #n ")" ::: "memory")
; template <class Epi, class Sched, bool ALIGN_EPI = false, bool SP2 = false>
; __device__ __forceinline__ void gemm_phase(PG8_LAS unsigned char* lds, const Gemm g, const Sched& S, const Epi& E) {
;     ...
;             const char* a1 = cA + (size_t)(t + 1) * kstA;
;             const char* a2 = last ? nA : cA + (size_t)(t + 2) * kstA; const char* b2 = last ? nB : cB + (size_t)(t + 2) * kstep;
;             const char* a3 = a2 + kstA; const char* b3 = b2 + kstep;
;             if (last && has_next) S.a_ready(nxt);
;             if constexpr (SP2) {
;             PG8_LDB(B0, 0, 0); PG8_LDB(B1, 0, 1); PG8_SCHED; PG8_LDA(At, 0, 0); PG8_STAGE(PG8_SA(1, 1), a1 + hstepA, voffA);
;             PG8_WAIT_V(8); PG8_WAIT_L(0); PG8_BAR; PG8_MMA(0, 0, At, B0); PG8_MMA(0, 1, At, B1); PG8_BAR; PG8_SCHED;
;             PG8_LDA(At, 0, 1); PG8_STAGE(PG8_SB(0, 0), b2, voffB); PG8_STAGE(PG8_SB(0, 1), b2 + hstepB, voffB); PG8_STAGE(PG8_SA(0, 0), a2, voffA);
;             PG8_WAIT_V(8); PG8_WAIT_L(0); PG8_BAR; PG8_MMA(1, 0, At, B0); PG8_MMA(1, 1, At, B1); PG8_BAR; PG8_SCHED;
;             PG8_LDB(B0, 1, 0); PG8_LDB(B1, 1, 1); PG8_SCHED; PG8_LDA(At, 1, 0); PG8_STAGE(PG8_SA(0, 1), a2 + hstepA, voffA);
;             PG8_WAIT_V(8); PG8_WAIT_L(0); PG8_BAR; PG8_MMA(0, 0, At, B0); PG8_MMA(0, 1, At, B1); PG8_BAR; PG8_SCHED;
;             PG8_LDA(At, 1, 1); PG8_STAGE(PG8_SB(1, 0), b3, voffB); PG8_STAGE(PG8_SB(1, 1), b3 + hstepB, voffB); PG8_STAGE(PG8_SA(1, 0), a3, voffA);
;             PG8_WAIT_V(8); PG8_WAIT_L(0); PG8_BAR; PG8_MMA(1, 0, At, B0); PG8_MMA(1, 1, At, B1); PG8_BAR; PG8_SCHED;
.LBB0_2050:
	ds_read_b128 v[128:131], v159
	ds_read_b128 v[132:135], v159 offset:1024
	ds_read_b128 v[164:167], v159 offset:2048
	ds_read_b128 v[168:171], v159 offset:3072
	ds_read_b128 v[172:175], v160
	ds_read_b128 v[176:179], v160 offset:1024
	ds_read_b128 v[180:183], v160 offset:2048
	ds_read_b128 v[190:193], v160 offset:3072
	s_add_u32 s13, s20, 0xfff80080
	s_addc_u32 s33, s21, -1
	s_cmp_eq_u32 s12, 28
	s_cselect_b32 s41, s1, s33
	s_cselect_b32 s40, s3, s13
	s_cselect_b32 s39, s4, s11
	s_cselect_b32 s38, s5, s10
	v_lshl_add_u64 v[226:227], s[20:21], 0, v[148:149]
	s_add_i32 m0, s7, 0xc000
	ds_read_b128 v[194:197], v161
	ds_read_b128 v[198:201], v161 offset:1024
	ds_read_b128 v[202:205], v161 offset:2048
	ds_read_b128 v[206:209], v161 offset:3072
	ds_read_b128 v[210:213], v161 offset:4096
	ds_read_b128 v[214:217], v161 offset:5120
	ds_read_b128 v[218:221], v161 offset:6144
	ds_read_b128 v[222:225], v161 offset:7168
	global_load_lds_dwordx4 v[226:227], off
	v_lshl_add_u64 v[226:227], s[20:21], 0, v[150:151]
	s_add_i32 m0, s7, 0xe000
	s_nop 0
	global_load_lds_dwordx4 v[226:227], off
	s_waitcnt vmcnt(8)
	s_waitcnt lgkmcnt(0)
	s_setprio 1
	s_barrier
	v_mfma_f32_16x16x32_bf16 v[124:127], v[128:131], v[194:197], v[124:127]
	v_mfma_f32_16x16x32_bf16 v[120:123], v[164:167], v[194:197], v[120:123]
	v_mfma_f32_16x16x32_bf16 v[108:111], v[128:131], v[202:205], v[108:111]
	v_mfma_f32_16x16x32_bf16 v[104:107], v[164:167], v[202:205], v[104:107]
	v_mfma_f32_16x16x32_bf16 v[92:95], v[128:131], v[210:213], v[92:95]
	v_mfma_f32_16x16x32_bf16 v[88:91], v[164:167], v[210:213], v[88:91]
	v_mfma_f32_16x16x32_bf16 v[76:79], v[128:131], v[218:221], v[76:79]
	v_mfma_f32_16x16x32_bf16 v[72:75], v[164:167], v[218:221], v[72:75]
	v_mfma_f32_16x16x32_bf16 v[124:127], v[132:135], v[198:201], v[124:127]
	v_mfma_f32_16x16x32_bf16 v[120:123], v[168:171], v[198:201], v[120:123]
	v_mfma_f32_16x16x32_bf16 v[108:111], v[132:135], v[206:209], v[108:111]
	v_mfma_f32_16x16x32_bf16 v[104:107], v[168:171], v[206:209], v[104:107]
	v_mfma_f32_16x16x32_bf16 v[92:95], v[132:135], v[214:217], v[92:95]
	v_mfma_f32_16x16x32_bf16 v[88:91], v[168:171], v[214:217], v[88:91]
	v_mfma_f32_16x16x32_bf16 v[76:79], v[132:135], v[222:225], v[76:79]
	v_mfma_f32_16x16x32_bf16 v[72:75], v[168:171], v[222:225], v[72:75]
	s_setprio 0
	s_setprio 1
	v_mfma_f32_16x16x32_bf16 v[116:119], v[172:175], v[194:197], v[116:119]
	v_mfma_f32_16x16x32_bf16 v[112:115], v[180:183], v[194:197], v[112:115]
	v_mfma_f32_16x16x32_bf16 v[100:103], v[172:175], v[202:205], v[100:103]
	v_mfma_f32_16x16x32_bf16 v[96:99], v[180:183], v[202:205], v[96:99]
	v_mfma_f32_16x16x32_bf16 v[84:87], v[172:175], v[210:213], v[84:87]
	v_mfma_f32_16x16x32_bf16 v[80:83], v[180:183], v[210:213], v[80:83]
	v_mfma_f32_16x16x32_bf16 v[68:71], v[172:175], v[218:221], v[68:71]
	v_mfma_f32_16x16x32_bf16 v[64:67], v[180:183], v[218:221], v[64:67]
	v_mfma_f32_16x16x32_bf16 v[116:119], v[176:179], v[198:201], v[116:119]
	v_mfma_f32_16x16x32_bf16 v[112:115], v[190:193], v[198:201], v[112:115]
	v_mfma_f32_16x16x32_bf16 v[100:103], v[176:179], v[206:209], v[100:103]
	v_mfma_f32_16x16x32_bf16 v[96:99], v[190:193], v[206:209], v[96:99]
	v_mfma_f32_16x16x32_bf16 v[84:87], v[176:179], v[214:217], v[84:87]
	v_mfma_f32_16x16x32_bf16 v[80:83], v[190:193], v[214:217], v[80:83]
	v_mfma_f32_16x16x32_bf16 v[68:71], v[176:179], v[222:225], v[68:71]
	v_mfma_f32_16x16x32_bf16 v[64:67], v[190:193], v[222:225], v[64:67]
	s_barrier
	s_setprio 0
	s_add_i32 s13, s69, s6
	v_lshl_add_u64 v[226:227], s[38:39], 0, v[138:139]
	s_mov_b32 m0, s13
	ds_read_b128 v[194:197], v161 offset:16384
	ds_read_b128 v[198:201], v161 offset:17408
	ds_read_b128 v[202:205], v161 offset:18432
	ds_read_b128 v[206:209], v161 offset:19456
	ds_read_b128 v[210:213], v161 offset:20480
	ds_read_b128 v[214:217], v161 offset:21504
	ds_read_b128 v[218:221], v161 offset:22528
	ds_read_b128 v[222:225], v161 offset:23552
	global_load_lds_dwordx4 v[226:227], off
	s_add_i32 m0, s13, 0x2000
	s_add_u32 s44, s38, 0x80000
	v_lshl_add_u64 v[228:229], s[38:39], 0, v[142:143]
	s_addc_u32 s45, s39, 0
	s_add_i32 s13, s70, s6
	global_load_lds_dwordx4 v[228:229], off
	v_lshl_add_u64 v[230:231], s[44:45], 0, v[138:139]
	s_mov_b32 m0, s13
	v_lshl_add_u64 v[232:233], s[40:41], 0, v[140:141]
	global_load_lds_dwordx4 v[230:231], off
	v_lshl_add_u64 v[230:231], s[44:45], 0, v[142:143]
	s_add_i32 m0, s13, 0x2000
	s_nop 0
	global_load_lds_dwordx4 v[230:231], off
	v_lshl_add_u64 v[230:231], s[40:41], 0, v[136:137]
	s_mov_b32 m0, s7
	s_nop 0
	global_load_lds_dwordx4 v[230:231], off
	s_mov_b32 m0, s8
	s_nop 0
	global_load_lds_dwordx4 v[232:233], off
	s_waitcnt vmcnt(8)
	s_waitcnt lgkmcnt(0)
	s_setprio 1
	s_barrier
; #define PG8_STAGE(bufoff, gbase, voff) do { _Pragma("unroll") for (int _i = 0; _i < 2; ++_i) \
;         __builtin_amdgcn_global_load_lds((const unsigned*)((const char*)(gbase) + (voff)[_i]), (PG8_LAS unsigned*)(lds + (bufoff) + ldsw + _i * 8192), 16, 0, 0); } while (0)
; #define PG8_LDA(dst, b, h) do { _Pragma("unroll") for (int m = 0; m < 4; ++m) _Pragma("unroll") for (int k = 0; k < 2; ++k) dst[m][k] = *(const PG8_LAS bf16x8*)(lds + PG8_SA(b, h) + aoff + m * 2048 + k * 1024); } while (0)
; #define PG8_LDB(dst, b, h) do { _Pragma("unroll") for (int n = 0; n < 2; ++n) _Pragma("unroll") for (int k = 0; k < 2; ++k) dst[n][k] = *(const PG8_LAS bf16x8*)(lds + PG8_SB(b, h) + boff + n * 2048 + k * 1024); } while (0)
; #define PG8_MMA(ai, bj, At, Bt) do { __builtin_amdgcn_s_setprio(1); _Pragma("unroll") for (int m = 0; m < 4; ++m) _Pragma("unroll") for (int n = 0; n < 2; ++n) _Pragma("unroll") for (int k = 0; k < 2; ++k) \
;         acc[ai][bj][m][n] = __builtin_amdgcn_mfma_f32_16x16x32_bf16(Bt[n][k], At[m][k], acc[ai][bj][m][n], 0, 0, 0); __builtin_amdgcn_s_setprio(0); } while (0)
; #define PG8_WAIT_V(n) asm volatile("s_waitcnt vmcnt(" #n ")" ::: "memory")
; #define PG8_WAIT_L(n) asm volatile("s_waitcnt lgkmcnt(" #n ")" ::: "memory")
; #define PG8_BAR __builtin_amdgcn_s_barrier()
; #define PG8_SCHED __builtin_amdgcn_sched_barrier(0)
; template <class Epi, class Sched, bool ALIGN_EPI = false, bool SP2 = false>
; __device__ __forceinline__ void gemm_phase(PG8_LAS unsigned char* lds, const Gemm g, const Sched& S, const Epi& E) {
;     ...
;             PG8_WAIT_V(8); PG8_WAIT_L(0); PG8_BAR; PG8_MMA(1, 0, At, B0); PG8_MMA(1, 1, At, B1); PG8_BAR; PG8_SCHED;
;             PG8_LDB(B0, 1, 0); PG8_LDB(B1, 1, 1); PG8_SCHED; PG8_LDA(At, 1, 0); PG8_STAGE(PG8_SA(0, 1), a2 + hstepA, voffA);
;             PG8_WAIT_V(8); PG8_WAIT_L(0); PG8_BAR; PG8_MMA(0, 0, At, B0); PG8_MMA(0, 1, At, B1); PG8_BAR; PG8_SCHED;
	v_mfma_f32_16x16x32_bf16 v[60:63], v[128:131], v[194:197], v[60:63]
	v_mfma_f32_16x16x32_bf16 v[56:59], v[164:167], v[194:197], v[56:59]
	v_mfma_f32_16x16x32_bf16 v[44:47], v[128:131], v[202:205], v[44:47]
	v_mfma_f32_16x16x32_bf16 v[40:43], v[164:167], v[202:205], v[40:43]
	v_mfma_f32_16x16x32_bf16 v[28:31], v[128:131], v[210:213], v[28:31]
	v_mfma_f32_16x16x32_bf16 v[24:27], v[164:167], v[210:213], v[24:27]
	v_mfma_f32_16x16x32_bf16 v[12:15], v[128:131], v[218:221], v[12:15]
	v_mfma_f32_16x16x32_bf16 v[8:11], v[164:167], v[218:221], v[8:11]
	v_mfma_f32_16x16x32_bf16 v[60:63], v[132:135], v[198:201], v[60:63]
	v_mfma_f32_16x16x32_bf16 v[56:59], v[168:171], v[198:201], v[56:59]
	v_mfma_f32_16x16x32_bf16 v[44:47], v[132:135], v[206:209], v[44:47]
	v_mfma_f32_16x16x32_bf16 v[40:43], v[168:171], v[206:209], v[40:43]
	v_mfma_f32_16x16x32_bf16 v[28:31], v[132:135], v[214:217], v[28:31]
	v_mfma_f32_16x16x32_bf16 v[24:27], v[168:171], v[214:217], v[24:27]
	v_mfma_f32_16x16x32_bf16 v[12:15], v[132:135], v[222:225], v[12:15]
	v_mfma_f32_16x16x32_bf16 v[8:11], v[168:171], v[222:225], v[8:11]
	s_setprio 0
	s_setprio 1
	v_mfma_f32_16x16x32_bf16 v[52:55], v[172:175], v[194:197], v[52:55]
	v_mfma_f32_16x16x32_bf16 v[48:51], v[180:183], v[194:197], v[48:51]
	v_mfma_f32_16x16x32_bf16 v[36:39], v[172:175], v[202:205], v[36:39]
	v_mfma_f32_16x16x32_bf16 v[32:35], v[180:183], v[202:205], v[32:35]
	v_mfma_f32_16x16x32_bf16 v[20:23], v[172:175], v[210:213], v[20:23]
	v_mfma_f32_16x16x32_bf16 v[16:19], v[180:183], v[210:213], v[16:19]
	v_mfma_f32_16x16x32_bf16 v[4:7], v[172:175], v[218:221], v[4:7]
	v_mfma_f32_16x16x32_bf16 v[0:3], v[180:183], v[218:221], v[0:3]
	v_mfma_f32_16x16x32_bf16 v[52:55], v[176:179], v[198:201], v[52:55]
	v_mfma_f32_16x16x32_bf16 v[48:51], v[190:193], v[198:201], v[48:51]
	v_mfma_f32_16x16x32_bf16 v[36:39], v[176:179], v[206:209], v[36:39]
	v_mfma_f32_16x16x32_bf16 v[32:35], v[190:193], v[206:209], v[32:35]
	v_mfma_f32_16x16x32_bf16 v[20:23], v[176:179], v[214:217], v[20:23]
	v_mfma_f32_16x16x32_bf16 v[16:19], v[190:193], v[214:217], v[16:19]
	v_mfma_f32_16x16x32_bf16 v[4:7], v[176:179], v[222:225], v[4:7]
	v_mfma_f32_16x16x32_bf16 v[0:3], v[190:193], v[222:225], v[0:3]
	s_barrier
	s_setprio 0
	s_add_i32 s13, 0, 0x18000
	v_add_u32_e32 v144, s13, v157
	s_add_i32 s33, 0, 0x1c000
	ds_read_b128 v[128:131], v144
	ds_read_b128 v[132:135], v144 offset:1024
	ds_read_b128 v[164:167], v144 offset:2048
	ds_read_b128 v[168:171], v144 offset:3072
	v_add_u32_e32 v144, s33, v157
	ds_read_b128 v[172:175], v144
	ds_read_b128 v[176:179], v144 offset:1024
	ds_read_b128 v[180:183], v144 offset:2048
	ds_read_b128 v[190:193], v144 offset:3072
	s_add_u32 s40, s40, 0x80000
	s_addc_u32 s41, s41, 0
	s_mov_b32 m0, s9
	v_lshl_add_u64 v[234:235], s[40:41], 0, v[136:137]
	ds_read_b128 v[194:197], v161 offset:32768
	ds_read_b128 v[198:201], v161 offset:33792
	ds_read_b128 v[202:205], v161 offset:34816
	ds_read_b128 v[206:209], v161 offset:35840
	ds_read_b128 v[210:213], v161 offset:36864
	ds_read_b128 v[214:217], v161 offset:37888
	ds_read_b128 v[218:221], v161 offset:38912
	ds_read_b128 v[222:225], v161 offset:39936
	global_load_lds_dwordx4 v[234:235], off
	v_lshl_add_u64 v[234:235], s[40:41], 0, v[140:141]
	s_mov_b32 m0, s35
	s_nop 0
	global_load_lds_dwordx4 v[234:235], off
	s_waitcnt vmcnt(8)
	s_waitcnt lgkmcnt(0)
	s_setprio 1
	s_barrier
	v_mfma_f32_16x16x32_bf16 v[124:127], v[128:131], v[194:197], v[124:127]
	v_mfma_f32_16x16x32_bf16 v[120:123], v[164:167], v[194:197], v[120:123]
	v_mfma_f32_16x16x32_bf16 v[108:111], v[128:131], v[202:205], v[108:111]
	v_mfma_f32_16x16x32_bf16 v[104:107], v[164:167], v[202:205], v[104:107]
	v_mfma_f32_16x16x32_bf16 v[92:95], v[128:131], v[210:213], v[92:95]
	v_mfma_f32_16x16x32_bf16 v[88:91], v[164:167], v[210:213], v[88:91]
	v_mfma_f32_16x16x32_bf16 v[76:79], v[128:131], v[218:221], v[76:79]
	v_mfma_f32_16x16x32_bf16 v[72:75], v[164:167], v[218:221], v[72:75]
	v_mfma_f32_16x16x32_bf16 v[124:127], v[132:135], v[198:201], v[124:127]
	v_mfma_f32_16x16x32_bf16 v[120:123], v[168:171], v[198:201], v[120:123]
	v_mfma_f32_16x16x32_bf16 v[108:111], v[132:135], v[206:209], v[108:111]
	v_mfma_f32_16x16x32_bf16 v[104:107], v[168:171], v[206:209], v[104:107]
	v_mfma_f32_16x16x32_bf16 v[92:95], v[132:135], v[214:217], v[92:95]
	v_mfma_f32_16x16x32_bf16 v[88:91], v[168:171], v[214:217], v[88:91]
	v_mfma_f32_16x16x32_bf16 v[76:79], v[132:135], v[222:225], v[76:79]
	v_mfma_f32_16x16x32_bf16 v[72:75], v[168:171], v[222:225], v[72:75]
	s_setprio 0
	s_setprio 1
	v_mfma_f32_16x16x32_bf16 v[116:119], v[172:175], v[194:197], v[116:119]
	v_mfma_f32_16x16x32_bf16 v[112:115], v[180:183], v[194:197], v[112:115]
	v_mfma_f32_16x16x32_bf16 v[100:103], v[172:175], v[202:205], v[100:103]
	v_mfma_f32_16x16x32_bf16 v[96:99], v[180:183], v[202:205], v[96:99]
	v_mfma_f32_16x16x32_bf16 v[84:87], v[172:175], v[210:213], v[84:87]
	v_mfma_f32_16x16x32_bf16 v[80:83], v[180:183], v[210:213], v[80:83]
	v_mfma_f32_16x16x32_bf16 v[68:71], v[172:175], v[218:221], v[68:71]
	v_mfma_f32_16x16x32_bf16 v[64:67], v[180:183], v[218:221], v[64:67]
	v_mfma_f32_16x16x32_bf16 v[116:119], v[176:179], v[198:201], v[116:119]
	v_mfma_f32_16x16x32_bf16 v[112:115], v[190:193], v[198:201], v[112:115]
	v_mfma_f32_16x16x32_bf16 v[100:103], v[176:179], v[206:209], v[100:103]
	v_mfma_f32_16x16x32_bf16 v[96:99], v[190:193], v[206:209], v[96:99]
	v_mfma_f32_16x16x32_bf16 v[84:87], v[176:179], v[214:217], v[84:87]
	v_mfma_f32_16x16x32_bf16 v[80:83], v[190:193], v[214:217], v[80:83]
	v_mfma_f32_16x16x32_bf16 v[68:71], v[176:179], v[222:225], v[68:71]
	v_mfma_f32_16x16x32_bf16 v[64:67], v[190:193], v[222:225], v[64:67]
	s_barrier
; #define PG8_STAGE(bufoff, gbase, voff) do { _Pragma("unroll") for (int _i = 0; _i < 2; ++_i) \
;         __builtin_amdgcn_global_load_lds((const unsigned*)((const char*)(gbase) + (voff)[_i]), (PG8_LAS unsigned*)(lds + (bufoff) + ldsw + _i * 8192), 16, 0, 0); } while (0)
; #define PG8_LDA(dst, b, h) do { _Pragma("unroll") for (int m = 0; m < 4; ++m) _Pragma("unroll") for (int k = 0; k < 2; ++k) dst[m][k] = *(const PG8_LAS bf16x8*)(lds + PG8_SA(b, h) + aoff + m * 2048 + k * 1024); } while (0)
; #define PG8_MMA(ai, bj, At, Bt) do { __builtin_amdgcn_s_setprio(1); _Pragma("unroll") for (int m = 0; m < 4; ++m) _Pragma("unroll") for (int n = 0; n < 2; ++n) _Pragma("unroll") for (int k = 0; k < 2; ++k) \
;         acc[ai][bj][m][n] = __builtin_amdgcn_mfma_f32_16x16x32_bf16(Bt[n][k], At[m][k], acc[ai][bj][m][n], 0, 0, 0); __builtin_amdgcn_s_setprio(0); } while (0)
; #define PG8_WAIT_V(n) asm volatile("s_waitcnt vmcnt(" #n ")" ::: "memory")
; #define PG8_WAIT_L(n) asm volatile("s_waitcnt lgkmcnt(" #n ")" ::: "memory")
; #define PG8_BAR __builtin_amdgcn_s_barrier()
; #define PG8_SCHED __builtin_amdgcn_sched_barrier(0)
; template <class Epi, class Sched, bool ALIGN_EPI = false, bool SP2 = false>
; __device__ __forceinline__ void gemm_phase(PG8_LAS unsigned char* lds, const Gemm g, const Sched& S, const Epi& E) {
;     ...
;         for (int t = 0; t < nt; t += 2) {
;     ...
;             PG8_LDA(At, 1, 1); PG8_STAGE(PG8_SB(1, 0), b3, voffB); PG8_STAGE(PG8_SB(1, 1), b3 + hstepB, voffB); PG8_STAGE(PG8_SA(1, 0), a3, voffA);
;             PG8_WAIT_V(8); PG8_WAIT_L(0); PG8_BAR; PG8_MMA(1, 0, At, B0); PG8_MMA(1, 1, At, B1); PG8_BAR; PG8_SCHED;
	s_setprio 0
	s_add_i32 s13, s13, s6
	v_lshl_add_u64 v[226:227], v[226:227], 0, s[54:55]
	s_mov_b32 m0, s13
	ds_read_b128 v[194:197], v161 offset:49152
	ds_read_b128 v[198:201], v161 offset:50176
	ds_read_b128 v[202:205], v161 offset:51200
	ds_read_b128 v[206:209], v161 offset:52224
	ds_read_b128 v[210:213], v161 offset:53248
	ds_read_b128 v[214:217], v161 offset:54272
	ds_read_b128 v[218:221], v161 offset:55296
	ds_read_b128 v[222:225], v161 offset:56320
	global_load_lds_dwordx4 v[226:227], off
	s_add_i32 m0, s13, 0x2000
	s_add_u32 s38, s38, 0x80080
	v_lshl_add_u64 v[226:227], v[228:229], 0, s[54:55]
	s_addc_u32 s39, s39, 0
	s_add_i32 s13, s33, s6
	global_load_lds_dwordx4 v[226:227], off
	v_lshl_add_u64 v[226:227], s[38:39], 0, v[138:139]
	s_mov_b32 m0, s13
	s_nop 0
	global_load_lds_dwordx4 v[226:227], off
	v_lshl_add_u64 v[226:227], s[38:39], 0, v[142:143]
	s_add_i32 m0, s13, 0x2000
	s_nop 0
	global_load_lds_dwordx4 v[226:227], off
	v_lshl_add_u64 v[226:227], v[230:231], 0, s[54:55]
	s_mov_b32 m0, s51
	s_nop 0
	global_load_lds_dwordx4 v[226:227], off
	v_lshl_add_u64 v[226:227], v[232:233], 0, s[54:55]
	s_mov_b32 m0, s68
	s_nop 0
	global_load_lds_dwordx4 v[226:227], off
	s_nop 0
	s_waitcnt vmcnt(8)
	s_waitcnt lgkmcnt(0)
	s_setprio 1
	s_barrier
	v_mfma_f32_16x16x32_bf16 v[60:63], v[128:131], v[194:197], v[60:63]
	v_mfma_f32_16x16x32_bf16 v[56:59], v[164:167], v[194:197], v[56:59]
	v_mfma_f32_16x16x32_bf16 v[44:47], v[128:131], v[202:205], v[44:47]
	v_mfma_f32_16x16x32_bf16 v[40:43], v[164:167], v[202:205], v[40:43]
	v_mfma_f32_16x16x32_bf16 v[28:31], v[128:131], v[210:213], v[28:31]
	v_mfma_f32_16x16x32_bf16 v[24:27], v[164:167], v[210:213], v[24:27]
	v_mfma_f32_16x16x32_bf16 v[12:15], v[128:131], v[218:221], v[12:15]
	v_mfma_f32_16x16x32_bf16 v[8:11], v[164:167], v[218:221], v[8:11]
	v_mfma_f32_16x16x32_bf16 v[60:63], v[132:135], v[198:201], v[60:63]
	v_mfma_f32_16x16x32_bf16 v[56:59], v[168:171], v[198:201], v[56:59]
	v_mfma_f32_16x16x32_bf16 v[44:47], v[132:135], v[206:209], v[44:47]
	v_mfma_f32_16x16x32_bf16 v[40:43], v[168:171], v[206:209], v[40:43]
	v_mfma_f32_16x16x32_bf16 v[28:31], v[132:135], v[214:217], v[28:31]
	v_mfma_f32_16x16x32_bf16 v[24:27], v[168:171], v[214:217], v[24:27]
	v_mfma_f32_16x16x32_bf16 v[12:15], v[132:135], v[222:225], v[12:15]
	v_mfma_f32_16x16x32_bf16 v[8:11], v[168:171], v[222:225], v[8:11]
	s_setprio 0
	s_setprio 1
	v_mfma_f32_16x16x32_bf16 v[52:55], v[172:175], v[194:197], v[52:55]
	v_mfma_f32_16x16x32_bf16 v[48:51], v[180:183], v[194:197], v[48:51]
	v_mfma_f32_16x16x32_bf16 v[36:39], v[172:175], v[202:205], v[36:39]
	v_mfma_f32_16x16x32_bf16 v[32:35], v[180:183], v[202:205], v[32:35]
	v_mfma_f32_16x16x32_bf16 v[20:23], v[172:175], v[210:213], v[20:23]
	v_mfma_f32_16x16x32_bf16 v[16:19], v[180:183], v[210:213], v[16:19]
	v_mfma_f32_16x16x32_bf16 v[4:7], v[172:175], v[218:221], v[4:7]
	v_mfma_f32_16x16x32_bf16 v[0:3], v[180:183], v[218:221], v[0:3]
	v_mfma_f32_16x16x32_bf16 v[52:55], v[176:179], v[198:201], v[52:55]
	v_mfma_f32_16x16x32_bf16 v[48:51], v[190:193], v[198:201], v[48:51]
	v_mfma_f32_16x16x32_bf16 v[36:39], v[176:179], v[206:209], v[36:39]
	v_mfma_f32_16x16x32_bf16 v[32:35], v[190:193], v[206:209], v[32:35]
	v_mfma_f32_16x16x32_bf16 v[20:23], v[176:179], v[214:217], v[20:23]
	v_mfma_f32_16x16x32_bf16 v[16:19], v[190:193], v[214:217], v[16:19]
	v_mfma_f32_16x16x32_bf16 v[4:7], v[176:179], v[222:225], v[4:7]
	v_mfma_f32_16x16x32_bf16 v[0:3], v[190:193], v[222:225], v[0:3]
	s_barrier
	s_setprio 0
	s_add_i32 s12, s12, 2
	s_add_u32 s20, s20, 0x100
	s_addc_u32 s21, s21, 0
	s_add_u32 s10, s10, 0x100
	s_addc_u32 s11, s11, 0
	s_cmp_gt_u32 s12, 29
	s_cbranch_scc0 .LBB0_2050
	s_and_b64 vcc, exec, s[56:57]
	s_cbranch_vccz .LBB0_2053
	s_barrier

; #define PG8_STAGE(bufoff, gbase, voff) do { _Pragma("unroll") for (int _i = 0; _i < 2; ++_i) \
;         __builtin_amdgcn_global_load_lds((const unsigned*)((const char*)(gbase) + (voff)[_i]), (PG8_LAS unsigned*)(lds + (bufoff) + ldsw + _i * 8192), 16, 0, 0); } while (0)
; #define PG8_LDA(dst, b, h) do { _Pragma("unroll") for (int m = 0; m < 4; ++m) _Pragma("unroll") for (int k = 0; k < 2; ++k) dst[m][k] = *(const PG8_LAS bf16x8*)(lds + PG8_SA(b, h) + aoff + m * 2048 + k * 1024); } while (0)
; #define PG8_LDB(dst, b, h) do { _Pragma("unroll") for (int n = 0; n < 2; ++n) _Pragma("unroll") for (int k = 0; k < 2; ++k) dst[n][k] = *(const PG8_LAS bf16x8*)(lds + PG8_SB(b, h) + boff + n * 2048 + k * 1024); } while (0)
; #define PG8_WAIT_V(n) asm volatile("s_waitcnt vmcnt(" #n ")" ::: "memory")
; template <class Epi, class Sched, bool ALIGN_EPI = false, bool SP2 = false>
; __device__ __forceinline__ void gemm_phase(PG8_LAS unsigned char* lds, const Gemm g, const Sched& S, const Epi& E) {
;     ...
;             const char* a1 = cA + (size_t)(t + 1) * kstA;
;             const char* a2 = last ? nA : cA + (size_t)(t + 2) * kstA; const char* b2 = last ? nB : cB + (size_t)(t + 2) * kstep;
;             const char* a3 = a2 + kstA; const char* b3 = b2 + kstep;
;             if (last && has_next) S.a_ready(nxt);
;             if constexpr (SP2) {
;             PG8_LDB(B0, 0, 0); PG8_LDB(B1, 0, 1); PG8_SCHED; PG8_LDA(At, 0, 0); PG8_STAGE(PG8_SA(1, 1), a1 + hstepA, voffA);
;             PG8_WAIT_V(8); PG8_WAIT_L(0); PG8_BAR; PG8_MMA(0, 0, At, B0); PG8_MMA(0, 1, At, B1); PG8_BAR; PG8_SCHED;
;             PG8_LDA(At, 0, 1); PG8_STAGE(PG8_SB(0, 0), b2, voffB); PG8_STAGE(PG8_SB(0, 1), b2 + hstepB, voffB); PG8_STAGE(PG8_SA(0, 0), a2, voffA);
;             PG8_WAIT_V(8); PG8_WAIT_L(0); PG8_BAR; PG8_MMA(1, 0, At, B0); PG8_MMA(1, 1, At, B1); PG8_BAR; PG8_SCHED;
;             PG8_LDB(B0, 1, 0); PG8_LDB(B1, 1, 1); PG8_SCHED; PG8_LDA(At, 1, 0); PG8_STAGE(PG8_SA(0, 1), a2 + hstepA, voffA);
;             PG8_WAIT_V(8); PG8_WAIT_L(0); PG8_BAR; PG8_MMA(0, 0, At, B0); PG8_MMA(0, 1, At, B1); PG8_BAR; PG8_SCHED;
;             PG8_LDA(At, 1, 1); PG8_STAGE(PG8_SB(1, 0), b3, voffB); PG8_STAGE(PG8_SB(1, 1), b3 + hstepB, voffB); PG8_STAGE(PG8_SA(1, 0), a3, voffA);
;             PG8_WAIT_V(8); PG8_WAIT_L(0); PG8_BAR; PG8_MMA(1, 0, At, B0); PG8_MMA(1, 1, At, B1); PG8_BAR; PG8_SCHED;
.LBB0_2749:
	v_add_u32_e32 v176, s77, v180
	v_add_u32_e32 v183, s84, v180
	ds_read_b128 v[132:135], v176
	ds_read_b128 v[136:139], v176 offset:1024
	ds_read_b128 v[140:143], v176 offset:2048
	ds_read_b128 v[176:179], v176 offset:3072
	ds_read_b128 v[190:193], v183
	ds_read_b128 v[194:197], v183 offset:1024
	ds_read_b128 v[198:201], v183 offset:2048
	ds_read_b128 v[202:205], v183 offset:3072
	s_add_u32 s4, s46, s62
	s_addc_u32 s5, s47, s63
	s_add_u32 s12, s48, s62
	s_addc_u32 s13, s49, s63
	s_cmp_eq_u32 s7, s1
	s_cselect_b32 s67, s59, s5
	s_cselect_b32 s66, s58, s4
	s_cselect_b32 s65, s61, s13
	s_cselect_b32 s64, s60, s12
	v_lshl_add_u64 v[238:239], s[46:47], 0, v[130:131]
	s_add_i32 m0, s9, 0xc000
	ds_read_b128 v[206:209], v182
	ds_read_b128 v[210:213], v182 offset:1024
	ds_read_b128 v[214:217], v182 offset:2048
	ds_read_b128 v[218:221], v182 offset:3072
	ds_read_b128 v[222:225], v182 offset:4096
	ds_read_b128 v[226:229], v182 offset:5120
	ds_read_b128 v[230:233], v182 offset:6144
	ds_read_b128 v[234:237], v182 offset:7168
	global_load_lds_dwordx4 v[238:239], off
	v_lshl_add_u64 v[238:239], s[46:47], 0, v[128:129]
	s_add_i32 m0, s9, 0xe000
	s_nop 0
	global_load_lds_dwordx4 v[238:239], off
	s_nop 0
	s_waitcnt vmcnt(8)
	s_waitcnt lgkmcnt(0)
	s_setprio 1
	s_barrier
	v_mfma_f32_16x16x32_bf16 v[124:127], v[132:135], v[206:209], v[124:127]
	v_mfma_f32_16x16x32_bf16 v[120:123], v[140:143], v[206:209], v[120:123]
	v_mfma_f32_16x16x32_bf16 v[116:119], v[132:135], v[214:217], v[116:119]
	v_mfma_f32_16x16x32_bf16 v[112:115], v[140:143], v[214:217], v[112:115]
	v_mfma_f32_16x16x32_bf16 v[108:111], v[132:135], v[222:225], v[108:111]
	v_mfma_f32_16x16x32_bf16 v[104:107], v[140:143], v[222:225], v[104:107]
	v_mfma_f32_16x16x32_bf16 v[100:103], v[132:135], v[230:233], v[100:103]
	v_mfma_f32_16x16x32_bf16 v[96:99], v[140:143], v[230:233], v[96:99]
	v_mfma_f32_16x16x32_bf16 v[124:127], v[136:139], v[210:213], v[124:127]
	v_mfma_f32_16x16x32_bf16 v[120:123], v[176:179], v[210:213], v[120:123]
	v_mfma_f32_16x16x32_bf16 v[116:119], v[136:139], v[218:221], v[116:119]
	v_mfma_f32_16x16x32_bf16 v[112:115], v[176:179], v[218:221], v[112:115]
	v_mfma_f32_16x16x32_bf16 v[108:111], v[136:139], v[226:229], v[108:111]
	v_mfma_f32_16x16x32_bf16 v[104:107], v[176:179], v[226:229], v[104:107]
	v_mfma_f32_16x16x32_bf16 v[100:103], v[136:139], v[234:237], v[100:103]
	v_mfma_f32_16x16x32_bf16 v[96:99], v[176:179], v[234:237], v[96:99]
	s_setprio 0
	s_setprio 1
	v_mfma_f32_16x16x32_bf16 v[92:95], v[190:193], v[206:209], v[92:95]
	v_mfma_f32_16x16x32_bf16 v[88:91], v[198:201], v[206:209], v[88:91]
	v_mfma_f32_16x16x32_bf16 v[84:87], v[190:193], v[214:217], v[84:87]
	v_mfma_f32_16x16x32_bf16 v[80:83], v[198:201], v[214:217], v[80:83]
	v_mfma_f32_16x16x32_bf16 v[76:79], v[190:193], v[222:225], v[76:79]
	v_mfma_f32_16x16x32_bf16 v[72:75], v[198:201], v[222:225], v[72:75]
	v_mfma_f32_16x16x32_bf16 v[68:71], v[190:193], v[230:233], v[68:71]
	v_mfma_f32_16x16x32_bf16 v[64:67], v[198:201], v[230:233], v[64:67]
	v_mfma_f32_16x16x32_bf16 v[92:95], v[194:197], v[210:213], v[92:95]
	v_mfma_f32_16x16x32_bf16 v[88:91], v[202:205], v[210:213], v[88:91]
	v_mfma_f32_16x16x32_bf16 v[84:87], v[194:197], v[218:221], v[84:87]
	v_mfma_f32_16x16x32_bf16 v[80:83], v[202:205], v[218:221], v[80:83]
	v_mfma_f32_16x16x32_bf16 v[76:79], v[194:197], v[226:229], v[76:79]
	v_mfma_f32_16x16x32_bf16 v[72:75], v[202:205], v[226:229], v[72:75]
	v_mfma_f32_16x16x32_bf16 v[68:71], v[194:197], v[234:237], v[68:71]
	v_mfma_f32_16x16x32_bf16 v[64:67], v[202:205], v[234:237], v[64:67]
	s_barrier
	s_setprio 0
	s_add_i32 s4, s77, s8
	v_lshl_add_u64 v[238:239], s[64:65], 0, v[146:147]
	s_mov_b32 m0, s4
	ds_read_b128 v[206:209], v182 offset:16384
	ds_read_b128 v[210:213], v182 offset:17408
	ds_read_b128 v[214:217], v182 offset:18432
	ds_read_b128 v[218:221], v182 offset:19456
	ds_read_b128 v[222:225], v182 offset:20480
	ds_read_b128 v[226:229], v182 offset:21504
	ds_read_b128 v[230:233], v182 offset:22528
	ds_read_b128 v[234:237], v182 offset:23552
	global_load_lds_dwordx4 v[238:239], off
	s_add_i32 m0, s4, 0x2000
	s_add_u32 s4, s64, 0x80000
	v_lshl_add_u64 v[240:241], s[64:65], 0, v[150:151]
	s_addc_u32 s5, s65, 0
	s_add_i32 s12, s84, s8
	global_load_lds_dwordx4 v[240:241], off
	v_lshl_add_u64 v[242:243], s[4:5], 0, v[146:147]
	s_mov_b32 m0, s12
	v_lshl_add_u64 v[244:245], s[66:67], 0, v[148:149]
	global_load_lds_dwordx4 v[242:243], off
	v_lshl_add_u64 v[242:243], s[4:5], 0, v[150:151]
	s_add_i32 m0, s12, 0x2000
	s_nop 0
	global_load_lds_dwordx4 v[242:243], off
	v_lshl_add_u64 v[242:243], s[66:67], 0, v[144:145]
	s_mov_b32 m0, s9
	s_nop 0
	global_load_lds_dwordx4 v[242:243], off
	s_mov_b32 m0, s37
	s_nop 0
	global_load_lds_dwordx4 v[244:245], off
	s_waitcnt vmcnt(8)
	s_waitcnt lgkmcnt(0)
	s_setprio 1
	s_barrier
; #define PG8_STAGE(bufoff, gbase, voff) do { _Pragma("unroll") for (int _i = 0; _i < 2; ++_i) \
;         __builtin_amdgcn_global_load_lds((const unsigned*)((const char*)(gbase) + (voff)[_i]), (PG8_LAS unsigned*)(lds + (bufoff) + ldsw + _i * 8192), 16, 0, 0); } while (0)
; #define PG8_LDA(dst, b, h) do { _Pragma("unroll") for (int m = 0; m < 4; ++m) _Pragma("unroll") for (int k = 0; k < 2; ++k) dst[m][k] = *(const PG8_LAS bf16x8*)(lds + PG8_SA(b, h) + aoff + m * 2048 + k * 1024); } while (0)
; #define PG8_LDB(dst, b, h) do { _Pragma("unroll") for (int n = 0; n < 2; ++n) _Pragma("unroll") for (int k = 0; k < 2; ++k) dst[n][k] = *(const PG8_LAS bf16x8*)(lds + PG8_SB(b, h) + boff + n * 2048 + k * 1024); } while (0)
; #define PG8_MMA(ai, bj, At, Bt) do { __builtin_amdgcn_s_setprio(1); _Pragma("unroll") for (int m = 0; m < 4; ++m) _Pragma("unroll") for (int n = 0; n < 2; ++n) _Pragma("unroll") for (int k = 0; k < 2; ++k) \
;         acc[ai][bj][m][n] = __builtin_amdgcn_mfma_f32_16x16x32_bf16(Bt[n][k], At[m][k], acc[ai][bj][m][n], 0, 0, 0); __builtin_amdgcn_s_setprio(0); } while (0)
; #define PG8_WAIT_V(n) asm volatile("s_waitcnt vmcnt(" #n ")" ::: "memory")
; #define PG8_WAIT_L(n) asm volatile("s_waitcnt lgkmcnt(" #n ")" ::: "memory")
; #define PG8_BAR __builtin_amdgcn_s_barrier()
; #define PG8_SCHED __builtin_amdgcn_sched_barrier(0)
; template <class Epi, class Sched, bool ALIGN_EPI = false, bool SP2 = false>
; __device__ __forceinline__ void gemm_phase(PG8_LAS unsigned char* lds, const Gemm g, const Sched& S, const Epi& E) {
;     ...
;             PG8_WAIT_V(8); PG8_WAIT_L(0); PG8_BAR; PG8_MMA(1, 0, At, B0); PG8_MMA(1, 1, At, B1); PG8_BAR; PG8_SCHED;
;             PG8_LDB(B0, 1, 0); PG8_LDB(B1, 1, 1); PG8_SCHED; PG8_LDA(At, 1, 0); PG8_STAGE(PG8_SA(0, 1), a2 + hstepA, voffA);
;             PG8_WAIT_V(8); PG8_WAIT_L(0); PG8_BAR; PG8_MMA(0, 0, At, B0); PG8_MMA(0, 1, At, B1); PG8_BAR; PG8_SCHED;
	v_mfma_f32_16x16x32_bf16 v[60:63], v[132:135], v[206:209], v[60:63]
	v_mfma_f32_16x16x32_bf16 v[56:59], v[140:143], v[206:209], v[56:59]
	v_mfma_f32_16x16x32_bf16 v[52:55], v[132:135], v[214:217], v[52:55]
	v_mfma_f32_16x16x32_bf16 v[48:51], v[140:143], v[214:217], v[48:51]
	v_mfma_f32_16x16x32_bf16 v[44:47], v[132:135], v[222:225], v[44:47]
	v_mfma_f32_16x16x32_bf16 v[40:43], v[140:143], v[222:225], v[40:43]
	v_mfma_f32_16x16x32_bf16 v[36:39], v[132:135], v[230:233], v[36:39]
	v_mfma_f32_16x16x32_bf16 v[32:35], v[140:143], v[230:233], v[32:35]
	v_mfma_f32_16x16x32_bf16 v[60:63], v[136:139], v[210:213], v[60:63]
	v_mfma_f32_16x16x32_bf16 v[56:59], v[176:179], v[210:213], v[56:59]
	v_mfma_f32_16x16x32_bf16 v[52:55], v[136:139], v[218:221], v[52:55]
	v_mfma_f32_16x16x32_bf16 v[48:51], v[176:179], v[218:221], v[48:51]
	v_mfma_f32_16x16x32_bf16 v[44:47], v[136:139], v[226:229], v[44:47]
	v_mfma_f32_16x16x32_bf16 v[40:43], v[176:179], v[226:229], v[40:43]
	v_mfma_f32_16x16x32_bf16 v[36:39], v[136:139], v[234:237], v[36:39]
	v_mfma_f32_16x16x32_bf16 v[32:35], v[176:179], v[234:237], v[32:35]
	s_setprio 0
	s_setprio 1
	v_mfma_f32_16x16x32_bf16 v[28:31], v[190:193], v[206:209], v[28:31]
	v_mfma_f32_16x16x32_bf16 v[24:27], v[198:201], v[206:209], v[24:27]
	v_mfma_f32_16x16x32_bf16 v[20:23], v[190:193], v[214:217], v[20:23]
	v_mfma_f32_16x16x32_bf16 v[16:19], v[198:201], v[214:217], v[16:19]
	v_mfma_f32_16x16x32_bf16 v[12:15], v[190:193], v[222:225], v[12:15]
	v_mfma_f32_16x16x32_bf16 v[8:11], v[198:201], v[222:225], v[8:11]
	v_mfma_f32_16x16x32_bf16 v[4:7], v[190:193], v[230:233], v[4:7]
	v_mfma_f32_16x16x32_bf16 v[0:3], v[198:201], v[230:233], v[0:3]
	v_mfma_f32_16x16x32_bf16 v[28:31], v[194:197], v[210:213], v[28:31]
	v_mfma_f32_16x16x32_bf16 v[24:27], v[202:205], v[210:213], v[24:27]
	v_mfma_f32_16x16x32_bf16 v[20:23], v[194:197], v[218:221], v[20:23]
	v_mfma_f32_16x16x32_bf16 v[16:19], v[202:205], v[218:221], v[16:19]
	v_mfma_f32_16x16x32_bf16 v[12:15], v[194:197], v[226:229], v[12:15]
	v_mfma_f32_16x16x32_bf16 v[8:11], v[202:205], v[226:229], v[8:11]
	v_mfma_f32_16x16x32_bf16 v[4:7], v[194:197], v[234:237], v[4:7]
	v_mfma_f32_16x16x32_bf16 v[0:3], v[202:205], v[234:237], v[0:3]
	s_barrier
	s_setprio 0
	s_add_i32 s12, 0, 0x18000
	s_add_i32 s13, 0, 0x1c000
	v_add_u32_e32 v176, s12, v180
	v_add_u32_e32 v183, s13, v180
	ds_read_b128 v[132:135], v176
	ds_read_b128 v[136:139], v176 offset:1024
	ds_read_b128 v[140:143], v176 offset:2048
	ds_read_b128 v[176:179], v176 offset:3072
	ds_read_b128 v[190:193], v183
	ds_read_b128 v[194:197], v183 offset:1024
	ds_read_b128 v[198:201], v183 offset:2048
	ds_read_b128 v[202:205], v183 offset:3072
	s_add_u32 s4, s66, 0x80000
	s_addc_u32 s5, s67, 0
	s_mov_b32 m0, s70
	v_lshl_add_u64 v[246:247], s[4:5], 0, v[144:145]
	ds_read_b128 v[206:209], v182 offset:32768
	ds_read_b128 v[210:213], v182 offset:33792
	ds_read_b128 v[214:217], v182 offset:34816
	ds_read_b128 v[218:221], v182 offset:35840
	ds_read_b128 v[222:225], v182 offset:36864
	ds_read_b128 v[226:229], v182 offset:37888
	ds_read_b128 v[230:233], v182 offset:38912
	ds_read_b128 v[234:237], v182 offset:39936
	global_load_lds_dwordx4 v[246:247], off
	v_lshl_add_u64 v[246:247], s[4:5], 0, v[148:149]
	s_mov_b32 m0, s71
	s_nop 0
	global_load_lds_dwordx4 v[246:247], off
	s_waitcnt vmcnt(8)
	s_waitcnt lgkmcnt(0)
	s_setprio 1
	s_barrier
	v_mfma_f32_16x16x32_bf16 v[124:127], v[132:135], v[206:209], v[124:127]
	v_mfma_f32_16x16x32_bf16 v[120:123], v[140:143], v[206:209], v[120:123]
	v_mfma_f32_16x16x32_bf16 v[116:119], v[132:135], v[214:217], v[116:119]
	v_mfma_f32_16x16x32_bf16 v[112:115], v[140:143], v[214:217], v[112:115]
	v_mfma_f32_16x16x32_bf16 v[108:111], v[132:135], v[222:225], v[108:111]
	v_mfma_f32_16x16x32_bf16 v[104:107], v[140:143], v[222:225], v[104:107]
	v_mfma_f32_16x16x32_bf16 v[100:103], v[132:135], v[230:233], v[100:103]
	v_mfma_f32_16x16x32_bf16 v[96:99], v[140:143], v[230:233], v[96:99]
	v_mfma_f32_16x16x32_bf16 v[124:127], v[136:139], v[210:213], v[124:127]
	v_mfma_f32_16x16x32_bf16 v[120:123], v[176:179], v[210:213], v[120:123]
	v_mfma_f32_16x16x32_bf16 v[116:119], v[136:139], v[218:221], v[116:119]
	v_mfma_f32_16x16x32_bf16 v[112:115], v[176:179], v[218:221], v[112:115]
	v_mfma_f32_16x16x32_bf16 v[108:111], v[136:139], v[226:229], v[108:111]
	v_mfma_f32_16x16x32_bf16 v[104:107], v[176:179], v[226:229], v[104:107]
	v_mfma_f32_16x16x32_bf16 v[100:103], v[136:139], v[234:237], v[100:103]
	v_mfma_f32_16x16x32_bf16 v[96:99], v[176:179], v[234:237], v[96:99]
	s_setprio 0
	s_setprio 1
	v_mfma_f32_16x16x32_bf16 v[92:95], v[190:193], v[206:209], v[92:95]
	v_mfma_f32_16x16x32_bf16 v[88:91], v[198:201], v[206:209], v[88:91]
	v_mfma_f32_16x16x32_bf16 v[84:87], v[190:193], v[214:217], v[84:87]
	v_mfma_f32_16x16x32_bf16 v[80:83], v[198:201], v[214:217], v[80:83]
	v_mfma_f32_16x16x32_bf16 v[76:79], v[190:193], v[222:225], v[76:79]
	v_mfma_f32_16x16x32_bf16 v[72:75], v[198:201], v[222:225], v[72:75]
	v_mfma_f32_16x16x32_bf16 v[68:71], v[190:193], v[230:233], v[68:71]
	v_mfma_f32_16x16x32_bf16 v[64:67], v[198:201], v[230:233], v[64:67]
	v_mfma_f32_16x16x32_bf16 v[92:95], v[194:197], v[210:213], v[92:95]
	v_mfma_f32_16x16x32_bf16 v[88:91], v[202:205], v[210:213], v[88:91]
	v_mfma_f32_16x16x32_bf16 v[84:87], v[194:197], v[218:221], v[84:87]
	v_mfma_f32_16x16x32_bf16 v[80:83], v[202:205], v[218:221], v[80:83]
	v_mfma_f32_16x16x32_bf16 v[76:79], v[194:197], v[226:229], v[76:79]
	v_mfma_f32_16x16x32_bf16 v[72:75], v[202:205], v[226:229], v[72:75]
	v_mfma_f32_16x16x32_bf16 v[68:71], v[194:197], v[234:237], v[68:71]
	v_mfma_f32_16x16x32_bf16 v[64:67], v[202:205], v[234:237], v[64:67]
	s_barrier
; #define PG8_STAGE(bufoff, gbase, voff) do { _Pragma("unroll") for (int _i = 0; _i < 2; ++_i) \
;         __builtin_amdgcn_global_load_lds((const unsigned*)((const char*)(gbase) + (voff)[_i]), (PG8_LAS unsigned*)(lds + (bufoff) + ldsw + _i * 8192), 16, 0, 0); } while (0)
; #define PG8_LDA(dst, b, h) do { _Pragma("unroll") for (int m = 0; m < 4; ++m) _Pragma("unroll") for (int k = 0; k < 2; ++k) dst[m][k] = *(const PG8_LAS bf16x8*)(lds + PG8_SA(b, h) + aoff + m * 2048 + k * 1024); } while (0)
; #define PG8_MMA(ai, bj, At, Bt) do { __builtin_amdgcn_s_setprio(1); _Pragma("unroll") for (int m = 0; m < 4; ++m) _Pragma("unroll") for (int n = 0; n < 2; ++n) _Pragma("unroll") for (int k = 0; k < 2; ++k) \
;         acc[ai][bj][m][n] = __builtin_amdgcn_mfma_f32_16x16x32_bf16(Bt[n][k], At[m][k], acc[ai][bj][m][n], 0, 0, 0); __builtin_amdgcn_s_setprio(0); } while (0)
; #define PG8_WAIT_V(n) asm volatile("s_waitcnt vmcnt(" #n ")" ::: "memory")
; #define PG8_WAIT_L(n) asm volatile("s_waitcnt lgkmcnt(" #n ")" ::: "memory")
; #define PG8_BAR __builtin_amdgcn_s_barrier()
; #define PG8_SCHED __builtin_amdgcn_sched_barrier(0)
; template <class Epi, class Sched, bool ALIGN_EPI = false, bool SP2 = false>
; __device__ __forceinline__ void gemm_phase(PG8_LAS unsigned char* lds, const Gemm g, const Sched& S, const Epi& E) {
;     ...
;         for (int t = 0; t < nt; t += 2) {
;     ...
;             PG8_LDA(At, 1, 1); PG8_STAGE(PG8_SB(1, 0), b3, voffB); PG8_STAGE(PG8_SB(1, 1), b3 + hstepB, voffB); PG8_STAGE(PG8_SA(1, 0), a3, voffA);
;             PG8_WAIT_V(8); PG8_WAIT_L(0); PG8_BAR; PG8_MMA(1, 0, At, B0); PG8_MMA(1, 1, At, B1); PG8_BAR; PG8_SCHED;
	s_setprio 0
	s_add_i32 s4, s12, s8
	v_lshl_add_u64 v[238:239], v[238:239], 0, s[52:53]
	s_mov_b32 m0, s4
	ds_read_b128 v[206:209], v182 offset:49152
	ds_read_b128 v[210:213], v182 offset:50176
	ds_read_b128 v[214:217], v182 offset:51200
	ds_read_b128 v[218:221], v182 offset:52224
	ds_read_b128 v[222:225], v182 offset:53248
	ds_read_b128 v[226:229], v182 offset:54272
	ds_read_b128 v[230:233], v182 offset:55296
	ds_read_b128 v[234:237], v182 offset:56320
	global_load_lds_dwordx4 v[238:239], off
	s_add_i32 m0, s4, 0x2000
	s_add_u32 s4, s64, 0x80080
	v_lshl_add_u64 v[238:239], v[240:241], 0, s[52:53]
	s_addc_u32 s5, s65, 0
	s_add_i32 s12, s13, s8
	global_load_lds_dwordx4 v[238:239], off
	v_lshl_add_u64 v[238:239], s[4:5], 0, v[146:147]
	s_mov_b32 m0, s12
	s_nop 0
	global_load_lds_dwordx4 v[238:239], off
	v_lshl_add_u64 v[238:239], s[4:5], 0, v[150:151]
	s_add_i32 m0, s12, 0x2000
	s_nop 0
	global_load_lds_dwordx4 v[238:239], off
	v_lshl_add_u64 v[238:239], v[242:243], 0, s[52:53]
	s_mov_b32 m0, s74
	s_nop 0
	global_load_lds_dwordx4 v[238:239], off
	v_lshl_add_u64 v[238:239], v[244:245], 0, s[52:53]
	s_mov_b32 m0, s75
	s_nop 0
	global_load_lds_dwordx4 v[238:239], off
	s_nop 0
	s_waitcnt vmcnt(8)
	s_waitcnt lgkmcnt(0)
	s_setprio 1
	s_barrier
	v_mfma_f32_16x16x32_bf16 v[60:63], v[132:135], v[206:209], v[60:63]
	v_mfma_f32_16x16x32_bf16 v[56:59], v[140:143], v[206:209], v[56:59]
	v_mfma_f32_16x16x32_bf16 v[52:55], v[132:135], v[214:217], v[52:55]
	v_mfma_f32_16x16x32_bf16 v[48:51], v[140:143], v[214:217], v[48:51]
	v_mfma_f32_16x16x32_bf16 v[44:47], v[132:135], v[222:225], v[44:47]
	v_mfma_f32_16x16x32_bf16 v[40:43], v[140:143], v[222:225], v[40:43]
	v_mfma_f32_16x16x32_bf16 v[36:39], v[132:135], v[230:233], v[36:39]
	v_mfma_f32_16x16x32_bf16 v[32:35], v[140:143], v[230:233], v[32:35]
	v_mfma_f32_16x16x32_bf16 v[60:63], v[136:139], v[210:213], v[60:63]
	v_mfma_f32_16x16x32_bf16 v[56:59], v[176:179], v[210:213], v[56:59]
	v_mfma_f32_16x16x32_bf16 v[52:55], v[136:139], v[218:221], v[52:55]
	v_mfma_f32_16x16x32_bf16 v[48:51], v[176:179], v[218:221], v[48:51]
	v_mfma_f32_16x16x32_bf16 v[44:47], v[136:139], v[226:229], v[44:47]
	v_mfma_f32_16x16x32_bf16 v[40:43], v[176:179], v[226:229], v[40:43]
	v_mfma_f32_16x16x32_bf16 v[36:39], v[136:139], v[234:237], v[36:39]
	v_mfma_f32_16x16x32_bf16 v[32:35], v[176:179], v[234:237], v[32:35]
	s_setprio 0
	s_setprio 1
	v_mfma_f32_16x16x32_bf16 v[28:31], v[190:193], v[206:209], v[28:31]
	v_mfma_f32_16x16x32_bf16 v[24:27], v[198:201], v[206:209], v[24:27]
	v_mfma_f32_16x16x32_bf16 v[20:23], v[190:193], v[214:217], v[20:23]
	v_mfma_f32_16x16x32_bf16 v[16:19], v[198:201], v[214:217], v[16:19]
	v_mfma_f32_16x16x32_bf16 v[12:15], v[190:193], v[222:225], v[12:15]
	v_mfma_f32_16x16x32_bf16 v[8:11], v[198:201], v[222:225], v[8:11]
	v_mfma_f32_16x16x32_bf16 v[4:7], v[190:193], v[230:233], v[4:7]
	v_mfma_f32_16x16x32_bf16 v[0:3], v[198:201], v[230:233], v[0:3]
	v_mfma_f32_16x16x32_bf16 v[28:31], v[194:197], v[210:213], v[28:31]
	v_mfma_f32_16x16x32_bf16 v[24:27], v[202:205], v[210:213], v[24:27]
	v_mfma_f32_16x16x32_bf16 v[20:23], v[194:197], v[218:221], v[20:23]
	v_mfma_f32_16x16x32_bf16 v[16:19], v[202:205], v[218:221], v[16:19]
	v_mfma_f32_16x16x32_bf16 v[12:15], v[194:197], v[226:229], v[12:15]
	v_mfma_f32_16x16x32_bf16 v[8:11], v[202:205], v[226:229], v[8:11]
	v_mfma_f32_16x16x32_bf16 v[4:7], v[194:197], v[234:237], v[4:7]
	v_mfma_f32_16x16x32_bf16 v[0:3], v[202:205], v[234:237], v[0:3]
	s_barrier
	s_setprio 0
	s_add_i32 s4, s1, 2
	s_add_u32 s62, s62, 0x100
	s_addc_u32 s63, s63, 0
	v_lshl_add_u64 v[130:131], v[130:131], 0, s[34:35]
	v_lshl_add_u64 v[128:129], v[128:129], 0, s[34:35]
	s_cmp_ge_i32 s1, s7
	s_mov_b32 s1, s4
	s_cbranch_scc0 .LBB0_2749
	s_and_b64 vcc, exec, s[54:55]
	s_cbranch_vccz .LBB0_2752
	s_barrier

; #define PG8_STAGE(bufoff, gbase, voff) do { _Pragma("unroll") for (int _i = 0; _i < 2; ++_i) \
;         __builtin_amdgcn_global_load_lds((const unsigned*)((const char*)(gbase) + (voff)[_i]), (PG8_LAS unsigned*)(lds + (bufoff) + ldsw + _i * 8192), 16, 0, 0); } while (0)
; #define PG8_LDA(dst, b, h) do { _Pragma("unroll") for (int m = 0; m < 4; ++m) _Pragma("unroll") for (int k = 0; k < 2; ++k) dst[m][k] = *(const PG8_LAS bf16x8*)(lds + PG8_SA(b, h) + aoff + m * 2048 + k * 1024); } while (0)
; #define PG8_LDB(dst, b, h) do { _Pragma("unroll") for (int n = 0; n < 2; ++n) _Pragma("unroll") for (int k = 0; k < 2; ++k) dst[n][k] = *(const PG8_LAS bf16x8*)(lds + PG8_SB(b, h) + boff + n * 2048 + k * 1024); } while (0)
; #define PG8_WAIT_V(n) asm volatile("s_waitcnt vmcnt(" #n ")" ::: "memory")
; template <class Epi, class Sched, bool ALIGN_EPI = false, bool SP2 = false>
; __device__ __forceinline__ void gemm_phase(PG8_LAS unsigned char* lds, const Gemm g, const Sched& S, const Epi& E) {
;     ...
;             const char* a1 = cA + (size_t)(t + 1) * kstA;
;             const char* a2 = last ? nA : cA + (size_t)(t + 2) * kstA; const char* b2 = last ? nB : cB + (size_t)(t + 2) * kstep;
;             const char* a3 = a2 + kstA; const char* b3 = b2 + kstep;
;             if (last && has_next) S.a_ready(nxt);
;             if constexpr (SP2) {
;             PG8_LDB(B0, 0, 0); PG8_LDB(B1, 0, 1); PG8_SCHED; PG8_LDA(At, 0, 0); PG8_STAGE(PG8_SA(1, 1), a1 + hstepA, voffA);
;             PG8_WAIT_V(8); PG8_WAIT_L(0); PG8_BAR; PG8_MMA(0, 0, At, B0); PG8_MMA(0, 1, At, B1); PG8_BAR; PG8_SCHED;
;             PG8_LDA(At, 0, 1); PG8_STAGE(PG8_SB(0, 0), b2, voffB); PG8_STAGE(PG8_SB(0, 1), b2 + hstepB, voffB); PG8_STAGE(PG8_SA(0, 0), a2, voffA);
;             PG8_WAIT_V(8); PG8_WAIT_L(0); PG8_BAR; PG8_MMA(1, 0, At, B0); PG8_MMA(1, 1, At, B1); PG8_BAR; PG8_SCHED;
;             PG8_LDB(B0, 1, 0); PG8_LDB(B1, 1, 1); PG8_SCHED; PG8_LDA(At, 1, 0); PG8_STAGE(PG8_SA(0, 1), a2 + hstepA, voffA);
;             PG8_WAIT_V(8); PG8_WAIT_L(0); PG8_BAR; PG8_MMA(0, 0, At, B0); PG8_MMA(0, 1, At, B1); PG8_BAR; PG8_SCHED;
;             PG8_LDA(At, 1, 1); PG8_STAGE(PG8_SB(1, 0), b3, voffB); PG8_STAGE(PG8_SB(1, 1), b3 + hstepB, voffB); PG8_STAGE(PG8_SA(1, 0), a3, voffA);
;             PG8_WAIT_V(8); PG8_WAIT_L(0); PG8_BAR; PG8_MMA(1, 0, At, B0); PG8_MMA(1, 1, At, B1); PG8_BAR; PG8_SCHED;
.LBB0_3058:
	ds_read_b128 v[156:159], v152
	ds_read_b128 v[160:163], v152 offset:1024
	ds_read_b128 v[164:167], v152 offset:2048
	ds_read_b128 v[168:171], v152 offset:3072
	ds_read_b128 v[172:175], v153
	ds_read_b128 v[176:179], v153 offset:1024
	ds_read_b128 v[180:183], v153 offset:2048
	ds_read_b128 v[190:193], v153 offset:3072
	s_add_u32 s42, s40, 0xfff80080
	s_addc_u32 s43, s41, -1
	s_cmp_eq_u32 s35, 28
	s_cselect_b32 s45, s4, s43
	s_cselect_b32 s44, s5, s42
	s_cselect_b32 s43, s12, s23
	s_cselect_b32 s42, s13, s21
	v_lshl_add_u64 v[226:227], s[40:41], 0, v[142:143]
	s_add_i32 m0, s8, 0xc000
	ds_read_b128 v[194:197], v154
	ds_read_b128 v[198:201], v154 offset:1024
	ds_read_b128 v[202:205], v154 offset:2048
	ds_read_b128 v[206:209], v154 offset:3072
	ds_read_b128 v[210:213], v154 offset:4096
	ds_read_b128 v[214:217], v154 offset:5120
	ds_read_b128 v[218:221], v154 offset:6144
	ds_read_b128 v[222:225], v154 offset:7168
	global_load_lds_dwordx4 v[226:227], off
	v_lshl_add_u64 v[226:227], s[40:41], 0, v[144:145]
	s_add_i32 m0, s8, 0xe000
	s_nop 0
	global_load_lds_dwordx4 v[226:227], off
	s_nop 0
	s_waitcnt vmcnt(8)
	s_waitcnt lgkmcnt(0)
	s_setprio 1
	s_barrier
	v_mfma_f32_16x16x32_bf16 v[124:127], v[156:159], v[194:197], v[124:127]
	v_mfma_f32_16x16x32_bf16 v[120:123], v[164:167], v[194:197], v[120:123]
	v_mfma_f32_16x16x32_bf16 v[108:111], v[156:159], v[202:205], v[108:111]
	v_mfma_f32_16x16x32_bf16 v[104:107], v[164:167], v[202:205], v[104:107]
	v_mfma_f32_16x16x32_bf16 v[92:95], v[156:159], v[210:213], v[92:95]
	v_mfma_f32_16x16x32_bf16 v[88:91], v[164:167], v[210:213], v[88:91]
	v_mfma_f32_16x16x32_bf16 v[76:79], v[156:159], v[218:221], v[76:79]
	v_mfma_f32_16x16x32_bf16 v[72:75], v[164:167], v[218:221], v[72:75]
	v_mfma_f32_16x16x32_bf16 v[124:127], v[160:163], v[198:201], v[124:127]
	v_mfma_f32_16x16x32_bf16 v[120:123], v[168:171], v[198:201], v[120:123]
	v_mfma_f32_16x16x32_bf16 v[108:111], v[160:163], v[206:209], v[108:111]
	v_mfma_f32_16x16x32_bf16 v[104:107], v[168:171], v[206:209], v[104:107]
	v_mfma_f32_16x16x32_bf16 v[92:95], v[160:163], v[214:217], v[92:95]
	v_mfma_f32_16x16x32_bf16 v[88:91], v[168:171], v[214:217], v[88:91]
	v_mfma_f32_16x16x32_bf16 v[76:79], v[160:163], v[222:225], v[76:79]
	v_mfma_f32_16x16x32_bf16 v[72:75], v[168:171], v[222:225], v[72:75]
	s_setprio 0
	s_setprio 1
	v_mfma_f32_16x16x32_bf16 v[116:119], v[172:175], v[194:197], v[116:119]
	v_mfma_f32_16x16x32_bf16 v[112:115], v[180:183], v[194:197], v[112:115]
	v_mfma_f32_16x16x32_bf16 v[100:103], v[172:175], v[202:205], v[100:103]
	v_mfma_f32_16x16x32_bf16 v[96:99], v[180:183], v[202:205], v[96:99]
	v_mfma_f32_16x16x32_bf16 v[84:87], v[172:175], v[210:213], v[84:87]
	v_mfma_f32_16x16x32_bf16 v[80:83], v[180:183], v[210:213], v[80:83]
	v_mfma_f32_16x16x32_bf16 v[68:71], v[172:175], v[218:221], v[68:71]
	v_mfma_f32_16x16x32_bf16 v[64:67], v[180:183], v[218:221], v[64:67]
	v_mfma_f32_16x16x32_bf16 v[116:119], v[176:179], v[198:201], v[116:119]
	v_mfma_f32_16x16x32_bf16 v[112:115], v[190:193], v[198:201], v[112:115]
	v_mfma_f32_16x16x32_bf16 v[100:103], v[176:179], v[206:209], v[100:103]
	v_mfma_f32_16x16x32_bf16 v[96:99], v[190:193], v[206:209], v[96:99]
	v_mfma_f32_16x16x32_bf16 v[84:87], v[176:179], v[214:217], v[84:87]
	v_mfma_f32_16x16x32_bf16 v[80:83], v[190:193], v[214:217], v[80:83]
	v_mfma_f32_16x16x32_bf16 v[68:71], v[176:179], v[222:225], v[68:71]
	v_mfma_f32_16x16x32_bf16 v[64:67], v[190:193], v[222:225], v[64:67]
	s_barrier
	s_setprio 0
	s_add_i32 s53, s50, s7
	v_lshl_add_u64 v[226:227], s[42:43], 0, v[130:131]
	s_mov_b32 m0, s53
	ds_read_b128 v[194:197], v154 offset:16384
	ds_read_b128 v[198:201], v154 offset:17408
	ds_read_b128 v[202:205], v154 offset:18432
	ds_read_b128 v[206:209], v154 offset:19456
	ds_read_b128 v[210:213], v154 offset:20480
	ds_read_b128 v[214:217], v154 offset:21504
	ds_read_b128 v[218:221], v154 offset:22528
	ds_read_b128 v[222:225], v154 offset:23552
	global_load_lds_dwordx4 v[226:227], off
	s_add_i32 m0, s53, 0x2000
	s_add_u32 s54, s42, 0x80000
	v_lshl_add_u64 v[228:229], s[42:43], 0, v[134:135]
	s_addc_u32 s55, s43, 0
	s_add_i32 s53, s51, s7
	global_load_lds_dwordx4 v[228:229], off
	v_lshl_add_u64 v[230:231], s[54:55], 0, v[130:131]
	s_mov_b32 m0, s53
	v_lshl_add_u64 v[232:233], s[44:45], 0, v[132:133]
	global_load_lds_dwordx4 v[230:231], off
	v_lshl_add_u64 v[230:231], s[54:55], 0, v[134:135]
	s_add_i32 m0, s53, 0x2000
	s_nop 0
	global_load_lds_dwordx4 v[230:231], off
	v_lshl_add_u64 v[230:231], s[44:45], 0, v[128:129]
	s_mov_b32 m0, s8
	s_nop 0
	global_load_lds_dwordx4 v[230:231], off
	s_mov_b32 m0, s9
	s_nop 0
	global_load_lds_dwordx4 v[232:233], off
	s_waitcnt vmcnt(8)
	s_waitcnt lgkmcnt(0)
	s_setprio 1
	s_barrier
; #define PG8_STAGE(bufoff, gbase, voff) do { _Pragma("unroll") for (int _i = 0; _i < 2; ++_i) \
;         __builtin_amdgcn_global_load_lds((const unsigned*)((const char*)(gbase) + (voff)[_i]), (PG8_LAS unsigned*)(lds + (bufoff) + ldsw + _i * 8192), 16, 0, 0); } while (0)
; #define PG8_LDA(dst, b, h) do { _Pragma("unroll") for (int m = 0; m < 4; ++m) _Pragma("unroll") for (int k = 0; k < 2; ++k) dst[m][k] = *(const PG8_LAS bf16x8*)(lds + PG8_SA(b, h) + aoff + m * 2048 + k * 1024); } while (0)
; #define PG8_LDB(dst, b, h) do { _Pragma("unroll") for (int n = 0; n < 2; ++n) _Pragma("unroll") for (int k = 0; k < 2; ++k) dst[n][k] = *(const PG8_LAS bf16x8*)(lds + PG8_SB(b, h) + boff + n * 2048 + k * 1024); } while (0)
; #define PG8_MMA(ai, bj, At, Bt) do { __builtin_amdgcn_s_setprio(1); _Pragma("unroll") for (int m = 0; m < 4; ++m) _Pragma("unroll") for (int n = 0; n < 2; ++n) _Pragma("unroll") for (int k = 0; k < 2; ++k) \
;         acc[ai][bj][m][n] = __builtin_amdgcn_mfma_f32_16x16x32_bf16(Bt[n][k], At[m][k], acc[ai][bj][m][n], 0, 0, 0); __builtin_amdgcn_s_setprio(0); } while (0)
; #define PG8_WAIT_V(n) asm volatile("s_waitcnt vmcnt(" #n ")" ::: "memory")
; #define PG8_WAIT_L(n) asm volatile("s_waitcnt lgkmcnt(" #n ")" ::: "memory")
; #define PG8_BAR __builtin_amdgcn_s_barrier()
; #define PG8_SCHED __builtin_amdgcn_sched_barrier(0)
; template <class Epi, class Sched, bool ALIGN_EPI = false, bool SP2 = false>
; __device__ __forceinline__ void gemm_phase(PG8_LAS unsigned char* lds, const Gemm g, const Sched& S, const Epi& E) {
;     ...
;             PG8_WAIT_V(8); PG8_WAIT_L(0); PG8_BAR; PG8_MMA(1, 0, At, B0); PG8_MMA(1, 1, At, B1); PG8_BAR; PG8_SCHED;
;             PG8_LDB(B0, 1, 0); PG8_LDB(B1, 1, 1); PG8_SCHED; PG8_LDA(At, 1, 0); PG8_STAGE(PG8_SA(0, 1), a2 + hstepA, voffA);
;             PG8_WAIT_V(8); PG8_WAIT_L(0); PG8_BAR; PG8_MMA(0, 0, At, B0); PG8_MMA(0, 1, At, B1); PG8_BAR; PG8_SCHED;
	v_mfma_f32_16x16x32_bf16 v[60:63], v[156:159], v[194:197], v[60:63]
	v_mfma_f32_16x16x32_bf16 v[56:59], v[164:167], v[194:197], v[56:59]
	v_mfma_f32_16x16x32_bf16 v[44:47], v[156:159], v[202:205], v[44:47]
	v_mfma_f32_16x16x32_bf16 v[40:43], v[164:167], v[202:205], v[40:43]
	v_mfma_f32_16x16x32_bf16 v[28:31], v[156:159], v[210:213], v[28:31]
	v_mfma_f32_16x16x32_bf16 v[24:27], v[164:167], v[210:213], v[24:27]
	v_mfma_f32_16x16x32_bf16 v[12:15], v[156:159], v[218:221], v[12:15]
	v_mfma_f32_16x16x32_bf16 v[8:11], v[164:167], v[218:221], v[8:11]
	v_mfma_f32_16x16x32_bf16 v[60:63], v[160:163], v[198:201], v[60:63]
	v_mfma_f32_16x16x32_bf16 v[56:59], v[168:171], v[198:201], v[56:59]
	v_mfma_f32_16x16x32_bf16 v[44:47], v[160:163], v[206:209], v[44:47]
	v_mfma_f32_16x16x32_bf16 v[40:43], v[168:171], v[206:209], v[40:43]
	v_mfma_f32_16x16x32_bf16 v[28:31], v[160:163], v[214:217], v[28:31]
	v_mfma_f32_16x16x32_bf16 v[24:27], v[168:171], v[214:217], v[24:27]
	v_mfma_f32_16x16x32_bf16 v[12:15], v[160:163], v[222:225], v[12:15]
	v_mfma_f32_16x16x32_bf16 v[8:11], v[168:171], v[222:225], v[8:11]
	s_setprio 0
	s_setprio 1
	v_mfma_f32_16x16x32_bf16 v[52:55], v[172:175], v[194:197], v[52:55]
	v_mfma_f32_16x16x32_bf16 v[48:51], v[180:183], v[194:197], v[48:51]
	v_mfma_f32_16x16x32_bf16 v[36:39], v[172:175], v[202:205], v[36:39]
	v_mfma_f32_16x16x32_bf16 v[32:35], v[180:183], v[202:205], v[32:35]
	v_mfma_f32_16x16x32_bf16 v[20:23], v[172:175], v[210:213], v[20:23]
	v_mfma_f32_16x16x32_bf16 v[16:19], v[180:183], v[210:213], v[16:19]
	v_mfma_f32_16x16x32_bf16 v[4:7], v[172:175], v[218:221], v[4:7]
	v_mfma_f32_16x16x32_bf16 v[0:3], v[180:183], v[218:221], v[0:3]
	v_mfma_f32_16x16x32_bf16 v[52:55], v[176:179], v[198:201], v[52:55]
	v_mfma_f32_16x16x32_bf16 v[48:51], v[190:193], v[198:201], v[48:51]
	v_mfma_f32_16x16x32_bf16 v[36:39], v[176:179], v[206:209], v[36:39]
	v_mfma_f32_16x16x32_bf16 v[32:35], v[190:193], v[206:209], v[32:35]
	v_mfma_f32_16x16x32_bf16 v[20:23], v[176:179], v[214:217], v[20:23]
	v_mfma_f32_16x16x32_bf16 v[16:19], v[190:193], v[214:217], v[16:19]
	v_mfma_f32_16x16x32_bf16 v[4:7], v[176:179], v[222:225], v[4:7]
	v_mfma_f32_16x16x32_bf16 v[0:3], v[190:193], v[222:225], v[0:3]
	s_barrier
	s_setprio 0
	s_add_i32 s53, 0, 0x18000
	v_add_u32_e32 v155, s53, v150
	s_add_i32 s54, 0, 0x1c000
	ds_read_b128 v[156:159], v155
	ds_read_b128 v[160:163], v155 offset:1024
	ds_read_b128 v[164:167], v155 offset:2048
	ds_read_b128 v[168:171], v155 offset:3072
	v_add_u32_e32 v155, s54, v150
	ds_read_b128 v[172:175], v155
	ds_read_b128 v[176:179], v155 offset:1024
	ds_read_b128 v[180:183], v155 offset:2048
	ds_read_b128 v[190:193], v155 offset:3072
	s_add_u32 s44, s44, 0x80000
	s_addc_u32 s45, s45, 0
	s_mov_b32 m0, s10
	v_lshl_add_u64 v[234:235], s[44:45], 0, v[128:129]
	ds_read_b128 v[194:197], v154 offset:32768
	ds_read_b128 v[198:201], v154 offset:33792
	ds_read_b128 v[202:205], v154 offset:34816
	ds_read_b128 v[206:209], v154 offset:35840
	ds_read_b128 v[210:213], v154 offset:36864
	ds_read_b128 v[214:217], v154 offset:37888
	ds_read_b128 v[218:221], v154 offset:38912
	ds_read_b128 v[222:225], v154 offset:39936
	global_load_lds_dwordx4 v[234:235], off
	v_lshl_add_u64 v[234:235], s[44:45], 0, v[132:133]
	s_mov_b32 m0, s11
	s_nop 0
	global_load_lds_dwordx4 v[234:235], off
	s_waitcnt vmcnt(8)
	s_waitcnt lgkmcnt(0)
	s_setprio 1
	s_barrier
	v_mfma_f32_16x16x32_bf16 v[124:127], v[156:159], v[194:197], v[124:127]
	v_mfma_f32_16x16x32_bf16 v[120:123], v[164:167], v[194:197], v[120:123]
	v_mfma_f32_16x16x32_bf16 v[108:111], v[156:159], v[202:205], v[108:111]
	v_mfma_f32_16x16x32_bf16 v[104:107], v[164:167], v[202:205], v[104:107]
	v_mfma_f32_16x16x32_bf16 v[92:95], v[156:159], v[210:213], v[92:95]
	v_mfma_f32_16x16x32_bf16 v[88:91], v[164:167], v[210:213], v[88:91]
	v_mfma_f32_16x16x32_bf16 v[76:79], v[156:159], v[218:221], v[76:79]
	v_mfma_f32_16x16x32_bf16 v[72:75], v[164:167], v[218:221], v[72:75]
	v_mfma_f32_16x16x32_bf16 v[124:127], v[160:163], v[198:201], v[124:127]
	v_mfma_f32_16x16x32_bf16 v[120:123], v[168:171], v[198:201], v[120:123]
	v_mfma_f32_16x16x32_bf16 v[108:111], v[160:163], v[206:209], v[108:111]
	v_mfma_f32_16x16x32_bf16 v[104:107], v[168:171], v[206:209], v[104:107]
	v_mfma_f32_16x16x32_bf16 v[92:95], v[160:163], v[214:217], v[92:95]
	v_mfma_f32_16x16x32_bf16 v[88:91], v[168:171], v[214:217], v[88:91]
	v_mfma_f32_16x16x32_bf16 v[76:79], v[160:163], v[222:225], v[76:79]
	v_mfma_f32_16x16x32_bf16 v[72:75], v[168:171], v[222:225], v[72:75]
	s_setprio 0
	s_setprio 1
	v_mfma_f32_16x16x32_bf16 v[116:119], v[172:175], v[194:197], v[116:119]
	v_mfma_f32_16x16x32_bf16 v[112:115], v[180:183], v[194:197], v[112:115]
	v_mfma_f32_16x16x32_bf16 v[100:103], v[172:175], v[202:205], v[100:103]
	v_mfma_f32_16x16x32_bf16 v[96:99], v[180:183], v[202:205], v[96:99]
	v_mfma_f32_16x16x32_bf16 v[84:87], v[172:175], v[210:213], v[84:87]
	v_mfma_f32_16x16x32_bf16 v[80:83], v[180:183], v[210:213], v[80:83]
	v_mfma_f32_16x16x32_bf16 v[68:71], v[172:175], v[218:221], v[68:71]
	v_mfma_f32_16x16x32_bf16 v[64:67], v[180:183], v[218:221], v[64:67]
	v_mfma_f32_16x16x32_bf16 v[116:119], v[176:179], v[198:201], v[116:119]
	v_mfma_f32_16x16x32_bf16 v[112:115], v[190:193], v[198:201], v[112:115]
	v_mfma_f32_16x16x32_bf16 v[100:103], v[176:179], v[206:209], v[100:103]
	v_mfma_f32_16x16x32_bf16 v[96:99], v[190:193], v[206:209], v[96:99]
	v_mfma_f32_16x16x32_bf16 v[84:87], v[176:179], v[214:217], v[84:87]
	v_mfma_f32_16x16x32_bf16 v[80:83], v[190:193], v[214:217], v[80:83]
	v_mfma_f32_16x16x32_bf16 v[68:71], v[176:179], v[222:225], v[68:71]
	v_mfma_f32_16x16x32_bf16 v[64:67], v[190:193], v[222:225], v[64:67]
	s_barrier
; #define PG8_STAGE(bufoff, gbase, voff) do { _Pragma("unroll") for (int _i = 0; _i < 2; ++_i) \
;         __builtin_amdgcn_global_load_lds((const unsigned*)((const char*)(gbase) + (voff)[_i]), (PG8_LAS unsigned*)(lds + (bufoff) + ldsw + _i * 8192), 16, 0, 0); } while (0)
; #define PG8_LDA(dst, b, h) do { _Pragma("unroll") for (int m = 0; m < 4; ++m) _Pragma("unroll") for (int k = 0; k < 2; ++k) dst[m][k] = *(const PG8_LAS bf16x8*)(lds + PG8_SA(b, h) + aoff + m * 2048 + k * 1024); } while (0)
; #define PG8_MMA(ai, bj, At, Bt) do { __builtin_amdgcn_s_setprio(1); _Pragma("unroll") for (int m = 0; m < 4; ++m) _Pragma("unroll") for (int n = 0; n < 2; ++n) _Pragma("unroll") for (int k = 0; k < 2; ++k) \
;         acc[ai][bj][m][n] = __builtin_amdgcn_mfma_f32_16x16x32_bf16(Bt[n][k], At[m][k], acc[ai][bj][m][n], 0, 0, 0); __builtin_amdgcn_s_setprio(0); } while (0)
; #define PG8_WAIT_V(n) asm volatile("s_waitcnt vmcnt(" #n ")" ::: "memory")
; #define PG8_WAIT_L(n) asm volatile("s_waitcnt lgkmcnt(" #n ")" ::: "memory")
; #define PG8_BAR __builtin_amdgcn_s_barrier()
; #define PG8_SCHED __builtin_amdgcn_sched_barrier(0)
; template <class Epi, class Sched, bool ALIGN_EPI = false, bool SP2 = false>
; __device__ __forceinline__ void gemm_phase(PG8_LAS unsigned char* lds, const Gemm g, const Sched& S, const Epi& E) {
;     ...
;         for (int t = 0; t < nt; t += 2) {
;     ...
;             PG8_LDA(At, 1, 1); PG8_STAGE(PG8_SB(1, 0), b3, voffB); PG8_STAGE(PG8_SB(1, 1), b3 + hstepB, voffB); PG8_STAGE(PG8_SA(1, 0), a3, voffA);
;             PG8_WAIT_V(8); PG8_WAIT_L(0); PG8_BAR; PG8_MMA(1, 0, At, B0); PG8_MMA(1, 1, At, B1); PG8_BAR; PG8_SCHED;
	s_setprio 0
	s_add_i32 s44, s53, s7
	v_lshl_add_u64 v[226:227], v[226:227], 0, s[16:17]
	s_mov_b32 m0, s44
	ds_read_b128 v[194:197], v154 offset:49152
	ds_read_b128 v[198:201], v154 offset:50176
	ds_read_b128 v[202:205], v154 offset:51200
	ds_read_b128 v[206:209], v154 offset:52224
	ds_read_b128 v[210:213], v154 offset:53248
	ds_read_b128 v[214:217], v154 offset:54272
	ds_read_b128 v[218:221], v154 offset:55296
	ds_read_b128 v[222:225], v154 offset:56320
	global_load_lds_dwordx4 v[226:227], off
	s_add_i32 m0, s44, 0x2000
	s_add_u32 s42, s42, 0x80080
	v_lshl_add_u64 v[226:227], v[228:229], 0, s[16:17]
	s_addc_u32 s43, s43, 0
	s_add_i32 s44, s54, s7
	global_load_lds_dwordx4 v[226:227], off
	v_lshl_add_u64 v[226:227], s[42:43], 0, v[130:131]
	s_mov_b32 m0, s44
	s_nop 0
	global_load_lds_dwordx4 v[226:227], off
	v_lshl_add_u64 v[226:227], s[42:43], 0, v[134:135]
	s_add_i32 m0, s44, 0x2000
	s_nop 0
	global_load_lds_dwordx4 v[226:227], off
	v_lshl_add_u64 v[226:227], v[230:231], 0, s[16:17]
	s_mov_b32 m0, s48
	s_nop 0
	global_load_lds_dwordx4 v[226:227], off
	v_lshl_add_u64 v[226:227], v[232:233], 0, s[16:17]
	s_mov_b32 m0, s49
	s_nop 0
	global_load_lds_dwordx4 v[226:227], off
	s_nop 0
	s_waitcnt vmcnt(8)
	s_waitcnt lgkmcnt(0)
	s_setprio 1
	s_barrier
	v_mfma_f32_16x16x32_bf16 v[60:63], v[156:159], v[194:197], v[60:63]
	v_mfma_f32_16x16x32_bf16 v[56:59], v[164:167], v[194:197], v[56:59]
	v_mfma_f32_16x16x32_bf16 v[44:47], v[156:159], v[202:205], v[44:47]
	v_mfma_f32_16x16x32_bf16 v[40:43], v[164:167], v[202:205], v[40:43]
	v_mfma_f32_16x16x32_bf16 v[28:31], v[156:159], v[210:213], v[28:31]
	v_mfma_f32_16x16x32_bf16 v[24:27], v[164:167], v[210:213], v[24:27]
	v_mfma_f32_16x16x32_bf16 v[12:15], v[156:159], v[218:221], v[12:15]
	v_mfma_f32_16x16x32_bf16 v[8:11], v[164:167], v[218:221], v[8:11]
	v_mfma_f32_16x16x32_bf16 v[60:63], v[160:163], v[198:201], v[60:63]
	v_mfma_f32_16x16x32_bf16 v[56:59], v[168:171], v[198:201], v[56:59]
	v_mfma_f32_16x16x32_bf16 v[44:47], v[160:163], v[206:209], v[44:47]
	v_mfma_f32_16x16x32_bf16 v[40:43], v[168:171], v[206:209], v[40:43]
	v_mfma_f32_16x16x32_bf16 v[28:31], v[160:163], v[214:217], v[28:31]
	v_mfma_f32_16x16x32_bf16 v[24:27], v[168:171], v[214:217], v[24:27]
	v_mfma_f32_16x16x32_bf16 v[12:15], v[160:163], v[222:225], v[12:15]
	v_mfma_f32_16x16x32_bf16 v[8:11], v[168:171], v[222:225], v[8:11]
	s_setprio 0
	s_setprio 1
	v_mfma_f32_16x16x32_bf16 v[52:55], v[172:175], v[194:197], v[52:55]
	v_mfma_f32_16x16x32_bf16 v[48:51], v[180:183], v[194:197], v[48:51]
	v_mfma_f32_16x16x32_bf16 v[36:39], v[172:175], v[202:205], v[36:39]
	v_mfma_f32_16x16x32_bf16 v[32:35], v[180:183], v[202:205], v[32:35]
	v_mfma_f32_16x16x32_bf16 v[20:23], v[172:175], v[210:213], v[20:23]
	v_mfma_f32_16x16x32_bf16 v[16:19], v[180:183], v[210:213], v[16:19]
	v_mfma_f32_16x16x32_bf16 v[4:7], v[172:175], v[218:221], v[4:7]
	v_mfma_f32_16x16x32_bf16 v[0:3], v[180:183], v[218:221], v[0:3]
	v_mfma_f32_16x16x32_bf16 v[52:55], v[176:179], v[198:201], v[52:55]
	v_mfma_f32_16x16x32_bf16 v[48:51], v[190:193], v[198:201], v[48:51]
	v_mfma_f32_16x16x32_bf16 v[36:39], v[176:179], v[206:209], v[36:39]
	v_mfma_f32_16x16x32_bf16 v[32:35], v[190:193], v[206:209], v[32:35]
	v_mfma_f32_16x16x32_bf16 v[20:23], v[176:179], v[214:217], v[20:23]
	v_mfma_f32_16x16x32_bf16 v[16:19], v[190:193], v[214:217], v[16:19]
	v_mfma_f32_16x16x32_bf16 v[4:7], v[176:179], v[222:225], v[4:7]
	v_mfma_f32_16x16x32_bf16 v[0:3], v[190:193], v[222:225], v[0:3]
	s_barrier
	s_setprio 0
	s_add_i32 s35, s35, 2
	s_add_u32 s40, s40, 0x100
	s_addc_u32 s41, s41, 0
	s_add_u32 s21, s21, 0x100
	s_addc_u32 s23, s23, 0
	s_cmp_gt_u32 s35, 29
	s_cbranch_scc0 .LBB0_3058
	s_and_b64 vcc, exec, s[18:19]
	s_cbranch_vccz .LBB0_3061
	s_barrier

; #define PG8_STAGE(bufoff, gbase, voff) do { _Pragma("unroll") for (int _i = 0; _i < 2; ++_i) \
;         __builtin_amdgcn_global_load_lds((const unsigned*)((const char*)(gbase) + (voff)[_i]), (PG8_LAS unsigned*)(lds + (bufoff) + ldsw + _i * 8192), 16, 0, 0); } while (0)
; #define PG8_LDA(dst, b, h) do { _Pragma("unroll") for (int m = 0; m < 4; ++m) _Pragma("unroll") for (int k = 0; k < 2; ++k) dst[m][k] = *(const PG8_LAS bf16x8*)(lds + PG8_SA(b, h) + aoff + m * 2048 + k * 1024); } while (0)
; #define PG8_LDB(dst, b, h) do { _Pragma("unroll") for (int n = 0; n < 2; ++n) _Pragma("unroll") for (int k = 0; k < 2; ++k) dst[n][k] = *(const PG8_LAS bf16x8*)(lds + PG8_SB(b, h) + boff + n * 2048 + k * 1024); } while (0)
; #define PG8_WAIT_V(n) asm volatile("s_waitcnt vmcnt(" #n ")" ::: "memory")
; template <class Epi, class Sched, bool ALIGN_EPI = false, bool SP2 = false>
; __device__ __forceinline__ void gemm_phase(PG8_LAS unsigned char* lds, const Gemm g, const Sched& S, const Epi& E) {
;     ...
;             const char* a1 = cA + (size_t)(t + 1) * kstA;
;             const char* a2 = last ? nA : cA + (size_t)(t + 2) * kstA; const char* b2 = last ? nB : cB + (size_t)(t + 2) * kstep;
;             const char* a3 = a2 + kstA; const char* b3 = b2 + kstep;
;             if (last && has_next) S.a_ready(nxt);
;             if constexpr (SP2) {
;             PG8_LDB(B0, 0, 0); PG8_LDB(B1, 0, 1); PG8_SCHED; PG8_LDA(At, 0, 0); PG8_STAGE(PG8_SA(1, 1), a1 + hstepA, voffA);
;             PG8_WAIT_V(8); PG8_WAIT_L(0); PG8_BAR; PG8_MMA(0, 0, At, B0); PG8_MMA(0, 1, At, B1); PG8_BAR; PG8_SCHED;
;             PG8_LDA(At, 0, 1); PG8_STAGE(PG8_SB(0, 0), b2, voffB); PG8_STAGE(PG8_SB(0, 1), b2 + hstepB, voffB); PG8_STAGE(PG8_SA(0, 0), a2, voffA);
;             PG8_WAIT_V(8); PG8_WAIT_L(0); PG8_BAR; PG8_MMA(1, 0, At, B0); PG8_MMA(1, 1, At, B1); PG8_BAR; PG8_SCHED;
;             PG8_LDB(B0, 1, 0); PG8_LDB(B1, 1, 1); PG8_SCHED; PG8_LDA(At, 1, 0); PG8_STAGE(PG8_SA(0, 1), a2 + hstepA, voffA);
;             PG8_WAIT_V(8); PG8_WAIT_L(0); PG8_BAR; PG8_MMA(0, 0, At, B0); PG8_MMA(0, 1, At, B1); PG8_BAR; PG8_SCHED;
;             PG8_LDA(At, 1, 1); PG8_STAGE(PG8_SB(1, 0), b3, voffB); PG8_STAGE(PG8_SB(1, 1), b3 + hstepB, voffB); PG8_STAGE(PG8_SA(1, 0), a3, voffA);
;             PG8_WAIT_V(8); PG8_WAIT_L(0); PG8_BAR; PG8_MMA(1, 0, At, B0); PG8_MMA(1, 1, At, B1); PG8_BAR; PG8_SCHED;
.LBB0_3147:
	v_add_u32_e32 v176, s64, v178
	ds_read_b128 v[164:167], v176
	ds_read_b128 v[168:171], v176 offset:1024
	ds_read_b128 v[172:175], v176 offset:2048
	ds_read_b128 v[190:193], v176 offset:3072
	v_add_u32_e32 v176, s65, v178
	ds_read_b128 v[194:197], v176
	ds_read_b128 v[198:201], v176 offset:1024
	ds_read_b128 v[202:205], v176 offset:2048
	ds_read_b128 v[206:209], v176 offset:3072
	s_add_u32 s12, s20, s46
	s_addc_u32 s13, s21, s47
	s_cmp_eq_u32 s7, s5
	s_cselect_b32 s52, s42, s12
	s_cselect_b32 s53, s43, s13
	s_cselect_b32 s51, s45, s4
	s_cselect_b32 s50, s44, s1
	s_add_u32 s48, s52, 0x8000
	s_addc_u32 s49, s53, 0
	v_lshl_add_u64 v[176:177], s[20:21], 0, v[162:163]
	s_add_i32 m0, s55, 0xc000
	ds_read_b128 v[210:213], v180
	ds_read_b128 v[214:217], v180 offset:1024
	ds_read_b128 v[218:221], v180 offset:2048
	ds_read_b128 v[222:225], v180 offset:3072
	ds_read_b128 v[226:229], v180 offset:4096
	ds_read_b128 v[230:233], v180 offset:5120
	ds_read_b128 v[234:237], v180 offset:6144
	ds_read_b128 v[238:241], v180 offset:7168
	global_load_lds_dwordx4 v[176:177], off
	v_lshl_add_u64 v[176:177], s[20:21], 0, v[160:161]
	s_add_i32 m0, s55, 0xe000
	s_nop 0
	global_load_lds_dwordx4 v[176:177], off
	s_waitcnt vmcnt(8)
	s_waitcnt lgkmcnt(0)
	s_setprio 1
	s_barrier
	v_mfma_f32_16x16x32_bf16 v[124:127], v[164:167], v[210:213], v[124:127]
	v_mfma_f32_16x16x32_bf16 v[120:123], v[172:175], v[210:213], v[120:123]
	v_mfma_f32_16x16x32_bf16 v[116:119], v[164:167], v[218:221], v[116:119]
	v_mfma_f32_16x16x32_bf16 v[112:115], v[172:175], v[218:221], v[112:115]
	v_mfma_f32_16x16x32_bf16 v[108:111], v[164:167], v[226:229], v[108:111]
	v_mfma_f32_16x16x32_bf16 v[104:107], v[172:175], v[226:229], v[104:107]
	v_mfma_f32_16x16x32_bf16 v[100:103], v[164:167], v[234:237], v[100:103]
	v_mfma_f32_16x16x32_bf16 v[96:99], v[172:175], v[234:237], v[96:99]
	v_mfma_f32_16x16x32_bf16 v[124:127], v[168:171], v[214:217], v[124:127]
	v_mfma_f32_16x16x32_bf16 v[120:123], v[190:193], v[214:217], v[120:123]
	v_mfma_f32_16x16x32_bf16 v[116:119], v[168:171], v[222:225], v[116:119]
	v_mfma_f32_16x16x32_bf16 v[112:115], v[190:193], v[222:225], v[112:115]
	v_mfma_f32_16x16x32_bf16 v[108:111], v[168:171], v[230:233], v[108:111]
	v_mfma_f32_16x16x32_bf16 v[104:107], v[190:193], v[230:233], v[104:107]
	v_mfma_f32_16x16x32_bf16 v[100:103], v[168:171], v[238:241], v[100:103]
	v_mfma_f32_16x16x32_bf16 v[96:99], v[190:193], v[238:241], v[96:99]
	s_setprio 0
	s_setprio 1
	v_mfma_f32_16x16x32_bf16 v[92:95], v[194:197], v[210:213], v[92:95]
	v_mfma_f32_16x16x32_bf16 v[88:91], v[202:205], v[210:213], v[88:91]
	v_mfma_f32_16x16x32_bf16 v[84:87], v[194:197], v[218:221], v[84:87]
	v_mfma_f32_16x16x32_bf16 v[80:83], v[202:205], v[218:221], v[80:83]
	v_mfma_f32_16x16x32_bf16 v[76:79], v[194:197], v[226:229], v[76:79]
	v_mfma_f32_16x16x32_bf16 v[72:75], v[202:205], v[226:229], v[72:75]
	v_mfma_f32_16x16x32_bf16 v[68:71], v[194:197], v[234:237], v[68:71]
	v_mfma_f32_16x16x32_bf16 v[64:67], v[202:205], v[234:237], v[64:67]
	v_mfma_f32_16x16x32_bf16 v[92:95], v[198:201], v[214:217], v[92:95]
	v_mfma_f32_16x16x32_bf16 v[88:91], v[206:209], v[214:217], v[88:91]
	v_mfma_f32_16x16x32_bf16 v[84:87], v[198:201], v[222:225], v[84:87]
	v_mfma_f32_16x16x32_bf16 v[80:83], v[206:209], v[222:225], v[80:83]
	v_mfma_f32_16x16x32_bf16 v[76:79], v[198:201], v[230:233], v[76:79]
	v_mfma_f32_16x16x32_bf16 v[72:75], v[206:209], v[230:233], v[72:75]
	v_mfma_f32_16x16x32_bf16 v[68:71], v[198:201], v[238:241], v[68:71]
	v_mfma_f32_16x16x32_bf16 v[64:67], v[206:209], v[238:241], v[64:67]
	s_barrier
	s_setprio 0
	s_add_i32 s12, s64, s54
	v_lshl_add_u64 v[176:177], s[50:51], 0, v[130:131]
	s_mov_b32 m0, s12
	ds_read_b128 v[210:213], v180 offset:16384
	ds_read_b128 v[214:217], v180 offset:17408
	ds_read_b128 v[218:221], v180 offset:18432
	ds_read_b128 v[222:225], v180 offset:19456
	ds_read_b128 v[226:229], v180 offset:20480
	ds_read_b128 v[230:233], v180 offset:21504
	ds_read_b128 v[234:237], v180 offset:22528
	ds_read_b128 v[238:241], v180 offset:23552
	global_load_lds_dwordx4 v[176:177], off
	s_add_i32 m0, s12, 0x2000
	s_add_u32 s12, s50, 0x160000
	v_lshl_add_u64 v[182:183], s[50:51], 0, v[134:135]
	s_addc_u32 s13, s51, 0
	s_add_i32 s17, s65, s54
	global_load_lds_dwordx4 v[182:183], off
	v_lshl_add_u64 v[242:243], s[12:13], 0, v[130:131]
	s_mov_b32 m0, s17
	s_nop 0
	global_load_lds_dwordx4 v[242:243], off
	v_lshl_add_u64 v[242:243], s[12:13], 0, v[134:135]
	s_add_i32 m0, s17, 0x2000
	s_nop 0
	global_load_lds_dwordx4 v[242:243], off
	v_lshl_add_u64 v[242:243], s[52:53], 0, v[128:129]
	s_mov_b32 m0, s55
	s_nop 0
	global_load_lds_dwordx4 v[242:243], off
	v_lshl_add_u64 v[242:243], s[52:53], 0, v[132:133]
	s_mov_b32 m0, s56
	s_nop 0
	global_load_lds_dwordx4 v[242:243], off
	s_nop 0
	s_waitcnt vmcnt(8)
	s_waitcnt lgkmcnt(0)
	s_setprio 1
	s_barrier
; #define PG8_STAGE(bufoff, gbase, voff) do { _Pragma("unroll") for (int _i = 0; _i < 2; ++_i) \
;         __builtin_amdgcn_global_load_lds((const unsigned*)((const char*)(gbase) + (voff)[_i]), (PG8_LAS unsigned*)(lds + (bufoff) + ldsw + _i * 8192), 16, 0, 0); } while (0)
; #define PG8_LDA(dst, b, h) do { _Pragma("unroll") for (int m = 0; m < 4; ++m) _Pragma("unroll") for (int k = 0; k < 2; ++k) dst[m][k] = *(const PG8_LAS bf16x8*)(lds + PG8_SA(b, h) + aoff + m * 2048 + k * 1024); } while (0)
; #define PG8_LDB(dst, b, h) do { _Pragma("unroll") for (int n = 0; n < 2; ++n) _Pragma("unroll") for (int k = 0; k < 2; ++k) dst[n][k] = *(const PG8_LAS bf16x8*)(lds + PG8_SB(b, h) + boff + n * 2048 + k * 1024); } while (0)
; #define PG8_MMA(ai, bj, At, Bt) do { __builtin_amdgcn_s_setprio(1); _Pragma("unroll") for (int m = 0; m < 4; ++m) _Pragma("unroll") for (int n = 0; n < 2; ++n) _Pragma("unroll") for (int k = 0; k < 2; ++k) \
;         acc[ai][bj][m][n] = __builtin_amdgcn_mfma_f32_16x16x32_bf16(Bt[n][k], At[m][k], acc[ai][bj][m][n], 0, 0, 0); __builtin_amdgcn_s_setprio(0); } while (0)
; #define PG8_WAIT_V(n) asm volatile("s_waitcnt vmcnt(" #n ")" ::: "memory")
; #define PG8_WAIT_L(n) asm volatile("s_waitcnt lgkmcnt(" #n ")" ::: "memory")
; #define PG8_BAR __builtin_amdgcn_s_barrier()
; #define PG8_SCHED __builtin_amdgcn_sched_barrier(0)
; template <class Epi, class Sched, bool ALIGN_EPI = false, bool SP2 = false>
; __device__ __forceinline__ void gemm_phase(PG8_LAS unsigned char* lds, const Gemm g, const Sched& S, const Epi& E) {
;     ...
;             PG8_WAIT_V(8); PG8_WAIT_L(0); PG8_BAR; PG8_MMA(1, 0, At, B0); PG8_MMA(1, 1, At, B1); PG8_BAR; PG8_SCHED;
;             PG8_LDB(B0, 1, 0); PG8_LDB(B1, 1, 1); PG8_SCHED; PG8_LDA(At, 1, 0); PG8_STAGE(PG8_SA(0, 1), a2 + hstepA, voffA);
;             PG8_WAIT_V(8); PG8_WAIT_L(0); PG8_BAR; PG8_MMA(0, 0, At, B0); PG8_MMA(0, 1, At, B1); PG8_BAR; PG8_SCHED;
	v_mfma_f32_16x16x32_bf16 v[60:63], v[164:167], v[210:213], v[60:63]
	v_mfma_f32_16x16x32_bf16 v[56:59], v[172:175], v[210:213], v[56:59]
	v_mfma_f32_16x16x32_bf16 v[52:55], v[164:167], v[218:221], v[52:55]
	v_mfma_f32_16x16x32_bf16 v[48:51], v[172:175], v[218:221], v[48:51]
	v_mfma_f32_16x16x32_bf16 v[44:47], v[164:167], v[226:229], v[44:47]
	v_mfma_f32_16x16x32_bf16 v[40:43], v[172:175], v[226:229], v[40:43]
	v_mfma_f32_16x16x32_bf16 v[36:39], v[164:167], v[234:237], v[36:39]
	v_mfma_f32_16x16x32_bf16 v[32:35], v[172:175], v[234:237], v[32:35]
	v_mfma_f32_16x16x32_bf16 v[60:63], v[168:171], v[214:217], v[60:63]
	v_mfma_f32_16x16x32_bf16 v[56:59], v[190:193], v[214:217], v[56:59]
	v_mfma_f32_16x16x32_bf16 v[52:55], v[168:171], v[222:225], v[52:55]
	v_mfma_f32_16x16x32_bf16 v[48:51], v[190:193], v[222:225], v[48:51]
	v_mfma_f32_16x16x32_bf16 v[44:47], v[168:171], v[230:233], v[44:47]
	v_mfma_f32_16x16x32_bf16 v[40:43], v[190:193], v[230:233], v[40:43]
	v_mfma_f32_16x16x32_bf16 v[36:39], v[168:171], v[238:241], v[36:39]
	v_mfma_f32_16x16x32_bf16 v[32:35], v[190:193], v[238:241], v[32:35]
	s_setprio 0
	s_setprio 1
	v_mfma_f32_16x16x32_bf16 v[28:31], v[194:197], v[210:213], v[28:31]
	v_mfma_f32_16x16x32_bf16 v[24:27], v[202:205], v[210:213], v[24:27]
	v_mfma_f32_16x16x32_bf16 v[20:23], v[194:197], v[218:221], v[20:23]
	v_mfma_f32_16x16x32_bf16 v[16:19], v[202:205], v[218:221], v[16:19]
	v_mfma_f32_16x16x32_bf16 v[12:15], v[194:197], v[226:229], v[12:15]
	v_mfma_f32_16x16x32_bf16 v[8:11], v[202:205], v[226:229], v[8:11]
	v_mfma_f32_16x16x32_bf16 v[4:7], v[194:197], v[234:237], v[4:7]
	v_mfma_f32_16x16x32_bf16 v[0:3], v[202:205], v[234:237], v[0:3]
	v_mfma_f32_16x16x32_bf16 v[28:31], v[198:201], v[214:217], v[28:31]
	v_mfma_f32_16x16x32_bf16 v[24:27], v[206:209], v[214:217], v[24:27]
	v_mfma_f32_16x16x32_bf16 v[20:23], v[198:201], v[222:225], v[20:23]
	v_mfma_f32_16x16x32_bf16 v[16:19], v[206:209], v[222:225], v[16:19]
	v_mfma_f32_16x16x32_bf16 v[12:15], v[198:201], v[230:233], v[12:15]
	v_mfma_f32_16x16x32_bf16 v[8:11], v[206:209], v[230:233], v[8:11]
	v_mfma_f32_16x16x32_bf16 v[4:7], v[198:201], v[238:241], v[4:7]
	v_mfma_f32_16x16x32_bf16 v[0:3], v[206:209], v[238:241], v[0:3]
	s_barrier
	s_setprio 0
	s_add_i32 s17, 0, 0x18000
	v_add_u32_e32 v181, s17, v178
	s_add_i32 s19, 0, 0x1c000
	ds_read_b128 v[164:167], v181
	ds_read_b128 v[168:171], v181 offset:1024
	ds_read_b128 v[172:175], v181 offset:2048
	ds_read_b128 v[190:193], v181 offset:3072
	v_add_u32_e32 v181, s19, v178
	ds_read_b128 v[194:197], v181
	ds_read_b128 v[198:201], v181 offset:1024
	ds_read_b128 v[202:205], v181 offset:2048
	ds_read_b128 v[206:209], v181 offset:3072
	s_add_u32 s12, s52, 0x4000
	s_addc_u32 s13, s53, 0
	s_mov_b32 m0, s57
	v_lshl_add_u64 v[242:243], s[12:13], 0, v[128:129]
	ds_read_b128 v[210:213], v180 offset:32768
	ds_read_b128 v[214:217], v180 offset:33792
	ds_read_b128 v[218:221], v180 offset:34816
	ds_read_b128 v[222:225], v180 offset:35840
	ds_read_b128 v[226:229], v180 offset:36864
	ds_read_b128 v[230:233], v180 offset:37888
	ds_read_b128 v[234:237], v180 offset:38912
	ds_read_b128 v[238:241], v180 offset:39936
	global_load_lds_dwordx4 v[242:243], off
	v_lshl_add_u64 v[242:243], s[12:13], 0, v[132:133]
	s_mov_b32 m0, s58
	s_nop 0
	global_load_lds_dwordx4 v[242:243], off
	s_waitcnt vmcnt(8)
	s_waitcnt lgkmcnt(0)
	s_setprio 1
	s_barrier
	v_mfma_f32_16x16x32_bf16 v[124:127], v[164:167], v[210:213], v[124:127]
	v_mfma_f32_16x16x32_bf16 v[120:123], v[172:175], v[210:213], v[120:123]
	v_mfma_f32_16x16x32_bf16 v[116:119], v[164:167], v[218:221], v[116:119]
	v_mfma_f32_16x16x32_bf16 v[112:115], v[172:175], v[218:221], v[112:115]
	v_mfma_f32_16x16x32_bf16 v[108:111], v[164:167], v[226:229], v[108:111]
	v_mfma_f32_16x16x32_bf16 v[104:107], v[172:175], v[226:229], v[104:107]
	v_mfma_f32_16x16x32_bf16 v[100:103], v[164:167], v[234:237], v[100:103]
	v_mfma_f32_16x16x32_bf16 v[96:99], v[172:175], v[234:237], v[96:99]
	v_mfma_f32_16x16x32_bf16 v[124:127], v[168:171], v[214:217], v[124:127]
	v_mfma_f32_16x16x32_bf16 v[120:123], v[190:193], v[214:217], v[120:123]
	v_mfma_f32_16x16x32_bf16 v[116:119], v[168:171], v[222:225], v[116:119]
	v_mfma_f32_16x16x32_bf16 v[112:115], v[190:193], v[222:225], v[112:115]
	v_mfma_f32_16x16x32_bf16 v[108:111], v[168:171], v[230:233], v[108:111]
	v_mfma_f32_16x16x32_bf16 v[104:107], v[190:193], v[230:233], v[104:107]
	v_mfma_f32_16x16x32_bf16 v[100:103], v[168:171], v[238:241], v[100:103]
	v_mfma_f32_16x16x32_bf16 v[96:99], v[190:193], v[238:241], v[96:99]
	s_setprio 0
	s_setprio 1
	v_mfma_f32_16x16x32_bf16 v[92:95], v[194:197], v[210:213], v[92:95]
	v_mfma_f32_16x16x32_bf16 v[88:91], v[202:205], v[210:213], v[88:91]
	v_mfma_f32_16x16x32_bf16 v[84:87], v[194:197], v[218:221], v[84:87]
	v_mfma_f32_16x16x32_bf16 v[80:83], v[202:205], v[218:221], v[80:83]
	v_mfma_f32_16x16x32_bf16 v[76:79], v[194:197], v[226:229], v[76:79]
	v_mfma_f32_16x16x32_bf16 v[72:75], v[202:205], v[226:229], v[72:75]
	v_mfma_f32_16x16x32_bf16 v[68:71], v[194:197], v[234:237], v[68:71]
	v_mfma_f32_16x16x32_bf16 v[64:67], v[202:205], v[234:237], v[64:67]
	v_mfma_f32_16x16x32_bf16 v[92:95], v[198:201], v[214:217], v[92:95]
	v_mfma_f32_16x16x32_bf16 v[88:91], v[206:209], v[214:217], v[88:91]
	v_mfma_f32_16x16x32_bf16 v[84:87], v[198:201], v[222:225], v[84:87]
	v_mfma_f32_16x16x32_bf16 v[80:83], v[206:209], v[222:225], v[80:83]
	v_mfma_f32_16x16x32_bf16 v[76:79], v[198:201], v[230:233], v[76:79]
	v_mfma_f32_16x16x32_bf16 v[72:75], v[206:209], v[230:233], v[72:75]
	v_mfma_f32_16x16x32_bf16 v[68:71], v[198:201], v[238:241], v[68:71]
	v_mfma_f32_16x16x32_bf16 v[64:67], v[206:209], v[238:241], v[64:67]
	s_barrier
; #define PG8_STAGE(bufoff, gbase, voff) do { _Pragma("unroll") for (int _i = 0; _i < 2; ++_i) \
;         __builtin_amdgcn_global_load_lds((const unsigned*)((const char*)(gbase) + (voff)[_i]), (PG8_LAS unsigned*)(lds + (bufoff) + ldsw + _i * 8192), 16, 0, 0); } while (0)
; #define PG8_LDA(dst, b, h) do { _Pragma("unroll") for (int m = 0; m < 4; ++m) _Pragma("unroll") for (int k = 0; k < 2; ++k) dst[m][k] = *(const PG8_LAS bf16x8*)(lds + PG8_SA(b, h) + aoff + m * 2048 + k * 1024); } while (0)
; #define PG8_MMA(ai, bj, At, Bt) do { __builtin_amdgcn_s_setprio(1); _Pragma("unroll") for (int m = 0; m < 4; ++m) _Pragma("unroll") for (int n = 0; n < 2; ++n) _Pragma("unroll") for (int k = 0; k < 2; ++k) \
;         acc[ai][bj][m][n] = __builtin_amdgcn_mfma_f32_16x16x32_bf16(Bt[n][k], At[m][k], acc[ai][bj][m][n], 0, 0, 0); __builtin_amdgcn_s_setprio(0); } while (0)
; #define PG8_WAIT_V(n) asm volatile("s_waitcnt vmcnt(" #n ")" ::: "memory")
; #define PG8_WAIT_L(n) asm volatile("s_waitcnt lgkmcnt(" #n ")" ::: "memory")
; #define PG8_BAR __builtin_amdgcn_s_barrier()
; #define PG8_SCHED __builtin_amdgcn_sched_barrier(0)
; template <class Epi, class Sched, bool ALIGN_EPI = false, bool SP2 = false>
; __device__ __forceinline__ void gemm_phase(PG8_LAS unsigned char* lds, const Gemm g, const Sched& S, const Epi& E) {
;     ...
;             PG8_LDA(At, 1, 1); PG8_STAGE(PG8_SB(1, 0), b3, voffB); PG8_STAGE(PG8_SB(1, 1), b3 + hstepB, voffB); PG8_STAGE(PG8_SA(1, 0), a3, voffA);
;             PG8_WAIT_V(8); PG8_WAIT_L(0); PG8_BAR; PG8_MMA(1, 0, At, B0); PG8_MMA(1, 1, At, B1); PG8_BAR; PG8_SCHED;
	s_setprio 0
	s_add_i32 s12, s17, s54
	v_lshl_add_u64 v[176:177], v[176:177], 0, s[30:31]
	s_mov_b32 m0, s12
	ds_read_b128 v[210:213], v180 offset:49152
	ds_read_b128 v[214:217], v180 offset:50176
	ds_read_b128 v[218:221], v180 offset:51200
	ds_read_b128 v[222:225], v180 offset:52224
	ds_read_b128 v[226:229], v180 offset:53248
	ds_read_b128 v[230:233], v180 offset:54272
	ds_read_b128 v[234:237], v180 offset:55296
	ds_read_b128 v[238:241], v180 offset:56320
	global_load_lds_dwordx4 v[176:177], off
	s_add_i32 m0, s12, 0x2000
	s_add_u32 s12, s50, 0x160080
	v_lshl_add_u64 v[176:177], v[182:183], 0, s[30:31]
	s_addc_u32 s13, s51, 0
	s_add_i32 s17, s19, s54
	global_load_lds_dwordx4 v[176:177], off
	v_lshl_add_u64 v[176:177], s[12:13], 0, v[130:131]
	s_mov_b32 m0, s17
	s_nop 0
	global_load_lds_dwordx4 v[176:177], off
	v_lshl_add_u64 v[176:177], s[12:13], 0, v[134:135]
	s_add_i32 m0, s17, 0x2000
	s_nop 0
	global_load_lds_dwordx4 v[176:177], off
	v_lshl_add_u64 v[176:177], s[48:49], 0, v[128:129]
	s_mov_b32 m0, s62
	s_nop 0
	global_load_lds_dwordx4 v[176:177], off
	v_lshl_add_u64 v[176:177], s[48:49], 0, v[132:133]
	s_mov_b32 m0, s63
	s_nop 0
	global_load_lds_dwordx4 v[176:177], off
	s_nop 0
	s_waitcnt vmcnt(8)
	s_waitcnt lgkmcnt(0)
	s_setprio 1
	s_barrier
	v_mfma_f32_16x16x32_bf16 v[60:63], v[164:167], v[210:213], v[60:63]
	v_mfma_f32_16x16x32_bf16 v[56:59], v[172:175], v[210:213], v[56:59]
	v_mfma_f32_16x16x32_bf16 v[52:55], v[164:167], v[218:221], v[52:55]
	v_mfma_f32_16x16x32_bf16 v[48:51], v[172:175], v[218:221], v[48:51]
	v_mfma_f32_16x16x32_bf16 v[44:47], v[164:167], v[226:229], v[44:47]
	v_mfma_f32_16x16x32_bf16 v[40:43], v[172:175], v[226:229], v[40:43]
	v_mfma_f32_16x16x32_bf16 v[36:39], v[164:167], v[234:237], v[36:39]
	v_mfma_f32_16x16x32_bf16 v[32:35], v[172:175], v[234:237], v[32:35]
	v_mfma_f32_16x16x32_bf16 v[60:63], v[168:171], v[214:217], v[60:63]
	v_mfma_f32_16x16x32_bf16 v[56:59], v[190:193], v[214:217], v[56:59]
	v_mfma_f32_16x16x32_bf16 v[52:55], v[168:171], v[222:225], v[52:55]
	v_mfma_f32_16x16x32_bf16 v[48:51], v[190:193], v[222:225], v[48:51]
	v_mfma_f32_16x16x32_bf16 v[44:47], v[168:171], v[230:233], v[44:47]
	v_mfma_f32_16x16x32_bf16 v[40:43], v[190:193], v[230:233], v[40:43]
	v_mfma_f32_16x16x32_bf16 v[36:39], v[168:171], v[238:241], v[36:39]
	v_mfma_f32_16x16x32_bf16 v[32:35], v[190:193], v[238:241], v[32:35]
	s_setprio 0
	s_setprio 1
	v_mfma_f32_16x16x32_bf16 v[28:31], v[194:197], v[210:213], v[28:31]
	v_mfma_f32_16x16x32_bf16 v[24:27], v[202:205], v[210:213], v[24:27]
	v_mfma_f32_16x16x32_bf16 v[20:23], v[194:197], v[218:221], v[20:23]
	v_mfma_f32_16x16x32_bf16 v[16:19], v[202:205], v[218:221], v[16:19]
	v_mfma_f32_16x16x32_bf16 v[12:15], v[194:197], v[226:229], v[12:15]
	v_mfma_f32_16x16x32_bf16 v[8:11], v[202:205], v[226:229], v[8:11]
	v_mfma_f32_16x16x32_bf16 v[4:7], v[194:197], v[234:237], v[4:7]
	v_mfma_f32_16x16x32_bf16 v[0:3], v[202:205], v[234:237], v[0:3]
	v_mfma_f32_16x16x32_bf16 v[28:31], v[198:201], v[214:217], v[28:31]
	v_mfma_f32_16x16x32_bf16 v[24:27], v[206:209], v[214:217], v[24:27]
	v_mfma_f32_16x16x32_bf16 v[20:23], v[198:201], v[222:225], v[20:23]
	v_mfma_f32_16x16x32_bf16 v[16:19], v[206:209], v[222:225], v[16:19]
	v_mfma_f32_16x16x32_bf16 v[12:15], v[198:201], v[230:233], v[12:15]
	v_mfma_f32_16x16x32_bf16 v[8:11], v[206:209], v[230:233], v[8:11]
	v_mfma_f32_16x16x32_bf16 v[4:7], v[198:201], v[238:241], v[4:7]
	v_mfma_f32_16x16x32_bf16 v[0:3], v[206:209], v[238:241], v[0:3]
	s_barrier
	s_setprio 0
	s_add_i32 s12, s5, 2
	s_add_u32 s46, s46, 0x10000
	s_addc_u32 s47, s47, 0
	s_add_u32 s1, s1, 0x100
	s_addc_u32 s4, s4, 0
	v_lshl_add_u64 v[162:163], v[162:163], 0, s[38:39]
	v_lshl_add_u64 v[160:161], v[160:161], 0, s[38:39]
	s_cmp_ge_i32 s5, s7
	s_mov_b32 s5, s12
	s_cbranch_scc0 .LBB0_3147
	s_and_b64 vcc, exec, s[36:37]
	s_cbranch_vccz .LBB0_3150
	s_barrier
